# prologue: pool-fold (weff) j-loop rewritten with 60 loads in flight + LDS reads 3 steps ahead; modulation GEMV silu computed once per lane and broadcast; all conversion loops keep next item's loads in
# speedup vs baseline: 1.0545x; 1.0256x over previous
.LBB0_455:
	s_waitcnt vmcnt(4)
	s_andn2_b64 vcc, exec, s[36:37]
	s_mov_b64 s[36:37], s[44:45]
	v_mov_b32_e32 v2, v38
	v_mov_b32_e32 v3, v39
	v_mov_b32_e32 v4, v40
	v_mov_b32_e32 v5, v41
	v_mov_b32_e32 v6, v34
	v_mov_b32_e32 v7, v35
	v_mov_b32_e32 v8, v36
	v_mov_b32_e32 v9, v37
	v_mov_b32_e32 v10, v46
	v_mov_b32_e32 v11, v47
	v_mov_b32_e32 v12, v48
	v_mov_b32_e32 v13, v49
	v_mov_b32_e32 v14, v42
	v_mov_b32_e32 v15, v43
	v_mov_b32_e32 v16, v44
	v_mov_b32_e32 v17, v45
	v_mov_b32_e32 v18, v54
	v_mov_b32_e32 v19, v55
	v_mov_b32_e32 v20, v56
	v_mov_b32_e32 v21, v57
	v_mov_b32_e32 v22, v50
	v_mov_b32_e32 v23, v51
	v_mov_b32_e32 v24, v52
	v_mov_b32_e32 v25, v53
	v_mov_b32_e32 v26, v62
	v_mov_b32_e32 v27, v63
	v_mov_b32_e32 v28, v64
	v_mov_b32_e32 v29, v65
	v_mov_b32_e32 v30, v58
	v_mov_b32_e32 v31, v59
	v_mov_b32_e32 v32, v60
	v_mov_b32_e32 v33, v61
	s_cbranch_vccz .LBB0_464

.LBB0_461:
	v_mul_u32_u24_e32 v34, s52, v77
	v_mul_u32_u24_e32 v36, s52, v78
	v_mul_u32_u24_e32 v42, s52, v79
	v_mul_u32_u24_e32 v44, s52, v80
	v_mul_u32_u24_e32 v50, s52, v81
	v_mul_u32_u24_e32 v52, s52, v82
	v_mul_u32_u24_e32 v60, s52, v83
	v_mul_u32_u24_e32 v62, s52, v84
	v_lshl_add_u64 v[58:59], s[56:57], 0, v[0:1]
	v_lshlrev_b32_e32 v34, 2, v34
	v_mov_b32_e32 v35, v1
	v_lshlrev_b32_e32 v36, 2, v36
	v_mov_b32_e32 v37, v1
	v_lshlrev_b32_e32 v42, 2, v42
	v_mov_b32_e32 v43, v1
	v_lshlrev_b32_e32 v44, 2, v44
	v_mov_b32_e32 v45, v1
	v_lshlrev_b32_e32 v50, 2, v50
	v_mov_b32_e32 v51, v1
	v_lshlrev_b32_e32 v52, 2, v52
	v_mov_b32_e32 v53, v1
	v_lshlrev_b32_e32 v60, 2, v60
	v_mov_b32_e32 v61, v1
	v_lshlrev_b32_e32 v62, 2, v62
	v_mov_b32_e32 v63, v1
	v_lshl_add_u64 v[34:35], v[58:59], 0, v[34:35]
	v_lshl_add_u64 v[36:37], v[58:59], 0, v[36:37]
	v_lshl_add_u64 v[42:43], v[58:59], 0, v[42:43]
	v_lshl_add_u64 v[44:45], v[58:59], 0, v[44:45]
	v_lshl_add_u64 v[50:51], v[58:59], 0, v[50:51]
	v_lshl_add_u64 v[52:53], v[58:59], 0, v[52:53]
	v_lshl_add_u64 v[60:61], v[58:59], 0, v[60:61]
	v_lshl_add_u64 v[58:59], v[58:59], 0, v[62:63]
	global_load_dwordx4 v[38:41], v[34:35], off
	s_nop 0
	global_load_dwordx4 v[34:37], v[36:37], off
	s_nop 0
	global_load_dwordx4 v[46:49], v[42:43], off
	s_nop 0
	global_load_dwordx4 v[42:45], v[44:45], off
	s_nop 0
	global_load_dwordx4 v[54:57], v[50:51], off
	s_nop 0
	global_load_dwordx4 v[50:53], v[52:53], off
	s_nop 0
	global_load_dwordx4 v[62:65], v[60:61], off
	s_nop 0
	global_load_dwordx4 v[58:61], v[58:59], off
	s_lshl_b64 s[48:49], s[48:49], 11
	s_add_u32 s48, s50, s48
	s_addc_u32 s49, s51, s49
	s_lshl_b64 s[44:45], s[44:45], 1
	s_add_u32 s44, s48, s44
	s_addc_u32 s45, s49, s45
	s_waitcnt vmcnt(8)
	s_branch .Lcvw456_go

.LBB0_462:
.Lcvw456_go:
	ds_write2_b32 v86, v2, v3 offset1:1
	ds_write2_b32 v86, v4, v5 offset0:2 offset1:3
	v_add_u32_e32 v2, 0x420, v86
	ds_write2_b32 v2, v6, v7 offset1:1
	v_add_u32_e32 v2, 0x428, v86
	ds_write2_b32 v2, v8, v9 offset1:1
	v_add_u32_e32 v2, 0x840, v86
	ds_write2_b32 v2, v10, v11 offset1:1
	v_add_u32_e32 v2, 0x848, v86
	ds_write2_b32 v2, v12, v13 offset1:1
	v_add_u32_e32 v2, 0xc60, v86
	ds_write2_b32 v2, v14, v15 offset1:1
	v_add_u32_e32 v2, 0xc68, v86
	ds_write2_b32 v2, v16, v17 offset1:1
	v_add_u32_e32 v2, 0x1080, v86
	ds_write2_b32 v2, v18, v19 offset1:1
	v_add_u32_e32 v2, 0x1088, v86
	ds_write2_b32 v2, v20, v21 offset1:1
	v_add_u32_e32 v2, 0x14a0, v86
	ds_write2_b32 v2, v22, v23 offset1:1
	v_add_u32_e32 v2, 0x14a8, v86
	ds_write2_b32 v2, v24, v25 offset1:1
	v_add_u32_e32 v2, 0x18c0, v86
	ds_write2_b32 v2, v26, v27 offset1:1
	v_add_u32_e32 v2, 0x18c8, v86
	ds_write2_b32 v2, v28, v29 offset1:1
	v_add_u32_e32 v2, 0x1ce0, v86
	ds_write2_b32 v2, v30, v31 offset1:1
	v_add_u32_e32 v2, 0x1ce8, v86
	ds_write2_b32 v2, v32, v33 offset1:1
	s_waitcnt lgkmcnt(0)
	ds_read2_b32 v[2:3], v85 offset1:33
	s_waitcnt lgkmcnt(0)
	v_cvt_pk_bf16_f32 v2, v2, v3
	ds_read2_b32 v[4:5], v85 offset0:66 offset1:99
	v_mov_b32_e32 v75, v1
	s_waitcnt lgkmcnt(0)
	v_cvt_pk_bf16_f32 v3, v4, v5
	ds_read2_b32 v[4:5], v85 offset0:132 offset1:165
	v_lshl_add_u64 v[8:9], s[36:37], 0, v[74:75]
	s_waitcnt lgkmcnt(0)
	v_cvt_pk_bf16_f32 v4, v4, v5
	ds_read2_b32 v[6:7], v85 offset0:198 offset1:231
	s_waitcnt lgkmcnt(0)
	v_cvt_pk_bf16_f32 v5, v6, v7
	v_lshl_add_u64 v[10:11], v[8:9], 0, v[66:67]
	ds_read2_b32 v[6:7], v85 offset0:8 offset1:41
	global_store_dwordx4 v[10:11], v[2:5], off
	v_lshl_add_u64 v[10:11], v[8:9], 0, v[68:69]
	s_andn2_b64 vcc, exec, s[42:43]
	s_waitcnt lgkmcnt(0)
	v_cvt_pk_bf16_f32 v2, v6, v7
	ds_read2_b32 v[4:5], v85 offset0:74 offset1:107
	s_waitcnt lgkmcnt(0)
	v_cvt_pk_bf16_f32 v3, v4, v5
	ds_read2_b32 v[4:5], v85 offset0:140 offset1:173
	s_waitcnt lgkmcnt(0)
	v_cvt_pk_bf16_f32 v4, v4, v5
	ds_read2_b32 v[6:7], v85 offset0:206 offset1:239
	s_waitcnt lgkmcnt(0)
	v_cvt_pk_bf16_f32 v5, v6, v7
	ds_read2_b32 v[6:7], v85 offset0:16 offset1:49
	global_store_dwordx4 v[10:11], v[2:5], off
	v_lshl_add_u64 v[10:11], v[8:9], 0, v[70:71]
	v_lshl_add_u64 v[8:9], v[8:9], 0, v[72:73]
	s_waitcnt lgkmcnt(0)
	v_cvt_pk_bf16_f32 v2, v6, v7
	ds_read2_b32 v[4:5], v85 offset0:82 offset1:115
	s_waitcnt lgkmcnt(0)
	v_cvt_pk_bf16_f32 v3, v4, v5
	ds_read2_b32 v[4:5], v85 offset0:148 offset1:181
	s_waitcnt lgkmcnt(0)
	v_cvt_pk_bf16_f32 v4, v4, v5
	ds_read2_b32 v[6:7], v85 offset0:214 offset1:247
	s_waitcnt lgkmcnt(0)
	v_cvt_pk_bf16_f32 v5, v6, v7
	ds_read2_b32 v[6:7], v85 offset0:24 offset1:57
	global_store_dwordx4 v[10:11], v[2:5], off
	s_mov_b64 s[36:37], -1
	s_waitcnt lgkmcnt(0)
	v_cvt_pk_bf16_f32 v2, v6, v7
	ds_read2_b32 v[4:5], v85 offset0:90 offset1:123
	s_waitcnt lgkmcnt(0)
	v_cvt_pk_bf16_f32 v3, v4, v5
	ds_read2_b32 v[4:5], v85 offset0:156 offset1:189
	s_waitcnt lgkmcnt(0)
	v_cvt_pk_bf16_f32 v4, v4, v5
	ds_read2_b32 v[6:7], v85 offset0:222 offset1:255
	s_waitcnt lgkmcnt(0)
	v_cvt_pk_bf16_f32 v5, v6, v7
	global_store_dwordx4 v[8:9], v[2:5], off
	s_waitcnt lgkmcnt(0)
	s_cbranch_vccnz .LBB0_455
	s_add_i32 s17, s17, s34
	s_add_i32 s25, s25, s35
	s_add_i32 s60, s60, s61
	s_add_i32 s62, s62, s63
	s_mov_b64 s[36:37], 0
	s_branch .LBB0_455

.LBB0_504:
	v_mov_b32_e32 v207, 0
	s_sub_i32 s2, s7, 32
	s_lshr_b32 s2, s2, 3
	s_add_i32 s2, s2, 1
	s_cmp_gt_i32 s7, 31
	v_mov_b32_e32 v172, v225
	s_cselect_b32 s42, s2, 0
	s_lshl_b32 s2, s6, 8
	s_or_b32 s2, s2, s53
	v_bfe_u32 v184, v172, 4, 2
	v_lshl_or_b32 v174, v184, 3, s2
	s_mul_i32 s2, s42, 0x6000
	s_mul_hi_u32 s3, s42, 0x6000
	s_add_u32 s2, s56, s2
	v_ashrrev_i32_e32 v175, 31, v174
	s_addc_u32 s3, s57, s3
	v_lshlrev_b64 v[58:59], 2, v[174:175]
	v_lshl_add_u64 v[60:61], s[2:3], 0, v[58:59]
	s_add_u32 s2, s73, s42
	s_addc_u32 s3, s72, 0
	s_lshl_b64 s[2:3], s[2:3], 12
	s_add_u32 s2, s65, s2
	s_addc_u32 s3, s66, s3
	s_lshl_b32 s7, s7, 8
	v_and_b32_e32 v173, 15, v172
	v_lshl_add_u64 v[62:63], s[2:3], 0, v[58:59]
	s_add_i32 s2, s7, s52
	v_or_b32_e32 v58, s2, v173
	v_ashrrev_i32_e32 v59, 31, v58
	v_lshlrev_b64 v[58:59], 11, v[58:59]
	v_lshl_add_u64 v[176:177], s[26:27], 0, v[58:59]
	v_lshl_add_u64 v[178:179], s[28:29], 0, v[58:59]
	v_lshlrev_b64 v[174:175], 1, v[174:175]
	v_lshl_add_u64 v[176:177], v[176:177], 0, v[174:175]
	v_lshl_add_u64 v[174:175], v[178:179], 0, v[174:175]
	v_mov_b64_e32 v[178:179], v[174:175]
	v_mov_b64_e32 v[180:181], v[176:177]
	global_load_dwordx4 v[90:93], v[60:61], off offset:16
	global_load_dwordx4 v[94:97], v[60:61], off
	global_load_dwordx4 v[82:85], v[62:63], off offset:16
	global_load_dwordx4 v[86:89], v[62:63], off
	global_load_dwordx4 v[66:69], v[60:61], off offset:528
	global_load_dwordx4 v[70:73], v[60:61], off offset:512
	s_nop 0
	global_load_dwordx4 v[58:61], v[62:63], off offset:528
	s_nop 0
	global_load_dwordx4 v[62:65], v[62:63], off offset:512
	global_load_dwordx4 v[186:189], v[180:181], off
	global_load_dwordx4 v[200:203], v[176:177], off offset:256
	v_cndmask_b32_e64 v185, 0, 1, s[34:35]
	v_cmp_ne_u32_e64 s[42:43], 1, v185
	s_andn2_b64 vcc, exec, s[34:35]
	s_waitcnt vmcnt(1)
	v_cvt_f32_f16_e32 v190, v186
	v_cvt_f32_f16_sdwa v191, v186 dst_sel:DWORD dst_unused:UNUSED_PAD src0_sel:WORD_1
	v_cvt_f32_f16_e32 v186, v187
	v_cvt_f32_f16_sdwa v187, v187 dst_sel:DWORD dst_unused:UNUSED_PAD src0_sel:WORD_1
	v_cvt_f32_f16_e32 v192, v188
	v_cvt_f32_f16_e32 v194, v189
	v_cvt_f32_f16_sdwa v195, v189 dst_sel:DWORD dst_unused:UNUSED_PAD src0_sel:WORD_1
	v_cvt_f32_f16_sdwa v193, v188 dst_sel:DWORD dst_unused:UNUSED_PAD src0_sel:WORD_1
	v_pk_fma_f32 v[160:161], v[160:161], v[96:97], v[186:187]
	v_pk_fma_f32 v[158:159], v[158:159], v[94:95], v[190:191]
	v_pk_fma_f32 v[156:157], v[156:157], v[92:93], v[194:195]
	v_pk_fma_f32 v[154:155], v[154:155], v[90:91], v[192:193]
	v_cvt_pk_f16_f32 v186, v158, v159
	v_cvt_pk_f16_f32 v187, v160, v161
	v_cvt_pk_f16_f32 v188, v154, v155
	v_cvt_pk_f16_f32 v189, v156, v157
	global_store_dwordx4 v[180:181], v[186:189], off
	s_cbranch_vccnz .LBB0_506
	s_nop 0
	v_mov_b32_e32 v188, v159
	v_mov_b32_e32 v189, v155
	v_mov_b32_e32 v192, v161
	v_mov_b32_e32 v193, v157
	v_mov_b32_e32 v186, v158
	v_mov_b32_e32 v187, v154
	v_pk_mul_f32 v[188:189], v[188:189], v[188:189]
	v_mov_b32_e32 v190, v160
	v_mov_b32_e32 v191, v156
	v_pk_mul_f32 v[192:193], v[192:193], v[192:193]
	v_pk_fma_f32 v[186:187], v[186:187], v[186:187], v[188:189]
	v_pk_fma_f32 v[188:189], v[190:191], v[190:191], v[192:193]
	v_pk_mul_f32 v[160:161], v[88:89], v[160:161]
	v_pk_add_f32 v[186:187], v[186:187], v[188:189]
	v_pk_mul_f32 v[158:159], v[86:87], v[158:159]
	v_add_f32_e32 v185, v186, v187
	v_pk_mul_f32 v[186:187], v[84:85], v[156:157]
	v_pk_mul_f32 v[156:157], v[82:83], v[154:155]
	v_cvt_pk_bf16_f32 v154, v158, v159
	v_cvt_pk_bf16_f32 v155, v160, v161
	s_nop 0
	v_cvt_pk_bf16_f32 v156, v156, v157
	v_cvt_pk_bf16_f32 v157, v186, v187
	global_store_dwordx4 v[178:179], v[154:157], off
	s_branch .LBB0_507

.LBB0_507:
	v_mov_b32_e32 v206, 0x8000
	v_lshl_add_u64 v[204:205], v[176:177], 0, v[206:207]
	global_load_dwordx4 v[196:199], v[204:205], off
	v_cmp_eq_u32_e64 s[44:45], 0, v184
	s_and_b64 vcc, exec, s[42:43]
	s_movk_i32 s78, 0x6000
	s_waitcnt vmcnt(2)
	v_cvt_f32_f16_sdwa v159, v200 dst_sel:DWORD dst_unused:UNUSED_PAD src0_sel:WORD_1
	v_cvt_f32_f16_e32 v158, v200
	v_cvt_f32_f16_sdwa v161, v201 dst_sel:DWORD dst_unused:UNUSED_PAD src0_sel:WORD_1
	v_cvt_f32_f16_e32 v160, v201
	v_cvt_f32_f16_sdwa v155, v202 dst_sel:DWORD dst_unused:UNUSED_PAD src0_sel:WORD_1
	v_cvt_f32_f16_sdwa v187, v203 dst_sel:DWORD dst_unused:UNUSED_PAD src0_sel:WORD_1
	v_cvt_f32_f16_e32 v186, v203
	v_cvt_f32_f16_e32 v154, v202
	v_pk_fma_f32 v[152:153], v[152:153], v[72:73], v[160:161]
	v_pk_fma_f32 v[150:151], v[150:151], v[70:71], v[158:159]
	v_pk_fma_f32 v[148:149], v[148:149], v[68:69], v[186:187]
	v_pk_fma_f32 v[146:147], v[146:147], v[66:67], v[154:155]
	v_cvt_pk_f16_f32 v154, v150, v151
	v_cvt_pk_f16_f32 v155, v152, v153
	v_cvt_pk_f16_f32 v156, v146, v147
	v_cvt_pk_f16_f32 v157, v148, v149
	global_store_dwordx4 v[180:181], v[154:157], off offset:256
	s_cbranch_vccnz .LBB0_511
	s_nop 0
	v_pk_mul_f32 v[154:155], v[62:63], v[150:151]
	v_pk_mul_f32 v[160:161], v[58:59], v[146:147]
	v_mul_f32_e32 v151, v151, v151
	v_mul_f32_e32 v147, v147, v147
	v_fmac_f32_e32 v151, v150, v150
	v_mul_f32_e32 v150, v153, v153
	v_fmac_f32_e32 v147, v146, v146
	v_mul_f32_e32 v146, v149, v149
	v_fmac_f32_e32 v150, v152, v152
	v_fmac_f32_e32 v146, v148, v148
	v_add_f32_e32 v150, v151, v150
	v_add_f32_e32 v146, v147, v146
	v_add_f32_e32 v146, v150, v146
	v_add_f32_e32 v146, v185, v146
	v_mov_b32_e32 v147, v146
	s_nop 1
	v_permlane16_swap_b32_e32 v146, v147
	v_add_f32_e32 v146, v146, v147
	v_mov_b32_e32 v147, v146
	v_pk_mul_f32 v[156:157], v[64:65], v[152:153]
	s_nop 0
	v_permlane32_swap_b32_e32 v146, v147
	v_pk_mul_f32 v[158:159], v[60:61], v[148:149]
	v_cvt_pk_bf16_f32 v154, v154, v155
	v_cvt_pk_bf16_f32 v155, v156, v157
	v_cvt_pk_bf16_f32 v156, v160, v161
	s_nop 0
	v_cvt_pk_bf16_f32 v157, v158, v159
	global_store_dwordx4 v[178:179], v[154:157], off offset:256
	s_and_saveexec_b64 s[2:3], s[44:45]
	v_lshl_add_u32 v148, v173, 2, s67
	v_add_f32_e32 v146, v146, v147
	ds_write_b32 v148, v146
	s_or_b64 exec, exec, s[2:3]
.LBB0_511:
	v_mov_b64_e32 v[148:149], v[176:177]
	v_mov_b64_e32 v[146:147], v[174:175]
	s_nop 0
	v_add_co_u32_e32 v154, vcc, 0x8000, v148
	s_nop 1
	v_addc_co_u32_e32 v155, vcc, 0, v149, vcc
	v_mov_b32_e32 v206, 0x8000
	v_lshl_add_u64 v[204:205], v[176:177], 0, v[206:207]
	global_load_dwordx4 v[200:203], v[204:205], off offset:256
	s_and_b64 vcc, exec, s[42:43]
	s_waitcnt vmcnt(2)
	v_cvt_f32_f16_e32 v156, v196
	v_cvt_f32_f16_sdwa v157, v196 dst_sel:DWORD dst_unused:UNUSED_PAD src0_sel:WORD_1
	v_cvt_f32_f16_e32 v150, v197
	v_cvt_f32_f16_sdwa v151, v197 dst_sel:DWORD dst_unused:UNUSED_PAD src0_sel:WORD_1
	v_cvt_f32_f16_e32 v158, v198
	v_cvt_f32_f16_e32 v160, v199
	v_cvt_f32_f16_sdwa v161, v199 dst_sel:DWORD dst_unused:UNUSED_PAD src0_sel:WORD_1
	v_cvt_f32_f16_sdwa v159, v198 dst_sel:DWORD dst_unused:UNUSED_PAD src0_sel:WORD_1
	v_pk_fma_f32 v[144:145], v[144:145], v[96:97], v[150:151]
	v_pk_fma_f32 v[142:143], v[142:143], v[94:95], v[156:157]
	v_pk_fma_f32 v[140:141], v[140:141], v[92:93], v[160:161]
	v_pk_fma_f32 v[138:139], v[138:139], v[90:91], v[158:159]
	v_cvt_pk_f16_f32 v150, v142, v143
	v_cvt_pk_f16_f32 v151, v144, v145
	v_cvt_pk_f16_f32 v152, v138, v139
	v_cvt_pk_f16_f32 v153, v140, v141
	global_store_dwordx4 v[154:155], v[150:153], off
	s_cbranch_vccnz .LBB0_513
	s_nop 0
	v_mov_b32_e32 v152, v143
	v_mov_b32_e32 v153, v139
	v_mov_b32_e32 v156, v145
	v_mov_b32_e32 v157, v141
	v_mov_b32_e32 v150, v142
	v_mov_b32_e32 v151, v138
	v_pk_mul_f32 v[152:153], v[152:153], v[152:153]
	v_mov_b32_e32 v154, v144
	v_mov_b32_e32 v155, v140
	v_pk_mul_f32 v[156:157], v[156:157], v[156:157]
	v_pk_fma_f32 v[150:151], v[150:151], v[150:151], v[152:153]
	v_pk_fma_f32 v[152:153], v[154:155], v[154:155], v[156:157]
	v_pk_mul_f32 v[142:143], v[86:87], v[142:143]
	v_pk_add_f32 v[150:151], v[150:151], v[152:153]
	v_pk_mul_f32 v[152:153], v[84:85], v[140:141]
	v_pk_mul_f32 v[140:141], v[82:83], v[138:139]
	v_cvt_pk_bf16_f32 v138, v142, v143
	v_add_co_u32_e32 v142, vcc, 0x8000, v146
	v_add_f32_e32 v150, v150, v151
	s_nop 0
	v_addc_co_u32_e32 v143, vcc, 0, v147, vcc
	v_pk_mul_f32 v[144:145], v[88:89], v[144:145]
	s_nop 0
	v_cvt_pk_bf16_f32 v139, v144, v145
	v_cvt_pk_bf16_f32 v140, v140, v141
	v_cvt_pk_bf16_f32 v141, v152, v153
	global_store_dwordx4 v[142:143], v[138:141], off
	s_branch .LBB0_514

.LBB0_514:
	v_add_co_u32_e32 v142, vcc, 0x8000, v148
	s_nop 1
	v_addc_co_u32_e32 v143, vcc, 0, v149, vcc
	v_mov_b32_e32 v206, 0x10000
	v_lshl_add_u64 v[204:205], v[176:177], 0, v[206:207]
	global_load_dwordx4 v[196:199], v[204:205], off
	s_and_b64 vcc, exec, s[42:43]
	s_waitcnt vmcnt(2)
	v_cvt_f32_f16_e32 v144, v200
	v_cvt_f32_f16_sdwa v145, v200 dst_sel:DWORD dst_unused:UNUSED_PAD src0_sel:WORD_1
	v_cvt_f32_f16_e32 v138, v201
	v_cvt_f32_f16_sdwa v139, v201 dst_sel:DWORD dst_unused:UNUSED_PAD src0_sel:WORD_1
	v_cvt_f32_f16_e32 v148, v202
	v_cvt_f32_f16_e32 v152, v203
	v_cvt_f32_f16_sdwa v153, v203 dst_sel:DWORD dst_unused:UNUSED_PAD src0_sel:WORD_1
	v_cvt_f32_f16_sdwa v149, v202 dst_sel:DWORD dst_unused:UNUSED_PAD src0_sel:WORD_1
	v_pk_fma_f32 v[136:137], v[136:137], v[72:73], v[138:139]
	v_pk_fma_f32 v[134:135], v[134:135], v[70:71], v[144:145]
	v_pk_fma_f32 v[132:133], v[132:133], v[68:69], v[152:153]
	v_pk_fma_f32 v[130:131], v[130:131], v[66:67], v[148:149]
	v_cvt_pk_f16_f32 v138, v134, v135
	v_cvt_pk_f16_f32 v139, v136, v137
	v_cvt_pk_f16_f32 v140, v130, v131
	v_cvt_pk_f16_f32 v141, v132, v133
	global_store_dwordx4 v[142:143], v[138:141], off offset:256
	s_cbranch_vccnz .LBB0_518
	s_nop 0
	v_pk_mul_f32 v[138:139], v[62:63], v[134:135]
	v_pk_mul_f32 v[144:145], v[58:59], v[130:131]
	v_mul_f32_e32 v135, v135, v135
	v_mul_f32_e32 v131, v131, v131
	v_fmac_f32_e32 v135, v134, v134
	v_mul_f32_e32 v134, v137, v137
	v_fmac_f32_e32 v131, v130, v130
	v_mul_f32_e32 v130, v133, v133
	v_fmac_f32_e32 v134, v136, v136
	v_fmac_f32_e32 v130, v132, v132
	v_add_f32_e32 v134, v135, v134
	v_add_f32_e32 v130, v131, v130
	v_add_f32_e32 v130, v134, v130
	v_add_f32_e32 v130, v150, v130
	v_mov_b32_e32 v131, v130
	s_nop 1
	v_permlane16_swap_b32_e32 v130, v131
	v_pk_mul_f32 v[140:141], v[64:65], v[136:137]
	v_pk_mul_f32 v[142:143], v[60:61], v[132:133]
	s_mov_b32 s2, 0x8000
	v_add_f32_e32 v130, v130, v131
	v_cvt_pk_bf16_f32 v138, v138, v139
	v_cvt_pk_bf16_f32 v139, v140, v141
	v_cvt_pk_bf16_f32 v140, v144, v145
	v_cvt_pk_bf16_f32 v141, v142, v143
	v_add_co_u32_e32 v142, vcc, s2, v146
	v_mov_b32_e32 v131, v130
	s_nop 0
	v_addc_co_u32_e32 v143, vcc, 0, v147, vcc
	v_permlane32_swap_b32_e32 v130, v131
	global_store_dwordx4 v[142:143], v[138:141], off offset:256
	s_and_saveexec_b64 s[2:3], s[44:45]
	v_lshl_add_u32 v132, v173, 2, s67
	v_add_f32_e32 v130, v130, v131
	ds_write_b32 v132, v130 offset:64
	s_or_b64 exec, exec, s[2:3]
.LBB0_518:
	v_mov_b64_e32 v[130:131], v[174:175]
	v_mov_b64_e32 v[132:133], v[176:177]
	s_nop 0
	v_add_co_u32_e32 v138, vcc, 0x10000, v132
	s_nop 1
	v_addc_co_u32_e32 v139, vcc, 0, v133, vcc
	v_mov_b32_e32 v206, 0x10000
	v_lshl_add_u64 v[204:205], v[176:177], 0, v[206:207]
	global_load_dwordx4 v[200:203], v[204:205], off offset:256
	s_and_b64 vcc, exec, s[42:43]
	s_waitcnt vmcnt(2)
	v_cvt_f32_f16_e32 v140, v196
	v_cvt_f32_f16_sdwa v141, v196 dst_sel:DWORD dst_unused:UNUSED_PAD src0_sel:WORD_1
	v_cvt_f32_f16_e32 v134, v197
	v_cvt_f32_f16_sdwa v135, v197 dst_sel:DWORD dst_unused:UNUSED_PAD src0_sel:WORD_1
	v_cvt_f32_f16_e32 v142, v198
	v_cvt_f32_f16_e32 v144, v199
	v_cvt_f32_f16_sdwa v145, v199 dst_sel:DWORD dst_unused:UNUSED_PAD src0_sel:WORD_1
	v_cvt_f32_f16_sdwa v143, v198 dst_sel:DWORD dst_unused:UNUSED_PAD src0_sel:WORD_1
	v_pk_fma_f32 v[128:129], v[128:129], v[96:97], v[134:135]
	v_pk_fma_f32 v[126:127], v[126:127], v[94:95], v[140:141]
	v_pk_fma_f32 v[124:125], v[124:125], v[92:93], v[144:145]
	v_pk_fma_f32 v[122:123], v[122:123], v[90:91], v[142:143]
	v_cvt_pk_f16_f32 v134, v126, v127
	v_cvt_pk_f16_f32 v135, v128, v129
	v_cvt_pk_f16_f32 v136, v122, v123
	v_cvt_pk_f16_f32 v137, v124, v125
	global_store_dwordx4 v[138:139], v[134:137], off
	s_cbranch_vccnz .LBB0_520
	s_nop 0
	v_mov_b32_e32 v136, v127
	v_mov_b32_e32 v137, v123
	v_mov_b32_e32 v140, v129
	v_mov_b32_e32 v141, v125
	v_mov_b32_e32 v134, v126
	v_mov_b32_e32 v135, v122
	v_pk_mul_f32 v[136:137], v[136:137], v[136:137]
	v_mov_b32_e32 v138, v128
	v_mov_b32_e32 v139, v124
	v_pk_mul_f32 v[140:141], v[140:141], v[140:141]
	v_pk_fma_f32 v[134:135], v[134:135], v[134:135], v[136:137]
	v_pk_fma_f32 v[136:137], v[138:139], v[138:139], v[140:141]
	v_pk_mul_f32 v[126:127], v[86:87], v[126:127]
	v_pk_add_f32 v[134:135], v[134:135], v[136:137]
	v_pk_mul_f32 v[136:137], v[84:85], v[124:125]
	v_pk_mul_f32 v[124:125], v[82:83], v[122:123]
	v_cvt_pk_bf16_f32 v122, v126, v127
	v_add_co_u32_e32 v126, vcc, 0x10000, v130
	v_add_f32_e32 v134, v134, v135
	s_nop 0
	v_addc_co_u32_e32 v127, vcc, 0, v131, vcc
	v_pk_mul_f32 v[128:129], v[88:89], v[128:129]
	s_nop 0
	v_cvt_pk_bf16_f32 v123, v128, v129
	v_cvt_pk_bf16_f32 v124, v124, v125
	v_cvt_pk_bf16_f32 v125, v136, v137
	global_store_dwordx4 v[126:127], v[122:125], off
	s_branch .LBB0_521

.LBB0_521:
	v_add_co_u32_e32 v126, vcc, 0x10000, v132
	s_nop 1
	v_addc_co_u32_e32 v127, vcc, 0, v133, vcc
	v_mov_b32_e32 v206, 0x18000
	v_lshl_add_u64 v[204:205], v[176:177], 0, v[206:207]
	global_load_dwordx4 v[196:199], v[204:205], off
	s_and_b64 vcc, exec, s[42:43]
	s_waitcnt vmcnt(2)
	v_cvt_f32_f16_e32 v128, v200
	v_cvt_f32_f16_sdwa v129, v200 dst_sel:DWORD dst_unused:UNUSED_PAD src0_sel:WORD_1
	v_cvt_f32_f16_e32 v122, v201
	v_cvt_f32_f16_sdwa v123, v201 dst_sel:DWORD dst_unused:UNUSED_PAD src0_sel:WORD_1
	v_cvt_f32_f16_e32 v132, v202
	v_cvt_f32_f16_e32 v136, v203
	v_cvt_f32_f16_sdwa v137, v203 dst_sel:DWORD dst_unused:UNUSED_PAD src0_sel:WORD_1
	v_cvt_f32_f16_sdwa v133, v202 dst_sel:DWORD dst_unused:UNUSED_PAD src0_sel:WORD_1
	v_pk_fma_f32 v[120:121], v[120:121], v[72:73], v[122:123]
	v_pk_fma_f32 v[118:119], v[118:119], v[70:71], v[128:129]
	v_pk_fma_f32 v[116:117], v[116:117], v[68:69], v[136:137]
	v_pk_fma_f32 v[114:115], v[114:115], v[66:67], v[132:133]
	v_cvt_pk_f16_f32 v122, v118, v119
	v_cvt_pk_f16_f32 v123, v120, v121
	v_cvt_pk_f16_f32 v124, v114, v115
	v_cvt_pk_f16_f32 v125, v116, v117
	global_store_dwordx4 v[126:127], v[122:125], off offset:256
	s_cbranch_vccnz .LBB0_525
	s_nop 0
	v_pk_mul_f32 v[122:123], v[62:63], v[118:119]
	v_pk_mul_f32 v[128:129], v[58:59], v[114:115]
	v_mul_f32_e32 v119, v119, v119
	v_mul_f32_e32 v115, v115, v115
	v_fmac_f32_e32 v119, v118, v118
	v_mul_f32_e32 v118, v121, v121
	v_fmac_f32_e32 v115, v114, v114
	v_mul_f32_e32 v114, v117, v117
	v_fmac_f32_e32 v118, v120, v120
	v_fmac_f32_e32 v114, v116, v116
	v_add_f32_e32 v118, v119, v118
	v_add_f32_e32 v114, v115, v114
	v_add_f32_e32 v114, v118, v114
	v_add_f32_e32 v114, v134, v114
	v_mov_b32_e32 v115, v114
	s_nop 1
	v_permlane16_swap_b32_e32 v114, v115
	v_pk_mul_f32 v[124:125], v[64:65], v[120:121]
	v_pk_mul_f32 v[126:127], v[60:61], v[116:117]
	s_mov_b32 s2, 0x10000
	v_add_f32_e32 v114, v114, v115
	v_cvt_pk_bf16_f32 v122, v122, v123
	v_cvt_pk_bf16_f32 v123, v124, v125
	v_cvt_pk_bf16_f32 v124, v128, v129
	v_cvt_pk_bf16_f32 v125, v126, v127
	v_add_co_u32_e32 v126, vcc, s2, v130
	v_mov_b32_e32 v115, v114
	s_nop 0
	v_addc_co_u32_e32 v127, vcc, 0, v131, vcc
	v_permlane32_swap_b32_e32 v114, v115
	global_store_dwordx4 v[126:127], v[122:125], off offset:256
	s_and_saveexec_b64 s[2:3], s[44:45]
	v_lshl_add_u32 v116, v173, 2, s67
	v_add_f32_e32 v114, v114, v115
	ds_write_b32 v116, v114 offset:128
	s_or_b64 exec, exec, s[2:3]
.LBB0_525:
	v_mov_b64_e32 v[116:117], v[176:177]
	v_mov_b64_e32 v[114:115], v[174:175]
	s_nop 0
	v_add_co_u32_e32 v122, vcc, 0x18000, v116
	s_nop 1
	v_addc_co_u32_e32 v123, vcc, 0, v117, vcc
	v_mov_b32_e32 v206, 0x18000
	v_lshl_add_u64 v[204:205], v[176:177], 0, v[206:207]
	global_load_dwordx4 v[200:203], v[204:205], off offset:256
	s_and_b64 vcc, exec, s[42:43]
	s_waitcnt vmcnt(2)
	v_cvt_f32_f16_e32 v124, v196
	v_cvt_f32_f16_sdwa v125, v196 dst_sel:DWORD dst_unused:UNUSED_PAD src0_sel:WORD_1
	v_cvt_f32_f16_e32 v118, v197
	v_cvt_f32_f16_sdwa v119, v197 dst_sel:DWORD dst_unused:UNUSED_PAD src0_sel:WORD_1
	v_cvt_f32_f16_e32 v126, v198
	v_cvt_f32_f16_e32 v128, v199
	v_cvt_f32_f16_sdwa v129, v199 dst_sel:DWORD dst_unused:UNUSED_PAD src0_sel:WORD_1
	v_cvt_f32_f16_sdwa v127, v198 dst_sel:DWORD dst_unused:UNUSED_PAD src0_sel:WORD_1
	v_pk_fma_f32 v[112:113], v[112:113], v[96:97], v[118:119]
	v_pk_fma_f32 v[110:111], v[110:111], v[94:95], v[124:125]
	v_pk_fma_f32 v[108:109], v[108:109], v[92:93], v[128:129]
	v_pk_fma_f32 v[106:107], v[106:107], v[90:91], v[126:127]
	v_cvt_pk_f16_f32 v118, v110, v111
	v_cvt_pk_f16_f32 v119, v112, v113
	v_cvt_pk_f16_f32 v120, v106, v107
	v_cvt_pk_f16_f32 v121, v108, v109
	global_store_dwordx4 v[122:123], v[118:121], off
	s_cbranch_vccnz .LBB0_527
	s_nop 0
	v_mov_b32_e32 v120, v111
	v_mov_b32_e32 v121, v107
	v_mov_b32_e32 v124, v113
	v_mov_b32_e32 v125, v109
	v_mov_b32_e32 v118, v110
	v_mov_b32_e32 v119, v106
	v_pk_mul_f32 v[120:121], v[120:121], v[120:121]
	v_mov_b32_e32 v122, v112
	v_mov_b32_e32 v123, v108
	v_pk_mul_f32 v[124:125], v[124:125], v[124:125]
	v_pk_fma_f32 v[118:119], v[118:119], v[118:119], v[120:121]
	v_pk_fma_f32 v[120:121], v[122:123], v[122:123], v[124:125]
	v_pk_mul_f32 v[110:111], v[86:87], v[110:111]
	v_pk_add_f32 v[118:119], v[118:119], v[120:121]
	v_pk_mul_f32 v[120:121], v[84:85], v[108:109]
	v_pk_mul_f32 v[108:109], v[82:83], v[106:107]
	v_cvt_pk_bf16_f32 v106, v110, v111
	v_add_co_u32_e32 v110, vcc, 0x18000, v114
	v_add_f32_e32 v118, v118, v119
	s_nop 0
	v_addc_co_u32_e32 v111, vcc, 0, v115, vcc
	v_pk_mul_f32 v[112:113], v[88:89], v[112:113]
	s_nop 0
	v_cvt_pk_bf16_f32 v107, v112, v113
	v_cvt_pk_bf16_f32 v108, v108, v109
	v_cvt_pk_bf16_f32 v109, v120, v121
	global_store_dwordx4 v[110:111], v[106:109], off
	s_branch .LBB0_528

.LBB0_528:
	v_add_co_u32_e32 v110, vcc, 0x18000, v116
	s_nop 1
	v_addc_co_u32_e32 v111, vcc, 0, v117, vcc
	v_mov_b32_e32 v206, 0x40000
	v_lshl_add_u64 v[204:205], v[176:177], 0, v[206:207]
	global_load_dwordx4 v[196:199], v[204:205], off
	s_and_b64 vcc, exec, s[42:43]
	s_waitcnt vmcnt(2)
	v_cvt_f32_f16_e32 v112, v200
	v_cvt_f32_f16_sdwa v113, v200 dst_sel:DWORD dst_unused:UNUSED_PAD src0_sel:WORD_1
	v_cvt_f32_f16_e32 v106, v201
	v_cvt_f32_f16_sdwa v107, v201 dst_sel:DWORD dst_unused:UNUSED_PAD src0_sel:WORD_1
	v_cvt_f32_f16_e32 v116, v202
	v_cvt_f32_f16_e32 v120, v203
	v_cvt_f32_f16_sdwa v121, v203 dst_sel:DWORD dst_unused:UNUSED_PAD src0_sel:WORD_1
	v_cvt_f32_f16_sdwa v117, v202 dst_sel:DWORD dst_unused:UNUSED_PAD src0_sel:WORD_1
	v_pk_fma_f32 v[104:105], v[104:105], v[72:73], v[106:107]
	v_pk_fma_f32 v[102:103], v[102:103], v[70:71], v[112:113]
	v_pk_fma_f32 v[100:101], v[100:101], v[68:69], v[120:121]
	v_pk_fma_f32 v[98:99], v[98:99], v[66:67], v[116:117]
	v_cvt_pk_f16_f32 v106, v102, v103
	v_cvt_pk_f16_f32 v107, v104, v105
	v_cvt_pk_f16_f32 v108, v98, v99
	v_cvt_pk_f16_f32 v109, v100, v101
	global_store_dwordx4 v[110:111], v[106:109], off offset:256
	s_cbranch_vccnz .LBB0_532
	s_nop 0
	v_pk_mul_f32 v[106:107], v[62:63], v[102:103]
	v_pk_mul_f32 v[112:113], v[58:59], v[98:99]
	v_mul_f32_e32 v103, v103, v103
	v_mul_f32_e32 v99, v99, v99
	v_fmac_f32_e32 v103, v102, v102
	v_mul_f32_e32 v102, v105, v105
	v_fmac_f32_e32 v99, v98, v98
	v_mul_f32_e32 v98, v101, v101
	v_fmac_f32_e32 v102, v104, v104
	v_fmac_f32_e32 v98, v100, v100
	v_add_f32_e32 v102, v103, v102
	v_add_f32_e32 v98, v99, v98
	v_add_f32_e32 v98, v102, v98
	v_add_f32_e32 v98, v118, v98
	v_mov_b32_e32 v99, v98
	s_nop 1
	v_permlane16_swap_b32_e32 v98, v99
	v_pk_mul_f32 v[108:109], v[64:65], v[104:105]
	v_pk_mul_f32 v[110:111], v[60:61], v[100:101]
	s_mov_b32 s2, 0x18000
	v_add_f32_e32 v98, v98, v99
	v_cvt_pk_bf16_f32 v106, v106, v107
	v_cvt_pk_bf16_f32 v107, v108, v109
	v_cvt_pk_bf16_f32 v108, v112, v113
	v_cvt_pk_bf16_f32 v109, v110, v111
	v_add_co_u32_e32 v110, vcc, s2, v114
	v_mov_b32_e32 v99, v98
	s_nop 0
	v_addc_co_u32_e32 v111, vcc, 0, v115, vcc
	v_permlane32_swap_b32_e32 v98, v99
	global_store_dwordx4 v[110:111], v[106:109], off offset:256
	s_and_saveexec_b64 s[2:3], s[44:45]
	v_lshl_add_u32 v100, v173, 2, s67
	v_add_f32_e32 v98, v98, v99
	ds_write_b32 v100, v98 offset:192
	s_or_b64 exec, exec, s[2:3]
.LBB0_532:
	v_mov_b64_e32 v[98:99], v[174:175]
	v_mov_b64_e32 v[100:101], v[176:177]
	s_nop 0
	v_add_co_u32_e32 v106, vcc, 0x40000, v100
	s_nop 1
	v_addc_co_u32_e32 v107, vcc, 0, v101, vcc
	v_mov_b32_e32 v206, 0x40000
	v_lshl_add_u64 v[204:205], v[176:177], 0, v[206:207]
	global_load_dwordx4 v[200:203], v[204:205], off offset:256
	s_and_b64 vcc, exec, s[42:43]
	s_waitcnt vmcnt(2)
	v_cvt_f32_f16_e32 v108, v196
	v_cvt_f32_f16_sdwa v109, v196 dst_sel:DWORD dst_unused:UNUSED_PAD src0_sel:WORD_1
	v_cvt_f32_f16_e32 v102, v197
	v_cvt_f32_f16_sdwa v103, v197 dst_sel:DWORD dst_unused:UNUSED_PAD src0_sel:WORD_1
	v_cvt_f32_f16_e32 v110, v198
	v_cvt_f32_f16_e32 v112, v199
	v_cvt_f32_f16_sdwa v113, v199 dst_sel:DWORD dst_unused:UNUSED_PAD src0_sel:WORD_1
	v_cvt_f32_f16_sdwa v111, v198 dst_sel:DWORD dst_unused:UNUSED_PAD src0_sel:WORD_1
	v_pk_fma_f32 v[80:81], v[80:81], v[96:97], v[102:103]
	v_pk_fma_f32 v[78:79], v[78:79], v[94:95], v[108:109]
	v_pk_fma_f32 v[76:77], v[76:77], v[92:93], v[112:113]
	v_pk_fma_f32 v[74:75], v[74:75], v[90:91], v[110:111]
	v_cvt_pk_f16_f32 v102, v78, v79
	v_cvt_pk_f16_f32 v103, v80, v81
	v_cvt_pk_f16_f32 v104, v74, v75
	v_cvt_pk_f16_f32 v105, v76, v77
	global_store_dwordx4 v[106:107], v[102:105], off
	s_cbranch_vccnz .LBB0_534
	s_nop 0
	v_mov_b32_e32 v104, v79
	v_mov_b32_e32 v105, v75
	v_mov_b32_e32 v108, v81
	v_mov_b32_e32 v109, v77
	v_mov_b32_e32 v102, v78
	v_mov_b32_e32 v103, v74
	v_pk_mul_f32 v[104:105], v[104:105], v[104:105]
	v_mov_b32_e32 v106, v80
	v_mov_b32_e32 v107, v76
	v_pk_mul_f32 v[108:109], v[108:109], v[108:109]
	v_pk_fma_f32 v[102:103], v[102:103], v[102:103], v[104:105]
	v_pk_fma_f32 v[104:105], v[106:107], v[106:107], v[108:109]
	v_pk_mul_f32 v[78:79], v[86:87], v[78:79]
	v_pk_add_f32 v[102:103], v[102:103], v[104:105]
	v_pk_mul_f32 v[104:105], v[84:85], v[76:77]
	v_pk_mul_f32 v[76:77], v[82:83], v[74:75]
	v_cvt_pk_bf16_f32 v74, v78, v79
	v_add_co_u32_e32 v78, vcc, 0x40000, v98
	v_add_f32_e32 v102, v102, v103
	s_nop 0
	v_addc_co_u32_e32 v79, vcc, 0, v99, vcc
	v_pk_mul_f32 v[80:81], v[88:89], v[80:81]
	s_nop 0
	v_cvt_pk_bf16_f32 v75, v80, v81
	v_cvt_pk_bf16_f32 v76, v76, v77
	v_cvt_pk_bf16_f32 v77, v104, v105
	global_store_dwordx4 v[78:79], v[74:77], off
	s_branch .LBB0_535

.LBB0_535:
	v_add_co_u32_e32 v78, vcc, 0x40000, v100
	s_nop 1
	v_addc_co_u32_e32 v79, vcc, 0, v101, vcc
	v_mov_b32_e32 v206, 0x48000
	v_lshl_add_u64 v[204:205], v[176:177], 0, v[206:207]
	global_load_dwordx4 v[196:199], v[204:205], off
	s_and_b64 vcc, exec, s[42:43]
	s_waitcnt vmcnt(2)
	v_cvt_f32_f16_e32 v80, v200
	v_cvt_f32_f16_sdwa v81, v200 dst_sel:DWORD dst_unused:UNUSED_PAD src0_sel:WORD_1
	v_cvt_f32_f16_e32 v74, v201
	v_cvt_f32_f16_sdwa v75, v201 dst_sel:DWORD dst_unused:UNUSED_PAD src0_sel:WORD_1
	v_cvt_f32_f16_e32 v100, v202
	v_cvt_f32_f16_e32 v104, v203
	v_cvt_f32_f16_sdwa v105, v203 dst_sel:DWORD dst_unused:UNUSED_PAD src0_sel:WORD_1
	v_cvt_f32_f16_sdwa v101, v202 dst_sel:DWORD dst_unused:UNUSED_PAD src0_sel:WORD_1
	v_pk_fma_f32 v[56:57], v[56:57], v[72:73], v[74:75]
	v_pk_fma_f32 v[54:55], v[54:55], v[70:71], v[80:81]
	v_pk_fma_f32 v[52:53], v[52:53], v[68:69], v[104:105]
	v_pk_fma_f32 v[50:51], v[50:51], v[66:67], v[100:101]
	v_cvt_pk_f16_f32 v74, v54, v55
	v_cvt_pk_f16_f32 v75, v56, v57
	v_cvt_pk_f16_f32 v76, v50, v51
	v_cvt_pk_f16_f32 v77, v52, v53
	global_store_dwordx4 v[78:79], v[74:77], off offset:256
	s_cbranch_vccnz .LBB0_539
	s_nop 0
	v_pk_mul_f32 v[74:75], v[62:63], v[54:55]
	v_pk_mul_f32 v[80:81], v[58:59], v[50:51]
	v_mul_f32_e32 v55, v55, v55
	v_mul_f32_e32 v51, v51, v51
	v_fmac_f32_e32 v55, v54, v54
	v_mul_f32_e32 v54, v57, v57
	v_fmac_f32_e32 v51, v50, v50
	v_mul_f32_e32 v50, v53, v53
	v_fmac_f32_e32 v54, v56, v56
	v_fmac_f32_e32 v50, v52, v52
	v_add_f32_e32 v54, v55, v54
	v_add_f32_e32 v50, v51, v50
	v_add_f32_e32 v50, v54, v50
	v_add_f32_e32 v50, v102, v50
	v_mov_b32_e32 v51, v50
	s_nop 1
	v_permlane16_swap_b32_e32 v50, v51
	v_pk_mul_f32 v[76:77], v[64:65], v[56:57]
	v_pk_mul_f32 v[78:79], v[60:61], v[52:53]
	s_mov_b32 s2, 0x40000
	v_add_f32_e32 v50, v50, v51
	v_cvt_pk_bf16_f32 v74, v74, v75
	v_cvt_pk_bf16_f32 v75, v76, v77
	v_cvt_pk_bf16_f32 v76, v80, v81
	v_cvt_pk_bf16_f32 v77, v78, v79
	v_add_co_u32_e32 v78, vcc, s2, v98
	v_mov_b32_e32 v51, v50
	s_nop 0
	v_addc_co_u32_e32 v79, vcc, 0, v99, vcc
	v_permlane32_swap_b32_e32 v50, v51
	global_store_dwordx4 v[78:79], v[74:77], off offset:256
	s_and_saveexec_b64 s[2:3], s[44:45]
	v_lshl_add_u32 v52, v173, 2, s67
	v_add_f32_e32 v50, v50, v51
	ds_write_b32 v52, v50 offset:512
	s_or_b64 exec, exec, s[2:3]
.LBB0_539:
	v_mov_b64_e32 v[50:51], v[174:175]
	v_mov_b64_e32 v[52:53], v[176:177]
	s_nop 0
	v_add_co_u32_e32 v74, vcc, 0x48000, v52
	s_nop 1
	v_addc_co_u32_e32 v75, vcc, 0, v53, vcc
	v_mov_b32_e32 v206, 0x48000
	v_lshl_add_u64 v[204:205], v[176:177], 0, v[206:207]
	global_load_dwordx4 v[200:203], v[204:205], off offset:256
	s_and_b64 vcc, exec, s[42:43]
	s_waitcnt vmcnt(2)
	v_cvt_f32_f16_e32 v76, v196
	v_cvt_f32_f16_sdwa v77, v196 dst_sel:DWORD dst_unused:UNUSED_PAD src0_sel:WORD_1
	v_cvt_f32_f16_e32 v54, v197
	v_cvt_f32_f16_sdwa v55, v197 dst_sel:DWORD dst_unused:UNUSED_PAD src0_sel:WORD_1
	v_cvt_f32_f16_e32 v78, v198
	v_cvt_f32_f16_e32 v80, v199
	v_cvt_f32_f16_sdwa v81, v199 dst_sel:DWORD dst_unused:UNUSED_PAD src0_sel:WORD_1
	v_cvt_f32_f16_sdwa v79, v198 dst_sel:DWORD dst_unused:UNUSED_PAD src0_sel:WORD_1
	v_pk_fma_f32 v[48:49], v[48:49], v[96:97], v[54:55]
	v_pk_fma_f32 v[46:47], v[46:47], v[94:95], v[76:77]
	v_pk_fma_f32 v[44:45], v[44:45], v[92:93], v[80:81]
	v_pk_fma_f32 v[42:43], v[42:43], v[90:91], v[78:79]
	v_cvt_pk_f16_f32 v54, v46, v47
	v_cvt_pk_f16_f32 v55, v48, v49
	v_cvt_pk_f16_f32 v56, v42, v43
	v_cvt_pk_f16_f32 v57, v44, v45
	global_store_dwordx4 v[74:75], v[54:57], off
	s_cbranch_vccnz .LBB0_541
	s_nop 0
	v_mov_b32_e32 v56, v47
	v_mov_b32_e32 v57, v43
	v_mov_b32_e32 v76, v49
	v_mov_b32_e32 v77, v45
	v_mov_b32_e32 v54, v46
	v_mov_b32_e32 v55, v42
	v_pk_mul_f32 v[56:57], v[56:57], v[56:57]
	v_mov_b32_e32 v74, v48
	v_mov_b32_e32 v75, v44
	v_pk_mul_f32 v[76:77], v[76:77], v[76:77]
	v_pk_fma_f32 v[54:55], v[54:55], v[54:55], v[56:57]
	v_pk_fma_f32 v[56:57], v[74:75], v[74:75], v[76:77]
	v_pk_mul_f32 v[46:47], v[86:87], v[46:47]
	v_pk_add_f32 v[54:55], v[54:55], v[56:57]
	v_pk_mul_f32 v[56:57], v[84:85], v[44:45]
	v_pk_mul_f32 v[44:45], v[82:83], v[42:43]
	v_cvt_pk_bf16_f32 v42, v46, v47
	v_add_co_u32_e32 v46, vcc, 0x48000, v50
	v_add_f32_e32 v54, v54, v55
	s_nop 0
	v_addc_co_u32_e32 v47, vcc, 0, v51, vcc
	v_pk_mul_f32 v[48:49], v[88:89], v[48:49]
	s_nop 0
	v_cvt_pk_bf16_f32 v43, v48, v49
	v_cvt_pk_bf16_f32 v44, v44, v45
	v_cvt_pk_bf16_f32 v45, v56, v57
	global_store_dwordx4 v[46:47], v[42:45], off
	s_branch .LBB0_542

.LBB0_542:
	v_add_co_u32_e32 v46, vcc, 0x48000, v52
	s_nop 1
	v_addc_co_u32_e32 v47, vcc, 0, v53, vcc
	v_mov_b32_e32 v206, 0x50000
	v_lshl_add_u64 v[204:205], v[176:177], 0, v[206:207]
	global_load_dwordx4 v[196:199], v[204:205], off
	s_and_b64 vcc, exec, s[42:43]
	s_waitcnt vmcnt(2)
	v_cvt_f32_f16_e32 v48, v200
	v_cvt_f32_f16_sdwa v49, v200 dst_sel:DWORD dst_unused:UNUSED_PAD src0_sel:WORD_1
	v_cvt_f32_f16_e32 v42, v201
	v_cvt_f32_f16_sdwa v43, v201 dst_sel:DWORD dst_unused:UNUSED_PAD src0_sel:WORD_1
	v_cvt_f32_f16_e32 v52, v202
	v_cvt_f32_f16_e32 v56, v203
	v_cvt_f32_f16_sdwa v57, v203 dst_sel:DWORD dst_unused:UNUSED_PAD src0_sel:WORD_1
	v_cvt_f32_f16_sdwa v53, v202 dst_sel:DWORD dst_unused:UNUSED_PAD src0_sel:WORD_1
	v_pk_fma_f32 v[40:41], v[40:41], v[72:73], v[42:43]
	v_pk_fma_f32 v[38:39], v[38:39], v[70:71], v[48:49]
	v_pk_fma_f32 v[36:37], v[36:37], v[68:69], v[56:57]
	v_pk_fma_f32 v[34:35], v[34:35], v[66:67], v[52:53]
	v_cvt_pk_f16_f32 v42, v38, v39
	v_cvt_pk_f16_f32 v43, v40, v41
	v_cvt_pk_f16_f32 v44, v34, v35
	v_cvt_pk_f16_f32 v45, v36, v37
	global_store_dwordx4 v[46:47], v[42:45], off offset:256
	s_cbranch_vccnz .LBB0_546
	s_nop 0
	v_pk_mul_f32 v[42:43], v[62:63], v[38:39]
	v_pk_mul_f32 v[48:49], v[58:59], v[34:35]
	v_mul_f32_e32 v39, v39, v39
	v_mul_f32_e32 v35, v35, v35
	v_fmac_f32_e32 v39, v38, v38
	v_mul_f32_e32 v38, v41, v41
	v_fmac_f32_e32 v35, v34, v34
	v_mul_f32_e32 v34, v37, v37
	v_fmac_f32_e32 v38, v40, v40
	v_fmac_f32_e32 v34, v36, v36
	v_add_f32_e32 v38, v39, v38
	v_add_f32_e32 v34, v35, v34
	v_add_f32_e32 v34, v38, v34
	v_add_f32_e32 v34, v54, v34
	v_mov_b32_e32 v35, v34
	s_nop 1
	v_permlane16_swap_b32_e32 v34, v35
	v_pk_mul_f32 v[44:45], v[64:65], v[40:41]
	v_pk_mul_f32 v[46:47], v[60:61], v[36:37]
	s_mov_b32 s2, 0x48000
	v_add_f32_e32 v34, v34, v35
	v_cvt_pk_bf16_f32 v42, v42, v43
	v_cvt_pk_bf16_f32 v43, v44, v45
	v_cvt_pk_bf16_f32 v44, v48, v49
	v_cvt_pk_bf16_f32 v45, v46, v47
	v_add_co_u32_e32 v46, vcc, s2, v50
	v_mov_b32_e32 v35, v34
	s_nop 0
	v_addc_co_u32_e32 v47, vcc, 0, v51, vcc
	v_permlane32_swap_b32_e32 v34, v35
	global_store_dwordx4 v[46:47], v[42:45], off offset:256
	s_and_saveexec_b64 s[2:3], s[44:45]
	v_lshl_add_u32 v36, v173, 2, s67
	v_add_f32_e32 v34, v34, v35
	ds_write_b32 v36, v34 offset:576
	s_or_b64 exec, exec, s[2:3]
.LBB0_546:
	v_mov_b64_e32 v[36:37], v[176:177]
	v_mov_b64_e32 v[34:35], v[174:175]
	s_nop 0
	v_add_co_u32_e32 v42, vcc, 0x50000, v36
	s_nop 1
	v_addc_co_u32_e32 v43, vcc, 0, v37, vcc
	v_mov_b32_e32 v206, 0x50000
	v_lshl_add_u64 v[204:205], v[176:177], 0, v[206:207]
	global_load_dwordx4 v[200:203], v[204:205], off offset:256
	s_and_b64 vcc, exec, s[42:43]
	s_waitcnt vmcnt(2)
	v_cvt_f32_f16_e32 v44, v196
	v_cvt_f32_f16_sdwa v45, v196 dst_sel:DWORD dst_unused:UNUSED_PAD src0_sel:WORD_1
	v_cvt_f32_f16_e32 v38, v197
	v_cvt_f32_f16_sdwa v39, v197 dst_sel:DWORD dst_unused:UNUSED_PAD src0_sel:WORD_1
	v_cvt_f32_f16_e32 v46, v198
	v_cvt_f32_f16_e32 v48, v199
	v_cvt_f32_f16_sdwa v49, v199 dst_sel:DWORD dst_unused:UNUSED_PAD src0_sel:WORD_1
	v_cvt_f32_f16_sdwa v47, v198 dst_sel:DWORD dst_unused:UNUSED_PAD src0_sel:WORD_1
	v_pk_fma_f32 v[32:33], v[32:33], v[96:97], v[38:39]
	v_pk_fma_f32 v[30:31], v[30:31], v[94:95], v[44:45]
	v_pk_fma_f32 v[28:29], v[28:29], v[92:93], v[48:49]
	v_pk_fma_f32 v[26:27], v[26:27], v[90:91], v[46:47]
	v_cvt_pk_f16_f32 v38, v30, v31
	v_cvt_pk_f16_f32 v39, v32, v33
	v_cvt_pk_f16_f32 v40, v26, v27
	v_cvt_pk_f16_f32 v41, v28, v29
	global_store_dwordx4 v[42:43], v[38:41], off
	s_cbranch_vccnz .LBB0_548
	s_nop 0
	v_mov_b32_e32 v40, v31
	v_mov_b32_e32 v41, v27
	v_mov_b32_e32 v44, v33
	v_mov_b32_e32 v45, v29
	v_mov_b32_e32 v38, v30
	v_mov_b32_e32 v39, v26
	v_pk_mul_f32 v[40:41], v[40:41], v[40:41]
	v_mov_b32_e32 v42, v32
	v_mov_b32_e32 v43, v28
	v_pk_mul_f32 v[44:45], v[44:45], v[44:45]
	v_pk_fma_f32 v[38:39], v[38:39], v[38:39], v[40:41]
	v_pk_fma_f32 v[40:41], v[42:43], v[42:43], v[44:45]
	v_pk_mul_f32 v[30:31], v[86:87], v[30:31]
	v_pk_add_f32 v[38:39], v[38:39], v[40:41]
	v_pk_mul_f32 v[40:41], v[84:85], v[28:29]
	v_pk_mul_f32 v[28:29], v[82:83], v[26:27]
	v_cvt_pk_bf16_f32 v26, v30, v31
	v_add_co_u32_e32 v30, vcc, 0x50000, v34
	v_add_f32_e32 v38, v38, v39
	s_nop 0
	v_addc_co_u32_e32 v31, vcc, 0, v35, vcc
	v_pk_mul_f32 v[32:33], v[88:89], v[32:33]
	s_nop 0
	v_cvt_pk_bf16_f32 v27, v32, v33
	v_cvt_pk_bf16_f32 v28, v28, v29
	v_cvt_pk_bf16_f32 v29, v40, v41
	global_store_dwordx4 v[30:31], v[26:29], off
	s_branch .LBB0_549

.LBB0_549:
	v_add_co_u32_e32 v30, vcc, 0x50000, v36
	s_nop 1
	v_addc_co_u32_e32 v31, vcc, 0, v37, vcc
	v_mov_b32_e32 v206, 0x58000
	v_lshl_add_u64 v[204:205], v[176:177], 0, v[206:207]
	global_load_dwordx4 v[196:199], v[204:205], off
	s_and_b64 vcc, exec, s[42:43]
	s_waitcnt vmcnt(2)
	v_cvt_f32_f16_e32 v32, v200
	v_cvt_f32_f16_sdwa v33, v200 dst_sel:DWORD dst_unused:UNUSED_PAD src0_sel:WORD_1
	v_cvt_f32_f16_e32 v26, v201
	v_cvt_f32_f16_sdwa v27, v201 dst_sel:DWORD dst_unused:UNUSED_PAD src0_sel:WORD_1
	v_cvt_f32_f16_e32 v36, v202
	v_cvt_f32_f16_e32 v40, v203
	v_cvt_f32_f16_sdwa v41, v203 dst_sel:DWORD dst_unused:UNUSED_PAD src0_sel:WORD_1
	v_cvt_f32_f16_sdwa v37, v202 dst_sel:DWORD dst_unused:UNUSED_PAD src0_sel:WORD_1
	v_pk_fma_f32 v[24:25], v[24:25], v[72:73], v[26:27]
	v_pk_fma_f32 v[22:23], v[22:23], v[70:71], v[32:33]
	v_pk_fma_f32 v[20:21], v[20:21], v[68:69], v[40:41]
	v_pk_fma_f32 v[18:19], v[18:19], v[66:67], v[36:37]
	v_cvt_pk_f16_f32 v26, v22, v23
	v_cvt_pk_f16_f32 v27, v24, v25
	v_cvt_pk_f16_f32 v28, v18, v19
	v_cvt_pk_f16_f32 v29, v20, v21
	global_store_dwordx4 v[30:31], v[26:29], off offset:256
	s_cbranch_vccnz .LBB0_553
	s_nop 0
	v_pk_mul_f32 v[26:27], v[62:63], v[22:23]
	v_pk_mul_f32 v[32:33], v[58:59], v[18:19]
	v_mul_f32_e32 v23, v23, v23
	v_mul_f32_e32 v19, v19, v19
	v_fmac_f32_e32 v23, v22, v22
	v_mul_f32_e32 v22, v25, v25
	v_fmac_f32_e32 v19, v18, v18
	v_mul_f32_e32 v18, v21, v21
	v_fmac_f32_e32 v22, v24, v24
	v_fmac_f32_e32 v18, v20, v20
	v_add_f32_e32 v22, v23, v22
	v_add_f32_e32 v18, v19, v18
	v_add_f32_e32 v18, v22, v18
	v_add_f32_e32 v18, v38, v18
	v_mov_b32_e32 v19, v18
	s_nop 1
	v_permlane16_swap_b32_e32 v18, v19
	v_pk_mul_f32 v[28:29], v[64:65], v[24:25]
	v_pk_mul_f32 v[30:31], v[60:61], v[20:21]
	s_mov_b32 s2, 0x50000
	v_add_f32_e32 v18, v18, v19
	v_cvt_pk_bf16_f32 v26, v26, v27
	v_cvt_pk_bf16_f32 v27, v28, v29
	v_cvt_pk_bf16_f32 v28, v32, v33
	v_cvt_pk_bf16_f32 v29, v30, v31
	v_add_co_u32_e32 v30, vcc, s2, v34
	v_mov_b32_e32 v19, v18
	s_nop 0
	v_addc_co_u32_e32 v31, vcc, 0, v35, vcc
	v_permlane32_swap_b32_e32 v18, v19
	global_store_dwordx4 v[30:31], v[26:29], off offset:256
	s_and_saveexec_b64 s[2:3], s[44:45]
	v_lshl_add_u32 v20, v173, 2, s67
	v_add_f32_e32 v18, v18, v19
	ds_write_b32 v20, v18 offset:640
	s_or_b64 exec, exec, s[2:3]
.LBB0_553:
	s_nop 0
	v_add_co_u32_e32 v22, vcc, 0x58000, v176
	s_nop 1
	v_addc_co_u32_e32 v23, vcc, 0, v177, vcc
	v_mov_b32_e32 v206, 0x58000
	v_lshl_add_u64 v[204:205], v[176:177], 0, v[206:207]
	global_load_dwordx4 v[200:203], v[204:205], off offset:256
	s_and_b64 vcc, exec, s[42:43]
	s_waitcnt vmcnt(2)
	v_cvt_f32_f16_e32 v24, v196
	v_cvt_f32_f16_sdwa v25, v196 dst_sel:DWORD dst_unused:UNUSED_PAD src0_sel:WORD_1
	v_cvt_f32_f16_e32 v18, v197
	v_cvt_f32_f16_sdwa v19, v197 dst_sel:DWORD dst_unused:UNUSED_PAD src0_sel:WORD_1
	v_cvt_f32_f16_e32 v26, v198
	v_cvt_f32_f16_e32 v28, v199
	v_cvt_f32_f16_sdwa v29, v199 dst_sel:DWORD dst_unused:UNUSED_PAD src0_sel:WORD_1
	v_cvt_f32_f16_sdwa v27, v198 dst_sel:DWORD dst_unused:UNUSED_PAD src0_sel:WORD_1
	v_pk_fma_f32 v[16:17], v[16:17], v[96:97], v[18:19]
	v_pk_fma_f32 v[14:15], v[14:15], v[94:95], v[24:25]
	v_pk_fma_f32 v[12:13], v[12:13], v[92:93], v[28:29]
	v_pk_fma_f32 v[10:11], v[10:11], v[90:91], v[26:27]
	v_cvt_pk_f16_f32 v18, v14, v15
	v_cvt_pk_f16_f32 v19, v16, v17
	v_cvt_pk_f16_f32 v20, v10, v11
	v_cvt_pk_f16_f32 v21, v12, v13
	global_store_dwordx4 v[22:23], v[18:21], off
	s_cbranch_vccnz .LBB0_555
	s_nop 0
	v_mov_b32_e32 v20, v15
	v_mov_b32_e32 v21, v11
	v_mov_b32_e32 v24, v17
	v_mov_b32_e32 v25, v13
	v_mov_b32_e32 v18, v14
	v_mov_b32_e32 v19, v10
	v_pk_mul_f32 v[20:21], v[20:21], v[20:21]
	v_mov_b32_e32 v22, v16
	v_mov_b32_e32 v23, v12
	v_pk_mul_f32 v[24:25], v[24:25], v[24:25]
	v_pk_fma_f32 v[18:19], v[18:19], v[18:19], v[20:21]
	v_pk_fma_f32 v[20:21], v[22:23], v[22:23], v[24:25]
	v_pk_mul_f32 v[14:15], v[86:87], v[14:15]
	v_pk_add_f32 v[18:19], v[18:19], v[20:21]
	v_pk_mul_f32 v[20:21], v[84:85], v[12:13]
	v_pk_mul_f32 v[12:13], v[82:83], v[10:11]
	v_cvt_pk_bf16_f32 v10, v14, v15
	v_add_co_u32_e32 v14, vcc, 0x58000, v174
	v_add_f32_e32 v18, v18, v19
	s_nop 0
	v_addc_co_u32_e32 v15, vcc, 0, v175, vcc
	v_pk_mul_f32 v[16:17], v[88:89], v[16:17]
	s_nop 0
	v_cvt_pk_bf16_f32 v11, v16, v17
	v_cvt_pk_bf16_f32 v12, v12, v13
	v_cvt_pk_bf16_f32 v13, v20, v21
	global_store_dwordx4 v[14:15], v[10:13], off
	s_branch .LBB0_556

.LBB0_556:
	v_add_co_u32_e32 v14, vcc, 0x58000, v176
	s_nop 1
	v_addc_co_u32_e32 v15, vcc, 0, v177, vcc
	s_and_b64 vcc, exec, s[42:43]
	s_waitcnt vmcnt(1)
	v_cvt_f32_f16_e32 v16, v200
	v_cvt_f32_f16_sdwa v17, v200 dst_sel:DWORD dst_unused:UNUSED_PAD src0_sel:WORD_1
	v_cvt_f32_f16_e32 v10, v201
	v_cvt_f32_f16_sdwa v11, v201 dst_sel:DWORD dst_unused:UNUSED_PAD src0_sel:WORD_1
	v_cvt_f32_f16_e32 v20, v202
	v_cvt_f32_f16_e32 v22, v203
	v_cvt_f32_f16_sdwa v23, v203 dst_sel:DWORD dst_unused:UNUSED_PAD src0_sel:WORD_1
	v_cvt_f32_f16_sdwa v21, v202 dst_sel:DWORD dst_unused:UNUSED_PAD src0_sel:WORD_1
	v_pk_fma_f32 v[8:9], v[8:9], v[72:73], v[10:11]
	v_pk_fma_f32 v[6:7], v[6:7], v[70:71], v[16:17]
	v_pk_fma_f32 v[4:5], v[4:5], v[68:69], v[22:23]
	v_pk_fma_f32 v[2:3], v[2:3], v[66:67], v[20:21]
	v_cvt_pk_f16_f32 v10, v6, v7
	v_cvt_pk_f16_f32 v11, v8, v9
	v_cvt_pk_f16_f32 v12, v2, v3
	v_cvt_pk_f16_f32 v13, v4, v5
	global_store_dwordx4 v[14:15], v[10:13], off offset:256
	s_cbranch_vccnz .LBB0_560
	s_nop 0
	v_pk_mul_f32 v[10:11], v[62:63], v[6:7]
	v_pk_mul_f32 v[16:17], v[58:59], v[2:3]
	v_mul_f32_e32 v7, v7, v7
	v_mul_f32_e32 v3, v3, v3
	v_fmac_f32_e32 v7, v6, v6
	v_mul_f32_e32 v6, v9, v9
	v_fmac_f32_e32 v3, v2, v2
	v_mul_f32_e32 v2, v5, v5
	v_fmac_f32_e32 v6, v8, v8
	v_fmac_f32_e32 v2, v4, v4
	v_add_f32_e32 v6, v7, v6
	v_add_f32_e32 v2, v3, v2
	v_add_f32_e32 v2, v6, v2
	v_add_f32_e32 v2, v18, v2
	v_mov_b32_e32 v3, v2
	s_nop 1
	v_permlane16_swap_b32_e32 v2, v3
	v_pk_mul_f32 v[12:13], v[64:65], v[8:9]
	v_pk_mul_f32 v[14:15], v[60:61], v[4:5]
	s_mov_b32 s2, 0x58000
	v_add_f32_e32 v2, v2, v3
	v_cvt_pk_bf16_f32 v10, v10, v11
	v_cvt_pk_bf16_f32 v11, v12, v13
	v_cvt_pk_bf16_f32 v12, v16, v17
	v_cvt_pk_bf16_f32 v13, v14, v15
	v_add_co_u32_e32 v14, vcc, s2, v174
	v_mov_b32_e32 v3, v2
	s_nop 0
	v_addc_co_u32_e32 v15, vcc, 0, v175, vcc
	v_permlane32_swap_b32_e32 v2, v3
	global_store_dwordx4 v[14:15], v[10:13], off offset:256
	s_and_saveexec_b64 s[2:3], s[44:45]
	v_lshl_add_u32 v4, v173, 2, s67
	v_add_f32_e32 v2, v2, v3
	ds_write_b32 v4, v2 offset:704
	s_or_b64 exec, exec, s[2:3]

.LBB0_686:
	s_mov_b32 s28, s17
	s_mov_b32 s29, s36
	s_mov_b32 s30, s37
	s_mov_b32 s31, s38
	v_lshlrev_b32_e32 v2, 2, v66
	global_load_dword v3, v2, s[28:29]
	global_load_dword v4, v2, s[28:29] offset:256
	global_load_dword v5, v2, s[6:7]
	global_load_dword v6, v2, s[6:7] offset:256
	global_load_dword v7, v2, s[30:31]
	global_load_dword v8, v2, s[30:31] offset:256
	s_mov_b32 s2, 0xfff46000
	s_mov_b32 s3, -1
	v_lshl_add_u64 v[36:37], v[34:35], 0, s[2:3]
	s_mov_b32 s26, 0x6000
	s_mov_b32 s27, 0
	global_load_dwordx2 v[68:69], v[36:37], off
	v_lshl_add_u64 v[36:37], v[36:37], 0, s[26:27]
	global_load_dwordx2 v[70:71], v[36:37], off
	v_lshl_add_u64 v[36:37], v[36:37], 0, s[26:27]
	global_load_dwordx2 v[72:73], v[36:37], off
	v_lshl_add_u64 v[36:37], v[36:37], 0, s[26:27]
	global_load_dwordx2 v[74:75], v[36:37], off
	v_lshl_add_u64 v[36:37], v[36:37], 0, s[26:27]
	global_load_dwordx2 v[76:77], v[36:37], off
	v_lshl_add_u64 v[36:37], v[36:37], 0, s[26:27]
	global_load_dwordx2 v[78:79], v[36:37], off
	v_lshl_add_u64 v[36:37], v[36:37], 0, s[26:27]
	global_load_dwordx2 v[80:81], v[36:37], off
	v_lshl_add_u64 v[36:37], v[36:37], 0, s[26:27]
	global_load_dwordx2 v[82:83], v[36:37], off
	v_lshl_add_u64 v[36:37], v[36:37], 0, s[26:27]
	global_load_dwordx2 v[84:85], v[36:37], off
	v_lshl_add_u64 v[36:37], v[36:37], 0, s[26:27]
	global_load_dwordx2 v[86:87], v[36:37], off
	v_lshl_add_u64 v[36:37], v[36:37], 0, s[26:27]
	global_load_dwordx2 v[88:89], v[36:37], off
	v_lshl_add_u64 v[36:37], v[36:37], 0, s[26:27]
	global_load_dwordx2 v[90:91], v[36:37], off
	v_lshl_add_u64 v[36:37], v[36:37], 0, s[26:27]
	global_load_dwordx2 v[92:93], v[36:37], off
	v_lshl_add_u64 v[36:37], v[36:37], 0, s[26:27]
	global_load_dwordx2 v[94:95], v[36:37], off
	v_lshl_add_u64 v[36:37], v[36:37], 0, s[26:27]
	global_load_dwordx2 v[96:97], v[36:37], off
	v_lshl_add_u64 v[36:37], v[36:37], 0, s[26:27]
	global_load_dwordx2 v[98:99], v[36:37], off
	v_lshl_add_u64 v[36:37], v[36:37], 0, s[26:27]
	global_load_dwordx2 v[100:101], v[36:37], off
	v_lshl_add_u64 v[36:37], v[36:37], 0, s[26:27]
	global_load_dwordx2 v[102:103], v[36:37], off
	v_lshl_add_u64 v[36:37], v[36:37], 0, s[26:27]
	global_load_dwordx2 v[104:105], v[36:37], off
	v_lshl_add_u64 v[36:37], v[36:37], 0, s[26:27]
	global_load_dwordx2 v[106:107], v[36:37], off
	v_lshl_add_u64 v[36:37], v[36:37], 0, s[26:27]
	global_load_dwordx2 v[108:109], v[36:37], off
	v_lshl_add_u64 v[36:37], v[36:37], 0, s[26:27]
	global_load_dwordx2 v[110:111], v[36:37], off
	v_lshl_add_u64 v[36:37], v[36:37], 0, s[26:27]
	global_load_dwordx2 v[112:113], v[36:37], off
	v_lshl_add_u64 v[36:37], v[36:37], 0, s[26:27]
	global_load_dwordx2 v[114:115], v[36:37], off
	v_lshl_add_u64 v[36:37], v[36:37], 0, s[26:27]
	global_load_dwordx2 v[116:117], v[36:37], off
	v_lshl_add_u64 v[36:37], v[36:37], 0, s[26:27]
	global_load_dwordx2 v[118:119], v[36:37], off
	v_lshl_add_u64 v[36:37], v[36:37], 0, s[26:27]
	global_load_dwordx2 v[120:121], v[36:37], off
	v_lshl_add_u64 v[36:37], v[36:37], 0, s[26:27]
	global_load_dwordx2 v[122:123], v[36:37], off
	v_lshl_add_u64 v[36:37], v[36:37], 0, s[26:27]
	global_load_dwordx2 v[124:125], v[36:37], off
	v_lshl_add_u64 v[36:37], v[36:37], 0, s[26:27]
	global_load_dwordx2 v[126:127], v[36:37], off
	v_lshl_add_u64 v[36:37], v[36:37], 0, s[26:27]
	global_load_dwordx2 v[128:129], v[36:37], off
	v_lshl_add_u64 v[36:37], v[36:37], 0, s[26:27]
	global_load_dwordx2 v[130:131], v[36:37], off
	v_lshl_add_u64 v[36:37], v[36:37], 0, s[26:27]
	s_waitcnt vmcnt(32)
	v_mul_f32_e32 v9, 0xbfb8aa3b, v3
	v_mul_f32_e32 v10, 0xbfb8aa3b, v4
	v_mul_f32_e32 v11, 0xbfb8aa3b, v5
	v_mul_f32_e32 v12, 0xbfb8aa3b, v6
	v_mul_f32_e32 v13, 0xbfb8aa3b, v7
	v_mul_f32_e32 v14, 0xbfb8aa3b, v8
	v_exp_f32_e32 v9, v9
	v_exp_f32_e32 v10, v10
	v_exp_f32_e32 v11, v11
	v_exp_f32_e32 v12, v12
	v_exp_f32_e32 v13, v13
	v_exp_f32_e32 v14, v14
	v_add_f32_e32 v9, 1.0, v9
	v_add_f32_e32 v10, 1.0, v10
	v_add_f32_e32 v11, 1.0, v11
	v_add_f32_e32 v12, 1.0, v12
	v_add_f32_e32 v13, 1.0, v13
	v_add_f32_e32 v14, 1.0, v14
	v_div_scale_f32 v15, s[2:3], v9, v9, v3
	v_div_scale_f32 v16, s[2:3], v10, v10, v4
	v_div_scale_f32 v17, s[2:3], v11, v11, v5
	v_div_scale_f32 v24, s[2:3], v12, v12, v6
	v_div_scale_f32 v25, s[2:3], v13, v13, v7
	v_div_scale_f32 v26, s[2:3], v14, v14, v8
	v_rcp_f32_e32 v27, v15
	v_rcp_f32_e32 v28, v16
	v_rcp_f32_e32 v29, v17
	v_rcp_f32_e32 v38, v24
	v_rcp_f32_e32 v39, v25
	v_rcp_f32_e32 v40, v26
	v_fma_f32 v41, -v15, v27, 1.0
	v_fma_f32 v42, -v16, v28, 1.0
	v_fma_f32 v43, -v17, v29, 1.0
	v_fma_f32 v48, -v24, v38, 1.0
	v_fma_f32 v49, -v25, v39, 1.0
	v_fma_f32 v50, -v26, v40, 1.0
	v_div_scale_f32 v51, s[42:43], v3, v9, v3
	v_div_scale_f32 v52, s[44:45], v4, v10, v4
	v_div_scale_f32 v53, s[46:47], v5, v11, v5
	v_div_scale_f32 v54, s[48:49], v6, v12, v6
	v_div_scale_f32 v55, s[50:51], v7, v13, v7
	v_div_scale_f32 v56, s[52:53], v8, v14, v8
	v_fmac_f32_e32 v27, v41, v27
	v_fmac_f32_e32 v28, v42, v28
	v_fmac_f32_e32 v29, v43, v29
	v_fmac_f32_e32 v38, v48, v38
	v_fmac_f32_e32 v39, v49, v39
	v_fmac_f32_e32 v40, v50, v40
	v_mul_f32_e32 v57, v51, v27
	v_mul_f32_e32 v58, v52, v28
	v_mul_f32_e32 v59, v53, v29
	v_mul_f32_e32 v60, v54, v38
	v_mul_f32_e32 v61, v55, v39
	v_mul_f32_e32 v62, v56, v40
	v_fma_f32 v41, -v15, v57, v51
	v_fma_f32 v42, -v16, v58, v52
	v_fma_f32 v43, -v17, v59, v53
	v_fma_f32 v48, -v24, v60, v54
	v_fma_f32 v49, -v25, v61, v55
	v_fma_f32 v50, -v26, v62, v56
	v_fmac_f32_e32 v57, v41, v27
	v_fmac_f32_e32 v58, v42, v28
	v_fmac_f32_e32 v59, v43, v29
	v_fmac_f32_e32 v60, v48, v38
	v_fmac_f32_e32 v61, v49, v39
	v_fmac_f32_e32 v62, v50, v40
	v_fma_f32 v41, -v15, v57, v51
	v_fma_f32 v42, -v16, v58, v52
	v_fma_f32 v43, -v17, v59, v53
	v_fma_f32 v48, -v24, v60, v54
	v_fma_f32 v49, -v25, v61, v55
	v_fma_f32 v50, -v26, v62, v56
	s_mov_b64 vcc, s[42:43]
	v_div_fmas_f32 v63, v41, v27, v57
	s_mov_b64 vcc, s[44:45]
	v_div_fmas_f32 v64, v42, v28, v58
	s_mov_b64 vcc, s[46:47]
	v_div_fmas_f32 v65, v43, v29, v59
	s_mov_b64 vcc, s[48:49]
	v_div_fmas_f32 v132, v48, v38, v60
	s_mov_b64 vcc, s[50:51]
	v_div_fmas_f32 v133, v49, v39, v61
	s_mov_b64 vcc, s[52:53]
	v_div_fmas_f32 v134, v50, v40, v62
	v_div_fixup_f32 v3, v63, v9, v3
	v_div_fixup_f32 v4, v64, v10, v4
	v_div_fixup_f32 v5, v65, v11, v5
	v_div_fixup_f32 v6, v132, v12, v6
	v_div_fixup_f32 v7, v133, v13, v7
	v_div_fixup_f32 v8, v134, v14, v8
	s_nop 1
	v_readlane_b32 s42, v3, 0
	v_readlane_b32 s44, v5, 0
	v_readlane_b32 s46, v7, 0
	v_readlane_b32 s48, v3, 1
	v_readlane_b32 s50, v5, 1
	v_readlane_b32 s52, v7, 1
	s_waitcnt vmcnt(31)
	v_pk_fma_f32 v[22:23], v[68:69], s[42:43], v[22:23] op_sel_hi:[1,0,1]
	v_pk_fma_f32 v[18:19], v[68:69], s[44:45], v[18:19] op_sel_hi:[1,0,1]
	v_pk_fma_f32 v[20:21], v[68:69], s[46:47], v[20:21] op_sel_hi:[1,0,1]
	global_load_dwordx2 v[68:69], v[36:37], off
	v_lshl_add_u64 v[36:37], v[36:37], 0, s[26:27]
	v_readlane_b32 s42, v3, 2
	v_readlane_b32 s44, v5, 2
	v_readlane_b32 s46, v7, 2
	s_waitcnt vmcnt(31)
	v_pk_fma_f32 v[22:23], v[70:71], s[48:49], v[22:23] op_sel_hi:[1,0,1]
	v_pk_fma_f32 v[18:19], v[70:71], s[50:51], v[18:19] op_sel_hi:[1,0,1]
	v_pk_fma_f32 v[20:21], v[70:71], s[52:53], v[20:21] op_sel_hi:[1,0,1]
	global_load_dwordx2 v[70:71], v[36:37], off
	v_lshl_add_u64 v[36:37], v[36:37], 0, s[26:27]
	v_readlane_b32 s48, v3, 3
	v_readlane_b32 s50, v5, 3
	v_readlane_b32 s52, v7, 3
	s_waitcnt vmcnt(31)
	v_pk_fma_f32 v[22:23], v[72:73], s[42:43], v[22:23] op_sel_hi:[1,0,1]
	v_pk_fma_f32 v[18:19], v[72:73], s[44:45], v[18:19] op_sel_hi:[1,0,1]
	v_pk_fma_f32 v[20:21], v[72:73], s[46:47], v[20:21] op_sel_hi:[1,0,1]
	global_load_dwordx2 v[72:73], v[36:37], off
	v_lshl_add_u64 v[36:37], v[36:37], 0, s[26:27]
	v_readlane_b32 s42, v3, 4
	v_readlane_b32 s44, v5, 4
	v_readlane_b32 s46, v7, 4
	s_waitcnt vmcnt(31)
	v_pk_fma_f32 v[22:23], v[74:75], s[48:49], v[22:23] op_sel_hi:[1,0,1]
	v_pk_fma_f32 v[18:19], v[74:75], s[50:51], v[18:19] op_sel_hi:[1,0,1]
	v_pk_fma_f32 v[20:21], v[74:75], s[52:53], v[20:21] op_sel_hi:[1,0,1]
	global_load_dwordx2 v[74:75], v[36:37], off
	v_lshl_add_u64 v[36:37], v[36:37], 0, s[26:27]
	v_readlane_b32 s48, v3, 5
	v_readlane_b32 s50, v5, 5
	v_readlane_b32 s52, v7, 5
	s_waitcnt vmcnt(31)
	v_pk_fma_f32 v[22:23], v[76:77], s[42:43], v[22:23] op_sel_hi:[1,0,1]
	v_pk_fma_f32 v[18:19], v[76:77], s[44:45], v[18:19] op_sel_hi:[1,0,1]
	v_pk_fma_f32 v[20:21], v[76:77], s[46:47], v[20:21] op_sel_hi:[1,0,1]
	global_load_dwordx2 v[76:77], v[36:37], off
	v_lshl_add_u64 v[36:37], v[36:37], 0, s[26:27]
	v_readlane_b32 s42, v3, 6
	v_readlane_b32 s44, v5, 6
	v_readlane_b32 s46, v7, 6
	s_waitcnt vmcnt(31)
	v_pk_fma_f32 v[22:23], v[78:79], s[48:49], v[22:23] op_sel_hi:[1,0,1]
	v_pk_fma_f32 v[18:19], v[78:79], s[50:51], v[18:19] op_sel_hi:[1,0,1]
	v_pk_fma_f32 v[20:21], v[78:79], s[52:53], v[20:21] op_sel_hi:[1,0,1]
	global_load_dwordx2 v[78:79], v[36:37], off
	v_lshl_add_u64 v[36:37], v[36:37], 0, s[26:27]
	v_readlane_b32 s48, v3, 7
	v_readlane_b32 s50, v5, 7
	v_readlane_b32 s52, v7, 7
	s_waitcnt vmcnt(31)
	v_pk_fma_f32 v[22:23], v[80:81], s[42:43], v[22:23] op_sel_hi:[1,0,1]
	v_pk_fma_f32 v[18:19], v[80:81], s[44:45], v[18:19] op_sel_hi:[1,0,1]
	v_pk_fma_f32 v[20:21], v[80:81], s[46:47], v[20:21] op_sel_hi:[1,0,1]
	global_load_dwordx2 v[80:81], v[36:37], off
	v_lshl_add_u64 v[36:37], v[36:37], 0, s[26:27]
	v_readlane_b32 s42, v3, 8
	v_readlane_b32 s44, v5, 8
	v_readlane_b32 s46, v7, 8
	s_waitcnt vmcnt(31)
	v_pk_fma_f32 v[22:23], v[82:83], s[48:49], v[22:23] op_sel_hi:[1,0,1]
	v_pk_fma_f32 v[18:19], v[82:83], s[50:51], v[18:19] op_sel_hi:[1,0,1]
	v_pk_fma_f32 v[20:21], v[82:83], s[52:53], v[20:21] op_sel_hi:[1,0,1]
	global_load_dwordx2 v[82:83], v[36:37], off
	v_lshl_add_u64 v[36:37], v[36:37], 0, s[26:27]
	v_readlane_b32 s48, v3, 9
	v_readlane_b32 s50, v5, 9
	v_readlane_b32 s52, v7, 9
	s_waitcnt vmcnt(31)
	v_pk_fma_f32 v[22:23], v[84:85], s[42:43], v[22:23] op_sel_hi:[1,0,1]
	v_pk_fma_f32 v[18:19], v[84:85], s[44:45], v[18:19] op_sel_hi:[1,0,1]
	v_pk_fma_f32 v[20:21], v[84:85], s[46:47], v[20:21] op_sel_hi:[1,0,1]
	global_load_dwordx2 v[84:85], v[36:37], off
	v_lshl_add_u64 v[36:37], v[36:37], 0, s[26:27]
	v_readlane_b32 s42, v3, 10
	v_readlane_b32 s44, v5, 10
	v_readlane_b32 s46, v7, 10
	s_waitcnt vmcnt(31)
	v_pk_fma_f32 v[22:23], v[86:87], s[48:49], v[22:23] op_sel_hi:[1,0,1]
	v_pk_fma_f32 v[18:19], v[86:87], s[50:51], v[18:19] op_sel_hi:[1,0,1]
	v_pk_fma_f32 v[20:21], v[86:87], s[52:53], v[20:21] op_sel_hi:[1,0,1]
	global_load_dwordx2 v[86:87], v[36:37], off
	v_lshl_add_u64 v[36:37], v[36:37], 0, s[26:27]
	v_readlane_b32 s48, v3, 11
	v_readlane_b32 s50, v5, 11
	v_readlane_b32 s52, v7, 11
	s_waitcnt vmcnt(31)
	v_pk_fma_f32 v[22:23], v[88:89], s[42:43], v[22:23] op_sel_hi:[1,0,1]
	v_pk_fma_f32 v[18:19], v[88:89], s[44:45], v[18:19] op_sel_hi:[1,0,1]
	v_pk_fma_f32 v[20:21], v[88:89], s[46:47], v[20:21] op_sel_hi:[1,0,1]
	global_load_dwordx2 v[88:89], v[36:37], off
	v_lshl_add_u64 v[36:37], v[36:37], 0, s[26:27]
	v_readlane_b32 s42, v3, 12
	v_readlane_b32 s44, v5, 12
	v_readlane_b32 s46, v7, 12
	s_waitcnt vmcnt(31)
	v_pk_fma_f32 v[22:23], v[90:91], s[48:49], v[22:23] op_sel_hi:[1,0,1]
	v_pk_fma_f32 v[18:19], v[90:91], s[50:51], v[18:19] op_sel_hi:[1,0,1]
	v_pk_fma_f32 v[20:21], v[90:91], s[52:53], v[20:21] op_sel_hi:[1,0,1]
	global_load_dwordx2 v[90:91], v[36:37], off
	v_lshl_add_u64 v[36:37], v[36:37], 0, s[26:27]
	v_readlane_b32 s48, v3, 13
	v_readlane_b32 s50, v5, 13
	v_readlane_b32 s52, v7, 13
	s_waitcnt vmcnt(31)
	v_pk_fma_f32 v[22:23], v[92:93], s[42:43], v[22:23] op_sel_hi:[1,0,1]
	v_pk_fma_f32 v[18:19], v[92:93], s[44:45], v[18:19] op_sel_hi:[1,0,1]
	v_pk_fma_f32 v[20:21], v[92:93], s[46:47], v[20:21] op_sel_hi:[1,0,1]
	global_load_dwordx2 v[92:93], v[36:37], off
	v_lshl_add_u64 v[36:37], v[36:37], 0, s[26:27]
	v_readlane_b32 s42, v3, 14
	v_readlane_b32 s44, v5, 14
	v_readlane_b32 s46, v7, 14
	s_waitcnt vmcnt(31)
	v_pk_fma_f32 v[22:23], v[94:95], s[48:49], v[22:23] op_sel_hi:[1,0,1]
	v_pk_fma_f32 v[18:19], v[94:95], s[50:51], v[18:19] op_sel_hi:[1,0,1]
	v_pk_fma_f32 v[20:21], v[94:95], s[52:53], v[20:21] op_sel_hi:[1,0,1]
	global_load_dwordx2 v[94:95], v[36:37], off
	v_lshl_add_u64 v[36:37], v[36:37], 0, s[26:27]
	v_readlane_b32 s48, v3, 15
	v_readlane_b32 s50, v5, 15
	v_readlane_b32 s52, v7, 15
	s_waitcnt vmcnt(31)
	v_pk_fma_f32 v[22:23], v[96:97], s[42:43], v[22:23] op_sel_hi:[1,0,1]
	v_pk_fma_f32 v[18:19], v[96:97], s[44:45], v[18:19] op_sel_hi:[1,0,1]
	v_pk_fma_f32 v[20:21], v[96:97], s[46:47], v[20:21] op_sel_hi:[1,0,1]
	global_load_dwordx2 v[96:97], v[36:37], off
	v_lshl_add_u64 v[36:37], v[36:37], 0, s[26:27]
	v_readlane_b32 s42, v3, 16
	v_readlane_b32 s44, v5, 16
	v_readlane_b32 s46, v7, 16
	s_waitcnt vmcnt(31)
	v_pk_fma_f32 v[22:23], v[98:99], s[48:49], v[22:23] op_sel_hi:[1,0,1]
	v_pk_fma_f32 v[18:19], v[98:99], s[50:51], v[18:19] op_sel_hi:[1,0,1]
	v_pk_fma_f32 v[20:21], v[98:99], s[52:53], v[20:21] op_sel_hi:[1,0,1]
	global_load_dwordx2 v[98:99], v[36:37], off
	v_lshl_add_u64 v[36:37], v[36:37], 0, s[26:27]
	v_readlane_b32 s48, v3, 17
	v_readlane_b32 s50, v5, 17
	v_readlane_b32 s52, v7, 17
	s_waitcnt vmcnt(31)
	v_pk_fma_f32 v[22:23], v[100:101], s[42:43], v[22:23] op_sel_hi:[1,0,1]
	v_pk_fma_f32 v[18:19], v[100:101], s[44:45], v[18:19] op_sel_hi:[1,0,1]
	v_pk_fma_f32 v[20:21], v[100:101], s[46:47], v[20:21] op_sel_hi:[1,0,1]
	global_load_dwordx2 v[100:101], v[36:37], off
	v_lshl_add_u64 v[36:37], v[36:37], 0, s[26:27]
	v_readlane_b32 s42, v3, 18
	v_readlane_b32 s44, v5, 18
	v_readlane_b32 s46, v7, 18
	s_waitcnt vmcnt(31)
	v_pk_fma_f32 v[22:23], v[102:103], s[48:49], v[22:23] op_sel_hi:[1,0,1]
	v_pk_fma_f32 v[18:19], v[102:103], s[50:51], v[18:19] op_sel_hi:[1,0,1]
	v_pk_fma_f32 v[20:21], v[102:103], s[52:53], v[20:21] op_sel_hi:[1,0,1]
	global_load_dwordx2 v[102:103], v[36:37], off
	v_lshl_add_u64 v[36:37], v[36:37], 0, s[26:27]
	v_readlane_b32 s48, v3, 19
	v_readlane_b32 s50, v5, 19
	v_readlane_b32 s52, v7, 19
	s_waitcnt vmcnt(31)
	v_pk_fma_f32 v[22:23], v[104:105], s[42:43], v[22:23] op_sel_hi:[1,0,1]
	v_pk_fma_f32 v[18:19], v[104:105], s[44:45], v[18:19] op_sel_hi:[1,0,1]
	v_pk_fma_f32 v[20:21], v[104:105], s[46:47], v[20:21] op_sel_hi:[1,0,1]
	global_load_dwordx2 v[104:105], v[36:37], off
	v_lshl_add_u64 v[36:37], v[36:37], 0, s[26:27]
	v_readlane_b32 s42, v3, 20
	v_readlane_b32 s44, v5, 20
	v_readlane_b32 s46, v7, 20
	s_waitcnt vmcnt(31)
	v_pk_fma_f32 v[22:23], v[106:107], s[48:49], v[22:23] op_sel_hi:[1,0,1]
	v_pk_fma_f32 v[18:19], v[106:107], s[50:51], v[18:19] op_sel_hi:[1,0,1]
	v_pk_fma_f32 v[20:21], v[106:107], s[52:53], v[20:21] op_sel_hi:[1,0,1]
	global_load_dwordx2 v[106:107], v[36:37], off
	v_lshl_add_u64 v[36:37], v[36:37], 0, s[26:27]
	v_readlane_b32 s48, v3, 21
	v_readlane_b32 s50, v5, 21
	v_readlane_b32 s52, v7, 21
	s_waitcnt vmcnt(31)
	v_pk_fma_f32 v[22:23], v[108:109], s[42:43], v[22:23] op_sel_hi:[1,0,1]
	v_pk_fma_f32 v[18:19], v[108:109], s[44:45], v[18:19] op_sel_hi:[1,0,1]
	v_pk_fma_f32 v[20:21], v[108:109], s[46:47], v[20:21] op_sel_hi:[1,0,1]
	global_load_dwordx2 v[108:109], v[36:37], off
	v_lshl_add_u64 v[36:37], v[36:37], 0, s[26:27]
	v_readlane_b32 s42, v3, 22
	v_readlane_b32 s44, v5, 22
	v_readlane_b32 s46, v7, 22
	s_waitcnt vmcnt(31)
	v_pk_fma_f32 v[22:23], v[110:111], s[48:49], v[22:23] op_sel_hi:[1,0,1]
	v_pk_fma_f32 v[18:19], v[110:111], s[50:51], v[18:19] op_sel_hi:[1,0,1]
	v_pk_fma_f32 v[20:21], v[110:111], s[52:53], v[20:21] op_sel_hi:[1,0,1]
	global_load_dwordx2 v[110:111], v[36:37], off
	v_lshl_add_u64 v[36:37], v[36:37], 0, s[26:27]
	v_readlane_b32 s48, v3, 23
	v_readlane_b32 s50, v5, 23
	v_readlane_b32 s52, v7, 23
	s_waitcnt vmcnt(31)
	v_pk_fma_f32 v[22:23], v[112:113], s[42:43], v[22:23] op_sel_hi:[1,0,1]
	v_pk_fma_f32 v[18:19], v[112:113], s[44:45], v[18:19] op_sel_hi:[1,0,1]
	v_pk_fma_f32 v[20:21], v[112:113], s[46:47], v[20:21] op_sel_hi:[1,0,1]
	global_load_dwordx2 v[112:113], v[36:37], off
	v_lshl_add_u64 v[36:37], v[36:37], 0, s[26:27]
	v_readlane_b32 s42, v3, 24
	v_readlane_b32 s44, v5, 24
	v_readlane_b32 s46, v7, 24
	s_waitcnt vmcnt(31)
	v_pk_fma_f32 v[22:23], v[114:115], s[48:49], v[22:23] op_sel_hi:[1,0,1]
	v_pk_fma_f32 v[18:19], v[114:115], s[50:51], v[18:19] op_sel_hi:[1,0,1]
	v_pk_fma_f32 v[20:21], v[114:115], s[52:53], v[20:21] op_sel_hi:[1,0,1]
	global_load_dwordx2 v[114:115], v[36:37], off
	v_lshl_add_u64 v[36:37], v[36:37], 0, s[26:27]
	v_readlane_b32 s48, v3, 25
	v_readlane_b32 s50, v5, 25
	v_readlane_b32 s52, v7, 25
	s_waitcnt vmcnt(31)
	v_pk_fma_f32 v[22:23], v[116:117], s[42:43], v[22:23] op_sel_hi:[1,0,1]
	v_pk_fma_f32 v[18:19], v[116:117], s[44:45], v[18:19] op_sel_hi:[1,0,1]
	v_pk_fma_f32 v[20:21], v[116:117], s[46:47], v[20:21] op_sel_hi:[1,0,1]
	global_load_dwordx2 v[116:117], v[36:37], off
	v_lshl_add_u64 v[36:37], v[36:37], 0, s[26:27]
	v_readlane_b32 s42, v3, 26
	v_readlane_b32 s44, v5, 26
	v_readlane_b32 s46, v7, 26
	s_waitcnt vmcnt(31)
	v_pk_fma_f32 v[22:23], v[118:119], s[48:49], v[22:23] op_sel_hi:[1,0,1]
	v_pk_fma_f32 v[18:19], v[118:119], s[50:51], v[18:19] op_sel_hi:[1,0,1]
	v_pk_fma_f32 v[20:21], v[118:119], s[52:53], v[20:21] op_sel_hi:[1,0,1]
	global_load_dwordx2 v[118:119], v[36:37], off
	v_lshl_add_u64 v[36:37], v[36:37], 0, s[26:27]
	v_readlane_b32 s48, v3, 27
	v_readlane_b32 s50, v5, 27
	v_readlane_b32 s52, v7, 27
	s_waitcnt vmcnt(31)
	v_pk_fma_f32 v[22:23], v[120:121], s[42:43], v[22:23] op_sel_hi:[1,0,1]
	v_pk_fma_f32 v[18:19], v[120:121], s[44:45], v[18:19] op_sel_hi:[1,0,1]
	v_pk_fma_f32 v[20:21], v[120:121], s[46:47], v[20:21] op_sel_hi:[1,0,1]
	global_load_dwordx2 v[120:121], v[36:37], off
	v_lshl_add_u64 v[36:37], v[36:37], 0, s[26:27]
	v_readlane_b32 s42, v3, 28
	v_readlane_b32 s44, v5, 28
	v_readlane_b32 s46, v7, 28
	s_waitcnt vmcnt(31)
	v_pk_fma_f32 v[22:23], v[122:123], s[48:49], v[22:23] op_sel_hi:[1,0,1]
	v_pk_fma_f32 v[18:19], v[122:123], s[50:51], v[18:19] op_sel_hi:[1,0,1]
	v_pk_fma_f32 v[20:21], v[122:123], s[52:53], v[20:21] op_sel_hi:[1,0,1]
	global_load_dwordx2 v[122:123], v[36:37], off
	v_lshl_add_u64 v[36:37], v[36:37], 0, s[26:27]
	v_readlane_b32 s48, v3, 29
	v_readlane_b32 s50, v5, 29
	v_readlane_b32 s52, v7, 29
	s_waitcnt vmcnt(31)
	v_pk_fma_f32 v[22:23], v[124:125], s[42:43], v[22:23] op_sel_hi:[1,0,1]
	v_pk_fma_f32 v[18:19], v[124:125], s[44:45], v[18:19] op_sel_hi:[1,0,1]
	v_pk_fma_f32 v[20:21], v[124:125], s[46:47], v[20:21] op_sel_hi:[1,0,1]
	global_load_dwordx2 v[124:125], v[36:37], off
	v_lshl_add_u64 v[36:37], v[36:37], 0, s[26:27]
	v_readlane_b32 s42, v3, 30
	v_readlane_b32 s44, v5, 30
	v_readlane_b32 s46, v7, 30
	s_waitcnt vmcnt(31)
	v_pk_fma_f32 v[22:23], v[126:127], s[48:49], v[22:23] op_sel_hi:[1,0,1]
	v_pk_fma_f32 v[18:19], v[126:127], s[50:51], v[18:19] op_sel_hi:[1,0,1]
	v_pk_fma_f32 v[20:21], v[126:127], s[52:53], v[20:21] op_sel_hi:[1,0,1]
	global_load_dwordx2 v[126:127], v[36:37], off
	v_lshl_add_u64 v[36:37], v[36:37], 0, s[26:27]
	v_readlane_b32 s48, v3, 31
	v_readlane_b32 s50, v5, 31
	v_readlane_b32 s52, v7, 31
	s_waitcnt vmcnt(31)
	v_pk_fma_f32 v[22:23], v[128:129], s[42:43], v[22:23] op_sel_hi:[1,0,1]
	v_pk_fma_f32 v[18:19], v[128:129], s[44:45], v[18:19] op_sel_hi:[1,0,1]
	v_pk_fma_f32 v[20:21], v[128:129], s[46:47], v[20:21] op_sel_hi:[1,0,1]
	global_load_dwordx2 v[128:129], v[36:37], off
	v_lshl_add_u64 v[36:37], v[36:37], 0, s[26:27]
	v_readlane_b32 s42, v3, 32
	v_readlane_b32 s44, v5, 32
	v_readlane_b32 s46, v7, 32
	s_waitcnt vmcnt(31)
	v_pk_fma_f32 v[22:23], v[130:131], s[48:49], v[22:23] op_sel_hi:[1,0,1]
	v_pk_fma_f32 v[18:19], v[130:131], s[50:51], v[18:19] op_sel_hi:[1,0,1]
	v_pk_fma_f32 v[20:21], v[130:131], s[52:53], v[20:21] op_sel_hi:[1,0,1]
	global_load_dwordx2 v[130:131], v[36:37], off
	v_lshl_add_u64 v[36:37], v[36:37], 0, s[26:27]
	v_readlane_b32 s48, v3, 33
	v_readlane_b32 s50, v5, 33
	v_readlane_b32 s52, v7, 33
	s_waitcnt vmcnt(31)
	v_pk_fma_f32 v[22:23], v[68:69], s[42:43], v[22:23] op_sel_hi:[1,0,1]
	v_pk_fma_f32 v[18:19], v[68:69], s[44:45], v[18:19] op_sel_hi:[1,0,1]
	v_pk_fma_f32 v[20:21], v[68:69], s[46:47], v[20:21] op_sel_hi:[1,0,1]
	global_load_dwordx2 v[68:69], v[36:37], off
	v_lshl_add_u64 v[36:37], v[36:37], 0, s[26:27]
	v_readlane_b32 s42, v3, 34
	v_readlane_b32 s44, v5, 34
	v_readlane_b32 s46, v7, 34
	s_waitcnt vmcnt(31)
	v_pk_fma_f32 v[22:23], v[70:71], s[48:49], v[22:23] op_sel_hi:[1,0,1]
	v_pk_fma_f32 v[18:19], v[70:71], s[50:51], v[18:19] op_sel_hi:[1,0,1]
	v_pk_fma_f32 v[20:21], v[70:71], s[52:53], v[20:21] op_sel_hi:[1,0,1]
	global_load_dwordx2 v[70:71], v[36:37], off
	v_lshl_add_u64 v[36:37], v[36:37], 0, s[26:27]
	v_readlane_b32 s48, v3, 35
	v_readlane_b32 s50, v5, 35
	v_readlane_b32 s52, v7, 35
	s_waitcnt vmcnt(31)
	v_pk_fma_f32 v[22:23], v[72:73], s[42:43], v[22:23] op_sel_hi:[1,0,1]
	v_pk_fma_f32 v[18:19], v[72:73], s[44:45], v[18:19] op_sel_hi:[1,0,1]
	v_pk_fma_f32 v[20:21], v[72:73], s[46:47], v[20:21] op_sel_hi:[1,0,1]
	global_load_dwordx2 v[72:73], v[36:37], off
	v_lshl_add_u64 v[36:37], v[36:37], 0, s[26:27]
	v_readlane_b32 s42, v3, 36
	v_readlane_b32 s44, v5, 36
	v_readlane_b32 s46, v7, 36
	s_waitcnt vmcnt(31)
	v_pk_fma_f32 v[22:23], v[74:75], s[48:49], v[22:23] op_sel_hi:[1,0,1]
	v_pk_fma_f32 v[18:19], v[74:75], s[50:51], v[18:19] op_sel_hi:[1,0,1]
	v_pk_fma_f32 v[20:21], v[74:75], s[52:53], v[20:21] op_sel_hi:[1,0,1]
	global_load_dwordx2 v[74:75], v[36:37], off
	v_lshl_add_u64 v[36:37], v[36:37], 0, s[26:27]
	v_readlane_b32 s48, v3, 37
	v_readlane_b32 s50, v5, 37
	v_readlane_b32 s52, v7, 37
	s_waitcnt vmcnt(31)
	v_pk_fma_f32 v[22:23], v[76:77], s[42:43], v[22:23] op_sel_hi:[1,0,1]
	v_pk_fma_f32 v[18:19], v[76:77], s[44:45], v[18:19] op_sel_hi:[1,0,1]
	v_pk_fma_f32 v[20:21], v[76:77], s[46:47], v[20:21] op_sel_hi:[1,0,1]
	global_load_dwordx2 v[76:77], v[36:37], off
	v_lshl_add_u64 v[36:37], v[36:37], 0, s[26:27]
	v_readlane_b32 s42, v3, 38
	v_readlane_b32 s44, v5, 38
	v_readlane_b32 s46, v7, 38
	s_waitcnt vmcnt(31)
	v_pk_fma_f32 v[22:23], v[78:79], s[48:49], v[22:23] op_sel_hi:[1,0,1]
	v_pk_fma_f32 v[18:19], v[78:79], s[50:51], v[18:19] op_sel_hi:[1,0,1]
	v_pk_fma_f32 v[20:21], v[78:79], s[52:53], v[20:21] op_sel_hi:[1,0,1]
	global_load_dwordx2 v[78:79], v[36:37], off
	v_lshl_add_u64 v[36:37], v[36:37], 0, s[26:27]
	v_readlane_b32 s48, v3, 39
	v_readlane_b32 s50, v5, 39
	v_readlane_b32 s52, v7, 39
	s_waitcnt vmcnt(31)
	v_pk_fma_f32 v[22:23], v[80:81], s[42:43], v[22:23] op_sel_hi:[1,0,1]
	v_pk_fma_f32 v[18:19], v[80:81], s[44:45], v[18:19] op_sel_hi:[1,0,1]
	v_pk_fma_f32 v[20:21], v[80:81], s[46:47], v[20:21] op_sel_hi:[1,0,1]
	global_load_dwordx2 v[80:81], v[36:37], off
	v_lshl_add_u64 v[36:37], v[36:37], 0, s[26:27]
	v_readlane_b32 s42, v3, 40
	v_readlane_b32 s44, v5, 40
	v_readlane_b32 s46, v7, 40
	s_waitcnt vmcnt(31)
	v_pk_fma_f32 v[22:23], v[82:83], s[48:49], v[22:23] op_sel_hi:[1,0,1]
	v_pk_fma_f32 v[18:19], v[82:83], s[50:51], v[18:19] op_sel_hi:[1,0,1]
	v_pk_fma_f32 v[20:21], v[82:83], s[52:53], v[20:21] op_sel_hi:[1,0,1]
	global_load_dwordx2 v[82:83], v[36:37], off
	v_lshl_add_u64 v[36:37], v[36:37], 0, s[26:27]
	v_readlane_b32 s48, v3, 41
	v_readlane_b32 s50, v5, 41
	v_readlane_b32 s52, v7, 41
	s_waitcnt vmcnt(31)
	v_pk_fma_f32 v[22:23], v[84:85], s[42:43], v[22:23] op_sel_hi:[1,0,1]
	v_pk_fma_f32 v[18:19], v[84:85], s[44:45], v[18:19] op_sel_hi:[1,0,1]
	v_pk_fma_f32 v[20:21], v[84:85], s[46:47], v[20:21] op_sel_hi:[1,0,1]
	global_load_dwordx2 v[84:85], v[36:37], off
	v_lshl_add_u64 v[36:37], v[36:37], 0, s[26:27]
	v_readlane_b32 s42, v3, 42
	v_readlane_b32 s44, v5, 42
	v_readlane_b32 s46, v7, 42
	s_waitcnt vmcnt(31)
	v_pk_fma_f32 v[22:23], v[86:87], s[48:49], v[22:23] op_sel_hi:[1,0,1]
	v_pk_fma_f32 v[18:19], v[86:87], s[50:51], v[18:19] op_sel_hi:[1,0,1]
	v_pk_fma_f32 v[20:21], v[86:87], s[52:53], v[20:21] op_sel_hi:[1,0,1]
	global_load_dwordx2 v[86:87], v[36:37], off
	v_lshl_add_u64 v[36:37], v[36:37], 0, s[26:27]
	v_readlane_b32 s48, v3, 43
	v_readlane_b32 s50, v5, 43
	v_readlane_b32 s52, v7, 43
	s_waitcnt vmcnt(31)
	v_pk_fma_f32 v[22:23], v[88:89], s[42:43], v[22:23] op_sel_hi:[1,0,1]
	v_pk_fma_f32 v[18:19], v[88:89], s[44:45], v[18:19] op_sel_hi:[1,0,1]
	v_pk_fma_f32 v[20:21], v[88:89], s[46:47], v[20:21] op_sel_hi:[1,0,1]
	global_load_dwordx2 v[88:89], v[36:37], off
	v_lshl_add_u64 v[36:37], v[36:37], 0, s[26:27]
	v_readlane_b32 s42, v3, 44
	v_readlane_b32 s44, v5, 44
	v_readlane_b32 s46, v7, 44
	s_waitcnt vmcnt(31)
	v_pk_fma_f32 v[22:23], v[90:91], s[48:49], v[22:23] op_sel_hi:[1,0,1]
	v_pk_fma_f32 v[18:19], v[90:91], s[50:51], v[18:19] op_sel_hi:[1,0,1]
	v_pk_fma_f32 v[20:21], v[90:91], s[52:53], v[20:21] op_sel_hi:[1,0,1]
	global_load_dwordx2 v[90:91], v[36:37], off
	v_lshl_add_u64 v[36:37], v[36:37], 0, s[26:27]
	v_readlane_b32 s48, v3, 45
	v_readlane_b32 s50, v5, 45
	v_readlane_b32 s52, v7, 45
	s_waitcnt vmcnt(31)
	v_pk_fma_f32 v[22:23], v[92:93], s[42:43], v[22:23] op_sel_hi:[1,0,1]
	v_pk_fma_f32 v[18:19], v[92:93], s[44:45], v[18:19] op_sel_hi:[1,0,1]
	v_pk_fma_f32 v[20:21], v[92:93], s[46:47], v[20:21] op_sel_hi:[1,0,1]
	global_load_dwordx2 v[92:93], v[36:37], off
	v_lshl_add_u64 v[36:37], v[36:37], 0, s[26:27]
	v_readlane_b32 s42, v3, 46
	v_readlane_b32 s44, v5, 46
	v_readlane_b32 s46, v7, 46
	s_waitcnt vmcnt(31)
	v_pk_fma_f32 v[22:23], v[94:95], s[48:49], v[22:23] op_sel_hi:[1,0,1]
	v_pk_fma_f32 v[18:19], v[94:95], s[50:51], v[18:19] op_sel_hi:[1,0,1]
	v_pk_fma_f32 v[20:21], v[94:95], s[52:53], v[20:21] op_sel_hi:[1,0,1]
	global_load_dwordx2 v[94:95], v[36:37], off
	v_lshl_add_u64 v[36:37], v[36:37], 0, s[26:27]
	v_readlane_b32 s48, v3, 47
	v_readlane_b32 s50, v5, 47
	v_readlane_b32 s52, v7, 47
	s_waitcnt vmcnt(31)
	v_pk_fma_f32 v[22:23], v[96:97], s[42:43], v[22:23] op_sel_hi:[1,0,1]
	v_pk_fma_f32 v[18:19], v[96:97], s[44:45], v[18:19] op_sel_hi:[1,0,1]
	v_pk_fma_f32 v[20:21], v[96:97], s[46:47], v[20:21] op_sel_hi:[1,0,1]
	global_load_dwordx2 v[96:97], v[36:37], off
	v_lshl_add_u64 v[36:37], v[36:37], 0, s[26:27]
	v_readlane_b32 s42, v3, 48
	v_readlane_b32 s44, v5, 48
	v_readlane_b32 s46, v7, 48
	s_waitcnt vmcnt(31)
	v_pk_fma_f32 v[22:23], v[98:99], s[48:49], v[22:23] op_sel_hi:[1,0,1]
	v_pk_fma_f32 v[18:19], v[98:99], s[50:51], v[18:19] op_sel_hi:[1,0,1]
	v_pk_fma_f32 v[20:21], v[98:99], s[52:53], v[20:21] op_sel_hi:[1,0,1]
	global_load_dwordx2 v[98:99], v[36:37], off
	v_lshl_add_u64 v[36:37], v[36:37], 0, s[26:27]
	v_readlane_b32 s48, v3, 49
	v_readlane_b32 s50, v5, 49
	v_readlane_b32 s52, v7, 49
	s_waitcnt vmcnt(31)
	v_pk_fma_f32 v[22:23], v[100:101], s[42:43], v[22:23] op_sel_hi:[1,0,1]
	v_pk_fma_f32 v[18:19], v[100:101], s[44:45], v[18:19] op_sel_hi:[1,0,1]
	v_pk_fma_f32 v[20:21], v[100:101], s[46:47], v[20:21] op_sel_hi:[1,0,1]
	global_load_dwordx2 v[100:101], v[36:37], off
	v_lshl_add_u64 v[36:37], v[36:37], 0, s[26:27]
	v_readlane_b32 s42, v3, 50
	v_readlane_b32 s44, v5, 50
	v_readlane_b32 s46, v7, 50
	s_waitcnt vmcnt(31)
	v_pk_fma_f32 v[22:23], v[102:103], s[48:49], v[22:23] op_sel_hi:[1,0,1]
	v_pk_fma_f32 v[18:19], v[102:103], s[50:51], v[18:19] op_sel_hi:[1,0,1]
	v_pk_fma_f32 v[20:21], v[102:103], s[52:53], v[20:21] op_sel_hi:[1,0,1]
	global_load_dwordx2 v[102:103], v[36:37], off
	v_lshl_add_u64 v[36:37], v[36:37], 0, s[26:27]
	v_readlane_b32 s48, v3, 51
	v_readlane_b32 s50, v5, 51
	v_readlane_b32 s52, v7, 51
	s_waitcnt vmcnt(31)
	v_pk_fma_f32 v[22:23], v[104:105], s[42:43], v[22:23] op_sel_hi:[1,0,1]
	v_pk_fma_f32 v[18:19], v[104:105], s[44:45], v[18:19] op_sel_hi:[1,0,1]
	v_pk_fma_f32 v[20:21], v[104:105], s[46:47], v[20:21] op_sel_hi:[1,0,1]
	global_load_dwordx2 v[104:105], v[36:37], off
	v_lshl_add_u64 v[36:37], v[36:37], 0, s[26:27]
	v_readlane_b32 s42, v3, 52
	v_readlane_b32 s44, v5, 52
	v_readlane_b32 s46, v7, 52
	s_waitcnt vmcnt(31)
	v_pk_fma_f32 v[22:23], v[106:107], s[48:49], v[22:23] op_sel_hi:[1,0,1]
	v_pk_fma_f32 v[18:19], v[106:107], s[50:51], v[18:19] op_sel_hi:[1,0,1]
	v_pk_fma_f32 v[20:21], v[106:107], s[52:53], v[20:21] op_sel_hi:[1,0,1]
	global_load_dwordx2 v[106:107], v[36:37], off
	v_lshl_add_u64 v[36:37], v[36:37], 0, s[26:27]
	v_readlane_b32 s48, v3, 53
	v_readlane_b32 s50, v5, 53
	v_readlane_b32 s52, v7, 53
	s_waitcnt vmcnt(31)
	v_pk_fma_f32 v[22:23], v[108:109], s[42:43], v[22:23] op_sel_hi:[1,0,1]
	v_pk_fma_f32 v[18:19], v[108:109], s[44:45], v[18:19] op_sel_hi:[1,0,1]
	v_pk_fma_f32 v[20:21], v[108:109], s[46:47], v[20:21] op_sel_hi:[1,0,1]
	global_load_dwordx2 v[108:109], v[36:37], off
	v_lshl_add_u64 v[36:37], v[36:37], 0, s[26:27]
	v_readlane_b32 s42, v3, 54
	v_readlane_b32 s44, v5, 54
	v_readlane_b32 s46, v7, 54
	s_waitcnt vmcnt(31)
	v_pk_fma_f32 v[22:23], v[110:111], s[48:49], v[22:23] op_sel_hi:[1,0,1]
	v_pk_fma_f32 v[18:19], v[110:111], s[50:51], v[18:19] op_sel_hi:[1,0,1]
	v_pk_fma_f32 v[20:21], v[110:111], s[52:53], v[20:21] op_sel_hi:[1,0,1]
	global_load_dwordx2 v[110:111], v[36:37], off
	v_lshl_add_u64 v[36:37], v[36:37], 0, s[26:27]
	v_readlane_b32 s48, v3, 55
	v_readlane_b32 s50, v5, 55
	v_readlane_b32 s52, v7, 55
	s_waitcnt vmcnt(31)
	v_pk_fma_f32 v[22:23], v[112:113], s[42:43], v[22:23] op_sel_hi:[1,0,1]
	v_pk_fma_f32 v[18:19], v[112:113], s[44:45], v[18:19] op_sel_hi:[1,0,1]
	v_pk_fma_f32 v[20:21], v[112:113], s[46:47], v[20:21] op_sel_hi:[1,0,1]
	global_load_dwordx2 v[112:113], v[36:37], off
	v_lshl_add_u64 v[36:37], v[36:37], 0, s[26:27]
	v_readlane_b32 s42, v3, 56
	v_readlane_b32 s44, v5, 56
	v_readlane_b32 s46, v7, 56
	s_waitcnt vmcnt(31)
	v_pk_fma_f32 v[22:23], v[114:115], s[48:49], v[22:23] op_sel_hi:[1,0,1]
	v_pk_fma_f32 v[18:19], v[114:115], s[50:51], v[18:19] op_sel_hi:[1,0,1]
	v_pk_fma_f32 v[20:21], v[114:115], s[52:53], v[20:21] op_sel_hi:[1,0,1]
	global_load_dwordx2 v[114:115], v[36:37], off
	v_lshl_add_u64 v[36:37], v[36:37], 0, s[26:27]
	v_readlane_b32 s48, v3, 57
	v_readlane_b32 s50, v5, 57
	v_readlane_b32 s52, v7, 57
	s_waitcnt vmcnt(31)
	v_pk_fma_f32 v[22:23], v[116:117], s[42:43], v[22:23] op_sel_hi:[1,0,1]
	v_pk_fma_f32 v[18:19], v[116:117], s[44:45], v[18:19] op_sel_hi:[1,0,1]
	v_pk_fma_f32 v[20:21], v[116:117], s[46:47], v[20:21] op_sel_hi:[1,0,1]
	global_load_dwordx2 v[116:117], v[36:37], off
	v_lshl_add_u64 v[36:37], v[36:37], 0, s[26:27]
	v_readlane_b32 s42, v3, 58
	v_readlane_b32 s44, v5, 58
	v_readlane_b32 s46, v7, 58
	s_waitcnt vmcnt(31)
	v_pk_fma_f32 v[22:23], v[118:119], s[48:49], v[22:23] op_sel_hi:[1,0,1]
	v_pk_fma_f32 v[18:19], v[118:119], s[50:51], v[18:19] op_sel_hi:[1,0,1]
	v_pk_fma_f32 v[20:21], v[118:119], s[52:53], v[20:21] op_sel_hi:[1,0,1]
	global_load_dwordx2 v[118:119], v[36:37], off
	v_lshl_add_u64 v[36:37], v[36:37], 0, s[26:27]
	v_readlane_b32 s48, v3, 59
	v_readlane_b32 s50, v5, 59
	v_readlane_b32 s52, v7, 59
	s_waitcnt vmcnt(31)
	v_pk_fma_f32 v[22:23], v[120:121], s[42:43], v[22:23] op_sel_hi:[1,0,1]
	v_pk_fma_f32 v[18:19], v[120:121], s[44:45], v[18:19] op_sel_hi:[1,0,1]
	v_pk_fma_f32 v[20:21], v[120:121], s[46:47], v[20:21] op_sel_hi:[1,0,1]
	global_load_dwordx2 v[120:121], v[36:37], off
	v_lshl_add_u64 v[36:37], v[36:37], 0, s[26:27]
	v_readlane_b32 s42, v3, 60
	v_readlane_b32 s44, v5, 60
	v_readlane_b32 s46, v7, 60
	s_waitcnt vmcnt(31)
	v_pk_fma_f32 v[22:23], v[122:123], s[48:49], v[22:23] op_sel_hi:[1,0,1]
	v_pk_fma_f32 v[18:19], v[122:123], s[50:51], v[18:19] op_sel_hi:[1,0,1]
	v_pk_fma_f32 v[20:21], v[122:123], s[52:53], v[20:21] op_sel_hi:[1,0,1]
	global_load_dwordx2 v[122:123], v[36:37], off
	v_lshl_add_u64 v[36:37], v[36:37], 0, s[26:27]
	v_readlane_b32 s48, v3, 61
	v_readlane_b32 s50, v5, 61
	v_readlane_b32 s52, v7, 61
	s_waitcnt vmcnt(31)
	v_pk_fma_f32 v[22:23], v[124:125], s[42:43], v[22:23] op_sel_hi:[1,0,1]
	v_pk_fma_f32 v[18:19], v[124:125], s[44:45], v[18:19] op_sel_hi:[1,0,1]
	v_pk_fma_f32 v[20:21], v[124:125], s[46:47], v[20:21] op_sel_hi:[1,0,1]
	global_load_dwordx2 v[124:125], v[36:37], off
	v_lshl_add_u64 v[36:37], v[36:37], 0, s[26:27]
	v_readlane_b32 s42, v3, 62
	v_readlane_b32 s44, v5, 62
	v_readlane_b32 s46, v7, 62
	s_waitcnt vmcnt(31)
	v_pk_fma_f32 v[22:23], v[126:127], s[48:49], v[22:23] op_sel_hi:[1,0,1]
	v_pk_fma_f32 v[18:19], v[126:127], s[50:51], v[18:19] op_sel_hi:[1,0,1]
	v_pk_fma_f32 v[20:21], v[126:127], s[52:53], v[20:21] op_sel_hi:[1,0,1]
	global_load_dwordx2 v[126:127], v[36:37], off
	v_lshl_add_u64 v[36:37], v[36:37], 0, s[26:27]
	v_readlane_b32 s48, v3, 63
	v_readlane_b32 s50, v5, 63
	v_readlane_b32 s52, v7, 63
	s_waitcnt vmcnt(31)
	v_pk_fma_f32 v[22:23], v[128:129], s[42:43], v[22:23] op_sel_hi:[1,0,1]
	v_pk_fma_f32 v[18:19], v[128:129], s[44:45], v[18:19] op_sel_hi:[1,0,1]
	v_pk_fma_f32 v[20:21], v[128:129], s[46:47], v[20:21] op_sel_hi:[1,0,1]
	global_load_dwordx2 v[128:129], v[36:37], off
	v_lshl_add_u64 v[36:37], v[36:37], 0, s[26:27]
	v_readlane_b32 s42, v4, 0
	v_readlane_b32 s44, v6, 0
	v_readlane_b32 s46, v8, 0
	s_waitcnt vmcnt(31)
	v_pk_fma_f32 v[22:23], v[130:131], s[48:49], v[22:23] op_sel_hi:[1,0,1]
	v_pk_fma_f32 v[18:19], v[130:131], s[50:51], v[18:19] op_sel_hi:[1,0,1]
	v_pk_fma_f32 v[20:21], v[130:131], s[52:53], v[20:21] op_sel_hi:[1,0,1]
	global_load_dwordx2 v[130:131], v[36:37], off
	v_lshl_add_u64 v[36:37], v[36:37], 0, s[26:27]
	v_readlane_b32 s48, v4, 1
	v_readlane_b32 s50, v6, 1
	v_readlane_b32 s52, v8, 1
	s_waitcnt vmcnt(31)
	v_pk_fma_f32 v[22:23], v[68:69], s[42:43], v[22:23] op_sel_hi:[1,0,1]
	v_pk_fma_f32 v[18:19], v[68:69], s[44:45], v[18:19] op_sel_hi:[1,0,1]
	v_pk_fma_f32 v[20:21], v[68:69], s[46:47], v[20:21] op_sel_hi:[1,0,1]
	global_load_dwordx2 v[68:69], v[36:37], off
	v_lshl_add_u64 v[36:37], v[36:37], 0, s[26:27]
	v_readlane_b32 s42, v4, 2
	v_readlane_b32 s44, v6, 2
	v_readlane_b32 s46, v8, 2
	s_waitcnt vmcnt(31)
	v_pk_fma_f32 v[22:23], v[70:71], s[48:49], v[22:23] op_sel_hi:[1,0,1]
	v_pk_fma_f32 v[18:19], v[70:71], s[50:51], v[18:19] op_sel_hi:[1,0,1]
	v_pk_fma_f32 v[20:21], v[70:71], s[52:53], v[20:21] op_sel_hi:[1,0,1]
	global_load_dwordx2 v[70:71], v[36:37], off
	v_lshl_add_u64 v[36:37], v[36:37], 0, s[26:27]
	v_readlane_b32 s48, v4, 3
	v_readlane_b32 s50, v6, 3
	v_readlane_b32 s52, v8, 3
	s_waitcnt vmcnt(31)
	v_pk_fma_f32 v[22:23], v[72:73], s[42:43], v[22:23] op_sel_hi:[1,0,1]
	v_pk_fma_f32 v[18:19], v[72:73], s[44:45], v[18:19] op_sel_hi:[1,0,1]
	v_pk_fma_f32 v[20:21], v[72:73], s[46:47], v[20:21] op_sel_hi:[1,0,1]
	global_load_dwordx2 v[72:73], v[36:37], off
	v_lshl_add_u64 v[36:37], v[36:37], 0, s[26:27]
	v_readlane_b32 s42, v4, 4
	v_readlane_b32 s44, v6, 4
	v_readlane_b32 s46, v8, 4
	s_waitcnt vmcnt(31)
	v_pk_fma_f32 v[22:23], v[74:75], s[48:49], v[22:23] op_sel_hi:[1,0,1]
	v_pk_fma_f32 v[18:19], v[74:75], s[50:51], v[18:19] op_sel_hi:[1,0,1]
	v_pk_fma_f32 v[20:21], v[74:75], s[52:53], v[20:21] op_sel_hi:[1,0,1]
	global_load_dwordx2 v[74:75], v[36:37], off
	v_lshl_add_u64 v[36:37], v[36:37], 0, s[26:27]
	v_readlane_b32 s48, v4, 5
	v_readlane_b32 s50, v6, 5
	v_readlane_b32 s52, v8, 5
	s_waitcnt vmcnt(31)
	v_pk_fma_f32 v[22:23], v[76:77], s[42:43], v[22:23] op_sel_hi:[1,0,1]
	v_pk_fma_f32 v[18:19], v[76:77], s[44:45], v[18:19] op_sel_hi:[1,0,1]
	v_pk_fma_f32 v[20:21], v[76:77], s[46:47], v[20:21] op_sel_hi:[1,0,1]
	global_load_dwordx2 v[76:77], v[36:37], off
	v_lshl_add_u64 v[36:37], v[36:37], 0, s[26:27]
	v_readlane_b32 s42, v4, 6
	v_readlane_b32 s44, v6, 6
	v_readlane_b32 s46, v8, 6
	s_waitcnt vmcnt(31)
	v_pk_fma_f32 v[22:23], v[78:79], s[48:49], v[22:23] op_sel_hi:[1,0,1]
	v_pk_fma_f32 v[18:19], v[78:79], s[50:51], v[18:19] op_sel_hi:[1,0,1]
	v_pk_fma_f32 v[20:21], v[78:79], s[52:53], v[20:21] op_sel_hi:[1,0,1]
	global_load_dwordx2 v[78:79], v[36:37], off
	v_lshl_add_u64 v[36:37], v[36:37], 0, s[26:27]
	v_readlane_b32 s48, v4, 7
	v_readlane_b32 s50, v6, 7
	v_readlane_b32 s52, v8, 7
	s_waitcnt vmcnt(31)
	v_pk_fma_f32 v[22:23], v[80:81], s[42:43], v[22:23] op_sel_hi:[1,0,1]
	v_pk_fma_f32 v[18:19], v[80:81], s[44:45], v[18:19] op_sel_hi:[1,0,1]
	v_pk_fma_f32 v[20:21], v[80:81], s[46:47], v[20:21] op_sel_hi:[1,0,1]
	global_load_dwordx2 v[80:81], v[36:37], off
	v_lshl_add_u64 v[36:37], v[36:37], 0, s[26:27]
	v_readlane_b32 s42, v4, 8
	v_readlane_b32 s44, v6, 8
	v_readlane_b32 s46, v8, 8
	s_waitcnt vmcnt(31)
	v_pk_fma_f32 v[22:23], v[82:83], s[48:49], v[22:23] op_sel_hi:[1,0,1]
	v_pk_fma_f32 v[18:19], v[82:83], s[50:51], v[18:19] op_sel_hi:[1,0,1]
	v_pk_fma_f32 v[20:21], v[82:83], s[52:53], v[20:21] op_sel_hi:[1,0,1]
	global_load_dwordx2 v[82:83], v[36:37], off
	v_lshl_add_u64 v[36:37], v[36:37], 0, s[26:27]
	v_readlane_b32 s48, v4, 9
	v_readlane_b32 s50, v6, 9
	v_readlane_b32 s52, v8, 9
	s_waitcnt vmcnt(31)
	v_pk_fma_f32 v[22:23], v[84:85], s[42:43], v[22:23] op_sel_hi:[1,0,1]
	v_pk_fma_f32 v[18:19], v[84:85], s[44:45], v[18:19] op_sel_hi:[1,0,1]
	v_pk_fma_f32 v[20:21], v[84:85], s[46:47], v[20:21] op_sel_hi:[1,0,1]
	global_load_dwordx2 v[84:85], v[36:37], off
	v_lshl_add_u64 v[36:37], v[36:37], 0, s[26:27]
	v_readlane_b32 s42, v4, 10
	v_readlane_b32 s44, v6, 10
	v_readlane_b32 s46, v8, 10
	s_waitcnt vmcnt(31)
	v_pk_fma_f32 v[22:23], v[86:87], s[48:49], v[22:23] op_sel_hi:[1,0,1]
	v_pk_fma_f32 v[18:19], v[86:87], s[50:51], v[18:19] op_sel_hi:[1,0,1]
	v_pk_fma_f32 v[20:21], v[86:87], s[52:53], v[20:21] op_sel_hi:[1,0,1]
	global_load_dwordx2 v[86:87], v[36:37], off
	v_lshl_add_u64 v[36:37], v[36:37], 0, s[26:27]
	v_readlane_b32 s48, v4, 11
	v_readlane_b32 s50, v6, 11
	v_readlane_b32 s52, v8, 11
	s_waitcnt vmcnt(31)
	v_pk_fma_f32 v[22:23], v[88:89], s[42:43], v[22:23] op_sel_hi:[1,0,1]
	v_pk_fma_f32 v[18:19], v[88:89], s[44:45], v[18:19] op_sel_hi:[1,0,1]
	v_pk_fma_f32 v[20:21], v[88:89], s[46:47], v[20:21] op_sel_hi:[1,0,1]
	global_load_dwordx2 v[88:89], v[36:37], off
	v_lshl_add_u64 v[36:37], v[36:37], 0, s[26:27]
	v_readlane_b32 s42, v4, 12
	v_readlane_b32 s44, v6, 12
	v_readlane_b32 s46, v8, 12
	s_waitcnt vmcnt(31)
	v_pk_fma_f32 v[22:23], v[90:91], s[48:49], v[22:23] op_sel_hi:[1,0,1]
	v_pk_fma_f32 v[18:19], v[90:91], s[50:51], v[18:19] op_sel_hi:[1,0,1]
	v_pk_fma_f32 v[20:21], v[90:91], s[52:53], v[20:21] op_sel_hi:[1,0,1]
	global_load_dwordx2 v[90:91], v[36:37], off
	v_lshl_add_u64 v[36:37], v[36:37], 0, s[26:27]
	v_readlane_b32 s48, v4, 13
	v_readlane_b32 s50, v6, 13
	v_readlane_b32 s52, v8, 13
	s_waitcnt vmcnt(31)
	v_pk_fma_f32 v[22:23], v[92:93], s[42:43], v[22:23] op_sel_hi:[1,0,1]
	v_pk_fma_f32 v[18:19], v[92:93], s[44:45], v[18:19] op_sel_hi:[1,0,1]
	v_pk_fma_f32 v[20:21], v[92:93], s[46:47], v[20:21] op_sel_hi:[1,0,1]
	global_load_dwordx2 v[92:93], v[36:37], off
	v_lshl_add_u64 v[36:37], v[36:37], 0, s[26:27]
	v_readlane_b32 s42, v4, 14
	v_readlane_b32 s44, v6, 14
	v_readlane_b32 s46, v8, 14
	s_waitcnt vmcnt(31)
	v_pk_fma_f32 v[22:23], v[94:95], s[48:49], v[22:23] op_sel_hi:[1,0,1]
	v_pk_fma_f32 v[18:19], v[94:95], s[50:51], v[18:19] op_sel_hi:[1,0,1]
	v_pk_fma_f32 v[20:21], v[94:95], s[52:53], v[20:21] op_sel_hi:[1,0,1]
	global_load_dwordx2 v[94:95], v[36:37], off
	v_lshl_add_u64 v[36:37], v[36:37], 0, s[26:27]
	v_readlane_b32 s48, v4, 15
	v_readlane_b32 s50, v6, 15
	v_readlane_b32 s52, v8, 15
	s_waitcnt vmcnt(31)
	v_pk_fma_f32 v[22:23], v[96:97], s[42:43], v[22:23] op_sel_hi:[1,0,1]
	v_pk_fma_f32 v[18:19], v[96:97], s[44:45], v[18:19] op_sel_hi:[1,0,1]
	v_pk_fma_f32 v[20:21], v[96:97], s[46:47], v[20:21] op_sel_hi:[1,0,1]
	global_load_dwordx2 v[96:97], v[36:37], off
	v_lshl_add_u64 v[36:37], v[36:37], 0, s[26:27]
	v_readlane_b32 s42, v4, 16
	v_readlane_b32 s44, v6, 16
	v_readlane_b32 s46, v8, 16
	s_waitcnt vmcnt(31)
	v_pk_fma_f32 v[22:23], v[98:99], s[48:49], v[22:23] op_sel_hi:[1,0,1]
	v_pk_fma_f32 v[18:19], v[98:99], s[50:51], v[18:19] op_sel_hi:[1,0,1]
	v_pk_fma_f32 v[20:21], v[98:99], s[52:53], v[20:21] op_sel_hi:[1,0,1]
	global_load_dwordx2 v[98:99], v[36:37], off
	v_lshl_add_u64 v[36:37], v[36:37], 0, s[26:27]
	v_readlane_b32 s48, v4, 17
	v_readlane_b32 s50, v6, 17
	v_readlane_b32 s52, v8, 17
	s_waitcnt vmcnt(31)
	v_pk_fma_f32 v[22:23], v[100:101], s[42:43], v[22:23] op_sel_hi:[1,0,1]
	v_pk_fma_f32 v[18:19], v[100:101], s[44:45], v[18:19] op_sel_hi:[1,0,1]
	v_pk_fma_f32 v[20:21], v[100:101], s[46:47], v[20:21] op_sel_hi:[1,0,1]
	global_load_dwordx2 v[100:101], v[36:37], off
	v_lshl_add_u64 v[36:37], v[36:37], 0, s[26:27]
	v_readlane_b32 s42, v4, 18
	v_readlane_b32 s44, v6, 18
	v_readlane_b32 s46, v8, 18
	s_waitcnt vmcnt(31)
	v_pk_fma_f32 v[22:23], v[102:103], s[48:49], v[22:23] op_sel_hi:[1,0,1]
	v_pk_fma_f32 v[18:19], v[102:103], s[50:51], v[18:19] op_sel_hi:[1,0,1]
	v_pk_fma_f32 v[20:21], v[102:103], s[52:53], v[20:21] op_sel_hi:[1,0,1]
	global_load_dwordx2 v[102:103], v[36:37], off
	v_lshl_add_u64 v[36:37], v[36:37], 0, s[26:27]
	v_readlane_b32 s48, v4, 19
	v_readlane_b32 s50, v6, 19
	v_readlane_b32 s52, v8, 19
	s_waitcnt vmcnt(31)
	v_pk_fma_f32 v[22:23], v[104:105], s[42:43], v[22:23] op_sel_hi:[1,0,1]
	v_pk_fma_f32 v[18:19], v[104:105], s[44:45], v[18:19] op_sel_hi:[1,0,1]
	v_pk_fma_f32 v[20:21], v[104:105], s[46:47], v[20:21] op_sel_hi:[1,0,1]
	global_load_dwordx2 v[104:105], v[36:37], off
	v_lshl_add_u64 v[36:37], v[36:37], 0, s[26:27]
	v_readlane_b32 s42, v4, 20
	v_readlane_b32 s44, v6, 20
	v_readlane_b32 s46, v8, 20
	s_waitcnt vmcnt(31)
	v_pk_fma_f32 v[22:23], v[106:107], s[48:49], v[22:23] op_sel_hi:[1,0,1]
	v_pk_fma_f32 v[18:19], v[106:107], s[50:51], v[18:19] op_sel_hi:[1,0,1]
	v_pk_fma_f32 v[20:21], v[106:107], s[52:53], v[20:21] op_sel_hi:[1,0,1]
	global_load_dwordx2 v[106:107], v[36:37], off
	v_lshl_add_u64 v[36:37], v[36:37], 0, s[26:27]
	v_readlane_b32 s48, v4, 21
	v_readlane_b32 s50, v6, 21
	v_readlane_b32 s52, v8, 21
	s_waitcnt vmcnt(31)
	v_pk_fma_f32 v[22:23], v[108:109], s[42:43], v[22:23] op_sel_hi:[1,0,1]
	v_pk_fma_f32 v[18:19], v[108:109], s[44:45], v[18:19] op_sel_hi:[1,0,1]
	v_pk_fma_f32 v[20:21], v[108:109], s[46:47], v[20:21] op_sel_hi:[1,0,1]
	global_load_dwordx2 v[108:109], v[36:37], off
	v_lshl_add_u64 v[36:37], v[36:37], 0, s[26:27]
	v_readlane_b32 s42, v4, 22
	v_readlane_b32 s44, v6, 22
	v_readlane_b32 s46, v8, 22
	s_waitcnt vmcnt(31)
	v_pk_fma_f32 v[22:23], v[110:111], s[48:49], v[22:23] op_sel_hi:[1,0,1]
	v_pk_fma_f32 v[18:19], v[110:111], s[50:51], v[18:19] op_sel_hi:[1,0,1]
	v_pk_fma_f32 v[20:21], v[110:111], s[52:53], v[20:21] op_sel_hi:[1,0,1]
	global_load_dwordx2 v[110:111], v[36:37], off
	v_lshl_add_u64 v[36:37], v[36:37], 0, s[26:27]
	v_readlane_b32 s48, v4, 23
	v_readlane_b32 s50, v6, 23
	v_readlane_b32 s52, v8, 23
	s_waitcnt vmcnt(31)
	v_pk_fma_f32 v[22:23], v[112:113], s[42:43], v[22:23] op_sel_hi:[1,0,1]
	v_pk_fma_f32 v[18:19], v[112:113], s[44:45], v[18:19] op_sel_hi:[1,0,1]
	v_pk_fma_f32 v[20:21], v[112:113], s[46:47], v[20:21] op_sel_hi:[1,0,1]
	global_load_dwordx2 v[112:113], v[36:37], off
	v_lshl_add_u64 v[36:37], v[36:37], 0, s[26:27]
	v_readlane_b32 s42, v4, 24
	v_readlane_b32 s44, v6, 24
	v_readlane_b32 s46, v8, 24
	s_waitcnt vmcnt(31)
	v_pk_fma_f32 v[22:23], v[114:115], s[48:49], v[22:23] op_sel_hi:[1,0,1]
	v_pk_fma_f32 v[18:19], v[114:115], s[50:51], v[18:19] op_sel_hi:[1,0,1]
	v_pk_fma_f32 v[20:21], v[114:115], s[52:53], v[20:21] op_sel_hi:[1,0,1]
	global_load_dwordx2 v[114:115], v[36:37], off
	v_lshl_add_u64 v[36:37], v[36:37], 0, s[26:27]
	v_readlane_b32 s48, v4, 25
	v_readlane_b32 s50, v6, 25
	v_readlane_b32 s52, v8, 25
	s_waitcnt vmcnt(31)
	v_pk_fma_f32 v[22:23], v[116:117], s[42:43], v[22:23] op_sel_hi:[1,0,1]
	v_pk_fma_f32 v[18:19], v[116:117], s[44:45], v[18:19] op_sel_hi:[1,0,1]
	v_pk_fma_f32 v[20:21], v[116:117], s[46:47], v[20:21] op_sel_hi:[1,0,1]
	global_load_dwordx2 v[116:117], v[36:37], off
	v_lshl_add_u64 v[36:37], v[36:37], 0, s[26:27]
	v_readlane_b32 s42, v4, 26
	v_readlane_b32 s44, v6, 26
	v_readlane_b32 s46, v8, 26
	s_waitcnt vmcnt(31)
	v_pk_fma_f32 v[22:23], v[118:119], s[48:49], v[22:23] op_sel_hi:[1,0,1]
	v_pk_fma_f32 v[18:19], v[118:119], s[50:51], v[18:19] op_sel_hi:[1,0,1]
	v_pk_fma_f32 v[20:21], v[118:119], s[52:53], v[20:21] op_sel_hi:[1,0,1]
	global_load_dwordx2 v[118:119], v[36:37], off
	v_lshl_add_u64 v[36:37], v[36:37], 0, s[26:27]
	v_readlane_b32 s48, v4, 27
	v_readlane_b32 s50, v6, 27
	v_readlane_b32 s52, v8, 27
	s_waitcnt vmcnt(31)
	v_pk_fma_f32 v[22:23], v[120:121], s[42:43], v[22:23] op_sel_hi:[1,0,1]
	v_pk_fma_f32 v[18:19], v[120:121], s[44:45], v[18:19] op_sel_hi:[1,0,1]
	v_pk_fma_f32 v[20:21], v[120:121], s[46:47], v[20:21] op_sel_hi:[1,0,1]
	global_load_dwordx2 v[120:121], v[36:37], off
	v_lshl_add_u64 v[36:37], v[36:37], 0, s[26:27]
	v_readlane_b32 s42, v4, 28
	v_readlane_b32 s44, v6, 28
	v_readlane_b32 s46, v8, 28
	s_waitcnt vmcnt(31)
	v_pk_fma_f32 v[22:23], v[122:123], s[48:49], v[22:23] op_sel_hi:[1,0,1]
	v_pk_fma_f32 v[18:19], v[122:123], s[50:51], v[18:19] op_sel_hi:[1,0,1]
	v_pk_fma_f32 v[20:21], v[122:123], s[52:53], v[20:21] op_sel_hi:[1,0,1]
	global_load_dwordx2 v[122:123], v[36:37], off
	v_lshl_add_u64 v[36:37], v[36:37], 0, s[26:27]
	v_readlane_b32 s48, v4, 29
	v_readlane_b32 s50, v6, 29
	v_readlane_b32 s52, v8, 29
	s_waitcnt vmcnt(31)
	v_pk_fma_f32 v[22:23], v[124:125], s[42:43], v[22:23] op_sel_hi:[1,0,1]
	v_pk_fma_f32 v[18:19], v[124:125], s[44:45], v[18:19] op_sel_hi:[1,0,1]
	v_pk_fma_f32 v[20:21], v[124:125], s[46:47], v[20:21] op_sel_hi:[1,0,1]
	global_load_dwordx2 v[124:125], v[36:37], off
	v_lshl_add_u64 v[36:37], v[36:37], 0, s[26:27]
	v_readlane_b32 s42, v4, 30
	v_readlane_b32 s44, v6, 30
	v_readlane_b32 s46, v8, 30
	s_waitcnt vmcnt(31)
	v_pk_fma_f32 v[22:23], v[126:127], s[48:49], v[22:23] op_sel_hi:[1,0,1]
	v_pk_fma_f32 v[18:19], v[126:127], s[50:51], v[18:19] op_sel_hi:[1,0,1]
	v_pk_fma_f32 v[20:21], v[126:127], s[52:53], v[20:21] op_sel_hi:[1,0,1]
	global_load_dwordx2 v[126:127], v[36:37], off
	v_lshl_add_u64 v[36:37], v[36:37], 0, s[26:27]
	v_readlane_b32 s48, v4, 31
	v_readlane_b32 s50, v6, 31
	v_readlane_b32 s52, v8, 31
	s_waitcnt vmcnt(31)
	v_pk_fma_f32 v[22:23], v[128:129], s[42:43], v[22:23] op_sel_hi:[1,0,1]
	v_pk_fma_f32 v[18:19], v[128:129], s[44:45], v[18:19] op_sel_hi:[1,0,1]
	v_pk_fma_f32 v[20:21], v[128:129], s[46:47], v[20:21] op_sel_hi:[1,0,1]
	global_load_dwordx2 v[128:129], v[36:37], off
	v_lshl_add_u64 v[36:37], v[36:37], 0, s[26:27]
	v_readlane_b32 s42, v4, 32
	v_readlane_b32 s44, v6, 32
	v_readlane_b32 s46, v8, 32
	s_waitcnt vmcnt(31)
	v_pk_fma_f32 v[22:23], v[130:131], s[48:49], v[22:23] op_sel_hi:[1,0,1]
	v_pk_fma_f32 v[18:19], v[130:131], s[50:51], v[18:19] op_sel_hi:[1,0,1]
	v_pk_fma_f32 v[20:21], v[130:131], s[52:53], v[20:21] op_sel_hi:[1,0,1]
	global_load_dwordx2 v[130:131], v[36:37], off
	v_lshl_add_u64 v[36:37], v[36:37], 0, s[26:27]
	v_readlane_b32 s48, v4, 33
	v_readlane_b32 s50, v6, 33
	v_readlane_b32 s52, v8, 33
	s_waitcnt vmcnt(31)
	v_pk_fma_f32 v[22:23], v[68:69], s[42:43], v[22:23] op_sel_hi:[1,0,1]
	v_pk_fma_f32 v[18:19], v[68:69], s[44:45], v[18:19] op_sel_hi:[1,0,1]
	v_pk_fma_f32 v[20:21], v[68:69], s[46:47], v[20:21] op_sel_hi:[1,0,1]
	v_readlane_b32 s42, v4, 34
	v_readlane_b32 s44, v6, 34
	v_readlane_b32 s46, v8, 34
	s_waitcnt vmcnt(30)
	v_pk_fma_f32 v[22:23], v[70:71], s[48:49], v[22:23] op_sel_hi:[1,0,1]
	v_pk_fma_f32 v[18:19], v[70:71], s[50:51], v[18:19] op_sel_hi:[1,0,1]
	v_pk_fma_f32 v[20:21], v[70:71], s[52:53], v[20:21] op_sel_hi:[1,0,1]
	v_readlane_b32 s48, v4, 35
	v_readlane_b32 s50, v6, 35
	v_readlane_b32 s52, v8, 35
	s_waitcnt vmcnt(29)
	v_pk_fma_f32 v[22:23], v[72:73], s[42:43], v[22:23] op_sel_hi:[1,0,1]
	v_pk_fma_f32 v[18:19], v[72:73], s[44:45], v[18:19] op_sel_hi:[1,0,1]
	v_pk_fma_f32 v[20:21], v[72:73], s[46:47], v[20:21] op_sel_hi:[1,0,1]
	v_readlane_b32 s42, v4, 36
	v_readlane_b32 s44, v6, 36
	v_readlane_b32 s46, v8, 36
	s_waitcnt vmcnt(28)
	v_pk_fma_f32 v[22:23], v[74:75], s[48:49], v[22:23] op_sel_hi:[1,0,1]
	v_pk_fma_f32 v[18:19], v[74:75], s[50:51], v[18:19] op_sel_hi:[1,0,1]
	v_pk_fma_f32 v[20:21], v[74:75], s[52:53], v[20:21] op_sel_hi:[1,0,1]
	v_readlane_b32 s48, v4, 37
	v_readlane_b32 s50, v6, 37
	v_readlane_b32 s52, v8, 37
	s_waitcnt vmcnt(27)
	v_pk_fma_f32 v[22:23], v[76:77], s[42:43], v[22:23] op_sel_hi:[1,0,1]
	v_pk_fma_f32 v[18:19], v[76:77], s[44:45], v[18:19] op_sel_hi:[1,0,1]
	v_pk_fma_f32 v[20:21], v[76:77], s[46:47], v[20:21] op_sel_hi:[1,0,1]
	v_readlane_b32 s42, v4, 38
	v_readlane_b32 s44, v6, 38
	v_readlane_b32 s46, v8, 38
	s_waitcnt vmcnt(26)
	v_pk_fma_f32 v[22:23], v[78:79], s[48:49], v[22:23] op_sel_hi:[1,0,1]
	v_pk_fma_f32 v[18:19], v[78:79], s[50:51], v[18:19] op_sel_hi:[1,0,1]
	v_pk_fma_f32 v[20:21], v[78:79], s[52:53], v[20:21] op_sel_hi:[1,0,1]
	v_readlane_b32 s48, v4, 39
	v_readlane_b32 s50, v6, 39
	v_readlane_b32 s52, v8, 39
	s_waitcnt vmcnt(25)
	v_pk_fma_f32 v[22:23], v[80:81], s[42:43], v[22:23] op_sel_hi:[1,0,1]
	v_pk_fma_f32 v[18:19], v[80:81], s[44:45], v[18:19] op_sel_hi:[1,0,1]
	v_pk_fma_f32 v[20:21], v[80:81], s[46:47], v[20:21] op_sel_hi:[1,0,1]
	v_readlane_b32 s42, v4, 40
	v_readlane_b32 s44, v6, 40
	v_readlane_b32 s46, v8, 40
	s_waitcnt vmcnt(24)
	v_pk_fma_f32 v[22:23], v[82:83], s[48:49], v[22:23] op_sel_hi:[1,0,1]
	v_pk_fma_f32 v[18:19], v[82:83], s[50:51], v[18:19] op_sel_hi:[1,0,1]
	v_pk_fma_f32 v[20:21], v[82:83], s[52:53], v[20:21] op_sel_hi:[1,0,1]
	v_readlane_b32 s48, v4, 41
	v_readlane_b32 s50, v6, 41
	v_readlane_b32 s52, v8, 41
	s_waitcnt vmcnt(23)
	v_pk_fma_f32 v[22:23], v[84:85], s[42:43], v[22:23] op_sel_hi:[1,0,1]
	v_pk_fma_f32 v[18:19], v[84:85], s[44:45], v[18:19] op_sel_hi:[1,0,1]
	v_pk_fma_f32 v[20:21], v[84:85], s[46:47], v[20:21] op_sel_hi:[1,0,1]
	v_readlane_b32 s42, v4, 42
	v_readlane_b32 s44, v6, 42
	v_readlane_b32 s46, v8, 42
	s_waitcnt vmcnt(22)
	v_pk_fma_f32 v[22:23], v[86:87], s[48:49], v[22:23] op_sel_hi:[1,0,1]
	v_pk_fma_f32 v[18:19], v[86:87], s[50:51], v[18:19] op_sel_hi:[1,0,1]
	v_pk_fma_f32 v[20:21], v[86:87], s[52:53], v[20:21] op_sel_hi:[1,0,1]
	v_readlane_b32 s48, v4, 43
	v_readlane_b32 s50, v6, 43
	v_readlane_b32 s52, v8, 43
	s_waitcnt vmcnt(21)
	v_pk_fma_f32 v[22:23], v[88:89], s[42:43], v[22:23] op_sel_hi:[1,0,1]
	v_pk_fma_f32 v[18:19], v[88:89], s[44:45], v[18:19] op_sel_hi:[1,0,1]
	v_pk_fma_f32 v[20:21], v[88:89], s[46:47], v[20:21] op_sel_hi:[1,0,1]
	v_readlane_b32 s42, v4, 44
	v_readlane_b32 s44, v6, 44
	v_readlane_b32 s46, v8, 44
	s_waitcnt vmcnt(20)
	v_pk_fma_f32 v[22:23], v[90:91], s[48:49], v[22:23] op_sel_hi:[1,0,1]
	v_pk_fma_f32 v[18:19], v[90:91], s[50:51], v[18:19] op_sel_hi:[1,0,1]
	v_pk_fma_f32 v[20:21], v[90:91], s[52:53], v[20:21] op_sel_hi:[1,0,1]
	v_readlane_b32 s48, v4, 45
	v_readlane_b32 s50, v6, 45
	v_readlane_b32 s52, v8, 45
	s_waitcnt vmcnt(19)
	v_pk_fma_f32 v[22:23], v[92:93], s[42:43], v[22:23] op_sel_hi:[1,0,1]
	v_pk_fma_f32 v[18:19], v[92:93], s[44:45], v[18:19] op_sel_hi:[1,0,1]
	v_pk_fma_f32 v[20:21], v[92:93], s[46:47], v[20:21] op_sel_hi:[1,0,1]
	v_readlane_b32 s42, v4, 46
	v_readlane_b32 s44, v6, 46
	v_readlane_b32 s46, v8, 46
	s_waitcnt vmcnt(18)
	v_pk_fma_f32 v[22:23], v[94:95], s[48:49], v[22:23] op_sel_hi:[1,0,1]
	v_pk_fma_f32 v[18:19], v[94:95], s[50:51], v[18:19] op_sel_hi:[1,0,1]
	v_pk_fma_f32 v[20:21], v[94:95], s[52:53], v[20:21] op_sel_hi:[1,0,1]
	v_readlane_b32 s48, v4, 47
	v_readlane_b32 s50, v6, 47
	v_readlane_b32 s52, v8, 47
	s_waitcnt vmcnt(17)
	v_pk_fma_f32 v[22:23], v[96:97], s[42:43], v[22:23] op_sel_hi:[1,0,1]
	v_pk_fma_f32 v[18:19], v[96:97], s[44:45], v[18:19] op_sel_hi:[1,0,1]
	v_pk_fma_f32 v[20:21], v[96:97], s[46:47], v[20:21] op_sel_hi:[1,0,1]
	v_readlane_b32 s42, v4, 48
	v_readlane_b32 s44, v6, 48
	v_readlane_b32 s46, v8, 48
	s_waitcnt vmcnt(16)
	v_pk_fma_f32 v[22:23], v[98:99], s[48:49], v[22:23] op_sel_hi:[1,0,1]
	v_pk_fma_f32 v[18:19], v[98:99], s[50:51], v[18:19] op_sel_hi:[1,0,1]
	v_pk_fma_f32 v[20:21], v[98:99], s[52:53], v[20:21] op_sel_hi:[1,0,1]
	v_readlane_b32 s48, v4, 49
	v_readlane_b32 s50, v6, 49
	v_readlane_b32 s52, v8, 49
	s_waitcnt vmcnt(15)
	v_pk_fma_f32 v[22:23], v[100:101], s[42:43], v[22:23] op_sel_hi:[1,0,1]
	v_pk_fma_f32 v[18:19], v[100:101], s[44:45], v[18:19] op_sel_hi:[1,0,1]
	v_pk_fma_f32 v[20:21], v[100:101], s[46:47], v[20:21] op_sel_hi:[1,0,1]
	v_readlane_b32 s42, v4, 50
	v_readlane_b32 s44, v6, 50
	v_readlane_b32 s46, v8, 50
	s_waitcnt vmcnt(14)
	v_pk_fma_f32 v[22:23], v[102:103], s[48:49], v[22:23] op_sel_hi:[1,0,1]
	v_pk_fma_f32 v[18:19], v[102:103], s[50:51], v[18:19] op_sel_hi:[1,0,1]
	v_pk_fma_f32 v[20:21], v[102:103], s[52:53], v[20:21] op_sel_hi:[1,0,1]
	v_readlane_b32 s48, v4, 51
	v_readlane_b32 s50, v6, 51
	v_readlane_b32 s52, v8, 51
	s_waitcnt vmcnt(13)
	v_pk_fma_f32 v[22:23], v[104:105], s[42:43], v[22:23] op_sel_hi:[1,0,1]
	v_pk_fma_f32 v[18:19], v[104:105], s[44:45], v[18:19] op_sel_hi:[1,0,1]
	v_pk_fma_f32 v[20:21], v[104:105], s[46:47], v[20:21] op_sel_hi:[1,0,1]
	v_readlane_b32 s42, v4, 52
	v_readlane_b32 s44, v6, 52
	v_readlane_b32 s46, v8, 52
	s_waitcnt vmcnt(12)
	v_pk_fma_f32 v[22:23], v[106:107], s[48:49], v[22:23] op_sel_hi:[1,0,1]
	v_pk_fma_f32 v[18:19], v[106:107], s[50:51], v[18:19] op_sel_hi:[1,0,1]
	v_pk_fma_f32 v[20:21], v[106:107], s[52:53], v[20:21] op_sel_hi:[1,0,1]
	v_readlane_b32 s48, v4, 53
	v_readlane_b32 s50, v6, 53
	v_readlane_b32 s52, v8, 53
	s_waitcnt vmcnt(11)
	v_pk_fma_f32 v[22:23], v[108:109], s[42:43], v[22:23] op_sel_hi:[1,0,1]
	v_pk_fma_f32 v[18:19], v[108:109], s[44:45], v[18:19] op_sel_hi:[1,0,1]
	v_pk_fma_f32 v[20:21], v[108:109], s[46:47], v[20:21] op_sel_hi:[1,0,1]
	v_readlane_b32 s42, v4, 54
	v_readlane_b32 s44, v6, 54
	v_readlane_b32 s46, v8, 54
	s_waitcnt vmcnt(10)
	v_pk_fma_f32 v[22:23], v[110:111], s[48:49], v[22:23] op_sel_hi:[1,0,1]
	v_pk_fma_f32 v[18:19], v[110:111], s[50:51], v[18:19] op_sel_hi:[1,0,1]
	v_pk_fma_f32 v[20:21], v[110:111], s[52:53], v[20:21] op_sel_hi:[1,0,1]
	v_readlane_b32 s48, v4, 55
	v_readlane_b32 s50, v6, 55
	v_readlane_b32 s52, v8, 55
	s_waitcnt vmcnt(9)
	v_pk_fma_f32 v[22:23], v[112:113], s[42:43], v[22:23] op_sel_hi:[1,0,1]
	v_pk_fma_f32 v[18:19], v[112:113], s[44:45], v[18:19] op_sel_hi:[1,0,1]
	v_pk_fma_f32 v[20:21], v[112:113], s[46:47], v[20:21] op_sel_hi:[1,0,1]
	v_readlane_b32 s42, v4, 56
	v_readlane_b32 s44, v6, 56
	v_readlane_b32 s46, v8, 56
	s_waitcnt vmcnt(8)
	v_pk_fma_f32 v[22:23], v[114:115], s[48:49], v[22:23] op_sel_hi:[1,0,1]
	v_pk_fma_f32 v[18:19], v[114:115], s[50:51], v[18:19] op_sel_hi:[1,0,1]
	v_pk_fma_f32 v[20:21], v[114:115], s[52:53], v[20:21] op_sel_hi:[1,0,1]
	v_readlane_b32 s48, v4, 57
	v_readlane_b32 s50, v6, 57
	v_readlane_b32 s52, v8, 57
	s_waitcnt vmcnt(7)
	v_pk_fma_f32 v[22:23], v[116:117], s[42:43], v[22:23] op_sel_hi:[1,0,1]
	v_pk_fma_f32 v[18:19], v[116:117], s[44:45], v[18:19] op_sel_hi:[1,0,1]
	v_pk_fma_f32 v[20:21], v[116:117], s[46:47], v[20:21] op_sel_hi:[1,0,1]
	v_readlane_b32 s42, v4, 58
	v_readlane_b32 s44, v6, 58
	v_readlane_b32 s46, v8, 58
	s_waitcnt vmcnt(6)
	v_pk_fma_f32 v[22:23], v[118:119], s[48:49], v[22:23] op_sel_hi:[1,0,1]
	v_pk_fma_f32 v[18:19], v[118:119], s[50:51], v[18:19] op_sel_hi:[1,0,1]
	v_pk_fma_f32 v[20:21], v[118:119], s[52:53], v[20:21] op_sel_hi:[1,0,1]
	v_readlane_b32 s48, v4, 59
	v_readlane_b32 s50, v6, 59
	v_readlane_b32 s52, v8, 59
	s_waitcnt vmcnt(5)
	v_pk_fma_f32 v[22:23], v[120:121], s[42:43], v[22:23] op_sel_hi:[1,0,1]
	v_pk_fma_f32 v[18:19], v[120:121], s[44:45], v[18:19] op_sel_hi:[1,0,1]
	v_pk_fma_f32 v[20:21], v[120:121], s[46:47], v[20:21] op_sel_hi:[1,0,1]
	v_readlane_b32 s42, v4, 60
	v_readlane_b32 s44, v6, 60
	v_readlane_b32 s46, v8, 60
	s_waitcnt vmcnt(4)
	v_pk_fma_f32 v[22:23], v[122:123], s[48:49], v[22:23] op_sel_hi:[1,0,1]
	v_pk_fma_f32 v[18:19], v[122:123], s[50:51], v[18:19] op_sel_hi:[1,0,1]
	v_pk_fma_f32 v[20:21], v[122:123], s[52:53], v[20:21] op_sel_hi:[1,0,1]
	v_readlane_b32 s48, v4, 61
	v_readlane_b32 s50, v6, 61
	v_readlane_b32 s52, v8, 61
	s_waitcnt vmcnt(3)
	v_pk_fma_f32 v[22:23], v[124:125], s[42:43], v[22:23] op_sel_hi:[1,0,1]
	v_pk_fma_f32 v[18:19], v[124:125], s[44:45], v[18:19] op_sel_hi:[1,0,1]
	v_pk_fma_f32 v[20:21], v[124:125], s[46:47], v[20:21] op_sel_hi:[1,0,1]
	v_readlane_b32 s42, v4, 62
	v_readlane_b32 s44, v6, 62
	v_readlane_b32 s46, v8, 62
	s_waitcnt vmcnt(2)
	v_pk_fma_f32 v[22:23], v[126:127], s[48:49], v[22:23] op_sel_hi:[1,0,1]
	v_pk_fma_f32 v[18:19], v[126:127], s[50:51], v[18:19] op_sel_hi:[1,0,1]
	v_pk_fma_f32 v[20:21], v[126:127], s[52:53], v[20:21] op_sel_hi:[1,0,1]
	v_readlane_b32 s48, v4, 63
	v_readlane_b32 s50, v6, 63
	v_readlane_b32 s52, v8, 63
	s_waitcnt vmcnt(1)
	v_pk_fma_f32 v[22:23], v[128:129], s[42:43], v[22:23] op_sel_hi:[1,0,1]
	v_pk_fma_f32 v[18:19], v[128:129], s[44:45], v[18:19] op_sel_hi:[1,0,1]
	v_pk_fma_f32 v[20:21], v[128:129], s[46:47], v[20:21] op_sel_hi:[1,0,1]
	s_nop 1
	s_waitcnt vmcnt(0)
	v_pk_fma_f32 v[22:23], v[130:131], s[48:49], v[22:23] op_sel_hi:[1,0,1]
	v_pk_fma_f32 v[18:19], v[130:131], s[50:51], v[18:19] op_sel_hi:[1,0,1]
	v_pk_fma_f32 v[20:21], v[130:131], s[52:53], v[20:21] op_sel_hi:[1,0,1]
	ds_write2st64_b64 v46, v[22:23], v[18:19] offset1:1
	ds_write_b64 v46, v[20:21] offset:1024
	s_waitcnt lgkmcnt(0)
	s_barrier
	s_and_saveexec_b64 s[2:3], s[40:41]
	s_cbranch_execz .LBB0_684
	s_mov_b32 s4, 7
	s_ashr_i32 s5, s4, 31
	s_lshl_b64 s[4:5], s[4:5], 3
	s_add_u32 s4, s0, s4
	s_addc_u32 s5, s1, s5
	s_load_dwordx2 s[4:5], s[4:5], 0x0
	s_mul_i32 s26, s54, 0x6000
	s_mul_hi_i32 s13, s54, 0x6000
	v_mov_b64_e32 v[22:23], s[22:23]
	s_waitcnt lgkmcnt(0)
	s_add_u32 s4, s4, s26
	s_addc_u32 s5, s5, s13
	s_add_u32 s4, s4, s24
	s_addc_u32 s5, s5, s25
	global_load_dwordx2 v[18:19], v0, s[4:5]
	ds_read2st64_b64 v[2:5], v47 offset1:3
	ds_read2st64_b64 v[6:9], v47 offset0:6 offset1:9
	ds_read2st64_b64 v[10:13], v47 offset0:12 offset1:15
	ds_read2st64_b64 v[14:17], v47 offset0:18 offset1:21
	v_mad_i64_i32 v[20:21], s[4:5], s54, 3, v[30:31]
	v_mad_u64_u32 v[22:23], s[4:5], v20, s78, v[22:23]
	v_mad_i32_i24 v23, v21, s78, v23
	v_lshl_add_u64 v[20:21], v[22:23], 0, s[24:25]
	s_waitcnt vmcnt(0) lgkmcnt(3)
	v_pk_add_f32 v[2:3], v[18:19], v[2:3]
	s_nop 0
	v_pk_add_f32 v[2:3], v[2:3], v[4:5]
	v_lshl_add_u64 v[4:5], v[20:21], 0, v[0:1]
	s_waitcnt lgkmcnt(2)
	v_pk_add_f32 v[2:3], v[2:3], v[6:7]
	s_nop 0
	v_pk_add_f32 v[2:3], v[2:3], v[8:9]
	s_waitcnt lgkmcnt(1)
	v_pk_add_f32 v[2:3], v[2:3], v[10:11]
	s_nop 0
	v_pk_add_f32 v[2:3], v[2:3], v[12:13]
	s_waitcnt lgkmcnt(0)
	v_pk_add_f32 v[2:3], v[2:3], v[14:15]
	s_nop 0
	v_pk_add_f32 v[2:3], v[2:3], v[16:17]
	global_store_dwordx2 v[4:5], v[2:3], off
	s_branch .LBB0_684

.LBB0_697:
	s_mov_b32 s2, 0x201000
	s_mov_b32 s3, 0
	v_lshl_add_u64 v[46:47], v[4:5], 0, s[2:3]
	s_mov_b32 s86, 0x2000
	s_mov_b32 s87, 0
	v_mov_b32_e32 v24, s15
	global_load_dword v96, v[46:47], off offset:-4096
	global_load_dword v97, v[46:47], off
	v_lshl_add_u64 v[46:47], v[46:47], 0, s[86:87]
	global_load_dword v98, v[46:47], off offset:-4096
	global_load_dword v99, v[46:47], off
	v_lshl_add_u64 v[46:47], v[46:47], 0, s[86:87]
	global_load_dword v100, v[46:47], off offset:-4096
	global_load_dword v101, v[46:47], off
	v_lshl_add_u64 v[46:47], v[46:47], 0, s[86:87]
	global_load_dword v102, v[46:47], off offset:-4096
	global_load_dword v103, v[46:47], off
	v_lshl_add_u64 v[46:47], v[46:47], 0, s[86:87]
	global_load_dword v104, v[46:47], off offset:-4096
	global_load_dword v105, v[46:47], off
	v_lshl_add_u64 v[46:47], v[46:47], 0, s[86:87]
	global_load_dword v106, v[46:47], off offset:-4096
	global_load_dword v107, v[46:47], off
	v_lshl_add_u64 v[46:47], v[46:47], 0, s[86:87]
	global_load_dword v108, v[46:47], off offset:-4096
	global_load_dword v109, v[46:47], off
	v_lshl_add_u64 v[46:47], v[46:47], 0, s[86:87]
	global_load_dword v110, v[46:47], off offset:-4096
	global_load_dword v111, v[46:47], off
	v_lshl_add_u64 v[46:47], v[46:47], 0, s[86:87]
	global_load_dword v112, v[46:47], off offset:-4096
	global_load_dword v113, v[46:47], off
	v_lshl_add_u64 v[46:47], v[46:47], 0, s[86:87]
	global_load_dword v114, v[46:47], off offset:-4096
	global_load_dword v115, v[46:47], off
	v_lshl_add_u64 v[46:47], v[46:47], 0, s[86:87]
	global_load_dword v116, v[46:47], off offset:-4096
	global_load_dword v117, v[46:47], off
	v_lshl_add_u64 v[46:47], v[46:47], 0, s[86:87]
	global_load_dword v118, v[46:47], off offset:-4096
	global_load_dword v119, v[46:47], off
	v_lshl_add_u64 v[46:47], v[46:47], 0, s[86:87]
	global_load_dword v120, v[46:47], off offset:-4096
	global_load_dword v121, v[46:47], off
	v_lshl_add_u64 v[46:47], v[46:47], 0, s[86:87]
	global_load_dword v122, v[46:47], off offset:-4096
	global_load_dword v123, v[46:47], off
	v_lshl_add_u64 v[46:47], v[46:47], 0, s[86:87]
	global_load_dword v124, v[46:47], off offset:-4096
	global_load_dword v125, v[46:47], off
	v_lshl_add_u64 v[46:47], v[46:47], 0, s[86:87]
	global_load_dword v126, v[46:47], off offset:-4096
	global_load_dword v127, v[46:47], off
	v_lshl_add_u64 v[46:47], v[46:47], 0, s[86:87]
	global_load_dword v128, v[46:47], off offset:-4096
	global_load_dword v129, v[46:47], off
	v_lshl_add_u64 v[46:47], v[46:47], 0, s[86:87]
	global_load_dword v130, v[46:47], off offset:-4096
	global_load_dword v131, v[46:47], off
	v_lshl_add_u64 v[46:47], v[46:47], 0, s[86:87]
	global_load_dword v132, v[46:47], off offset:-4096
	global_load_dword v133, v[46:47], off
	v_lshl_add_u64 v[46:47], v[46:47], 0, s[86:87]
	global_load_dword v134, v[46:47], off offset:-4096
	global_load_dword v135, v[46:47], off
	v_lshl_add_u64 v[46:47], v[46:47], 0, s[86:87]
	global_load_dword v136, v[46:47], off offset:-4096
	global_load_dword v137, v[46:47], off
	v_lshl_add_u64 v[46:47], v[46:47], 0, s[86:87]
	global_load_dword v138, v[46:47], off offset:-4096
	global_load_dword v139, v[46:47], off
	v_lshl_add_u64 v[46:47], v[46:47], 0, s[86:87]
	global_load_dword v140, v[46:47], off offset:-4096
	global_load_dword v141, v[46:47], off
	v_lshl_add_u64 v[46:47], v[46:47], 0, s[86:87]
	global_load_dword v142, v[46:47], off offset:-4096
	global_load_dword v143, v[46:47], off
	v_lshl_add_u64 v[46:47], v[46:47], 0, s[86:87]
	global_load_dword v144, v[46:47], off offset:-4096
	global_load_dword v145, v[46:47], off
	v_lshl_add_u64 v[46:47], v[46:47], 0, s[86:87]
	global_load_dword v146, v[46:47], off offset:-4096
	global_load_dword v147, v[46:47], off
	v_lshl_add_u64 v[46:47], v[46:47], 0, s[86:87]
	global_load_dword v148, v[46:47], off offset:-4096
	global_load_dword v149, v[46:47], off
	v_lshl_add_u64 v[46:47], v[46:47], 0, s[86:87]
	global_load_dword v150, v[46:47], off offset:-4096
	global_load_dword v151, v[46:47], off
	v_lshl_add_u64 v[46:47], v[46:47], 0, s[86:87]
	global_load_dword v152, v[46:47], off offset:-4096
	global_load_dword v153, v[46:47], off
	v_lshl_add_u64 v[46:47], v[46:47], 0, s[86:87]
	global_load_dword v154, v[46:47], off offset:-4096
	global_load_dword v155, v[46:47], off
	v_lshl_add_u64 v[46:47], v[46:47], 0, s[86:87]
	ds_read_b128 v[26:29], v24
	ds_read_b128 v[30:33], v24 offset:16
	ds_read_b128 v[34:37], v24 offset:32
	ds_read_b128 v[38:41], v24 offset:48
	ds_read_b128 v[48:51], v24 offset:64
	ds_read_b128 v[52:55], v24 offset:80
	ds_read_b128 v[56:59], v24 offset:96
	ds_read_b128 v[60:63], v24 offset:112
	ds_read_b128 v[228:231], v24 offset:128
	ds_read_b128 v[232:235], v24 offset:144
	ds_read_b128 v[240:243], v24 offset:160
	ds_read_b128 v[244:247], v24 offset:176
	s_waitcnt vmcnt(59) lgkmcnt(8)
	v_pk_fma_f32 v[12:13], v[26:27], v[96:97], v[12:13] op_sel_hi:[1,0,1]
	v_pk_fma_f32 v[10:11], v[28:29], v[96:97], v[10:11] op_sel_hi:[1,0,1]
	v_pk_fma_f32 v[16:17], v[30:31], v[96:97], v[16:17] op_sel_hi:[1,0,1]
	v_pk_fma_f32 v[14:15], v[32:33], v[96:97], v[14:15] op_sel_hi:[1,0,1]
	v_pk_fma_f32 v[20:21], v[34:35], v[96:97], v[20:21] op_sel_hi:[1,0,1]
	v_pk_fma_f32 v[18:19], v[36:37], v[96:97], v[18:19] op_sel_hi:[1,0,1]
	v_pk_fma_f32 v[6:7], v[38:39], v[96:97], v[6:7] op_sel_hi:[1,0,1]
	v_pk_fma_f32 v[8:9], v[40:41], v[96:97], v[8:9] op_sel_hi:[1,0,1]
	global_load_dword v96, v[46:47], off offset:-4096
	ds_read_b128 v[26:29], v24 offset:192
	ds_read_b128 v[30:33], v24 offset:208
	ds_read_b128 v[34:37], v24 offset:224
	ds_read_b128 v[38:41], v24 offset:240
	s_waitcnt vmcnt(59) lgkmcnt(8)
	v_pk_fma_f32 v[12:13], v[48:49], v[96:97], v[12:13] op_sel:[0,1,0] op_sel_hi:[1,1,1]
	v_pk_fma_f32 v[10:11], v[50:51], v[96:97], v[10:11] op_sel:[0,1,0] op_sel_hi:[1,1,1]
	v_pk_fma_f32 v[16:17], v[52:53], v[96:97], v[16:17] op_sel:[0,1,0] op_sel_hi:[1,1,1]
	v_pk_fma_f32 v[14:15], v[54:55], v[96:97], v[14:15] op_sel:[0,1,0] op_sel_hi:[1,1,1]
	v_pk_fma_f32 v[20:21], v[56:57], v[96:97], v[20:21] op_sel:[0,1,0] op_sel_hi:[1,1,1]
	v_pk_fma_f32 v[18:19], v[58:59], v[96:97], v[18:19] op_sel:[0,1,0] op_sel_hi:[1,1,1]
	v_pk_fma_f32 v[6:7], v[60:61], v[96:97], v[6:7] op_sel:[0,1,0] op_sel_hi:[1,1,1]
	v_pk_fma_f32 v[8:9], v[62:63], v[96:97], v[8:9] op_sel:[0,1,0] op_sel_hi:[1,1,1]
	global_load_dword v97, v[46:47], off
	v_lshl_add_u64 v[46:47], v[46:47], 0, s[86:87]
	ds_read_b128 v[48:51], v24 offset:256
	ds_read_b128 v[52:55], v24 offset:272
	ds_read_b128 v[56:59], v24 offset:288
	ds_read_b128 v[60:63], v24 offset:304
	s_waitcnt vmcnt(59) lgkmcnt(8)
	v_pk_fma_f32 v[12:13], v[228:229], v[98:99], v[12:13] op_sel_hi:[1,0,1]
	v_pk_fma_f32 v[10:11], v[230:231], v[98:99], v[10:11] op_sel_hi:[1,0,1]
	v_pk_fma_f32 v[16:17], v[232:233], v[98:99], v[16:17] op_sel_hi:[1,0,1]
	v_pk_fma_f32 v[14:15], v[234:235], v[98:99], v[14:15] op_sel_hi:[1,0,1]
	v_pk_fma_f32 v[20:21], v[240:241], v[98:99], v[20:21] op_sel_hi:[1,0,1]
	v_pk_fma_f32 v[18:19], v[242:243], v[98:99], v[18:19] op_sel_hi:[1,0,1]
	v_pk_fma_f32 v[6:7], v[244:245], v[98:99], v[6:7] op_sel_hi:[1,0,1]
	v_pk_fma_f32 v[8:9], v[246:247], v[98:99], v[8:9] op_sel_hi:[1,0,1]
	global_load_dword v98, v[46:47], off offset:-4096
	ds_read_b128 v[228:231], v24 offset:320
	ds_read_b128 v[232:235], v24 offset:336
	ds_read_b128 v[240:243], v24 offset:352
	ds_read_b128 v[244:247], v24 offset:368
	s_waitcnt vmcnt(59) lgkmcnt(8)
	v_pk_fma_f32 v[12:13], v[26:27], v[98:99], v[12:13] op_sel:[0,1,0] op_sel_hi:[1,1,1]
	v_pk_fma_f32 v[10:11], v[28:29], v[98:99], v[10:11] op_sel:[0,1,0] op_sel_hi:[1,1,1]
	v_pk_fma_f32 v[16:17], v[30:31], v[98:99], v[16:17] op_sel:[0,1,0] op_sel_hi:[1,1,1]
	v_pk_fma_f32 v[14:15], v[32:33], v[98:99], v[14:15] op_sel:[0,1,0] op_sel_hi:[1,1,1]
	v_pk_fma_f32 v[20:21], v[34:35], v[98:99], v[20:21] op_sel:[0,1,0] op_sel_hi:[1,1,1]
	v_pk_fma_f32 v[18:19], v[36:37], v[98:99], v[18:19] op_sel:[0,1,0] op_sel_hi:[1,1,1]
	v_pk_fma_f32 v[6:7], v[38:39], v[98:99], v[6:7] op_sel:[0,1,0] op_sel_hi:[1,1,1]
	v_pk_fma_f32 v[8:9], v[40:41], v[98:99], v[8:9] op_sel:[0,1,0] op_sel_hi:[1,1,1]
	global_load_dword v99, v[46:47], off
	v_lshl_add_u64 v[46:47], v[46:47], 0, s[86:87]
	ds_read_b128 v[26:29], v24 offset:384
	ds_read_b128 v[30:33], v24 offset:400
	ds_read_b128 v[34:37], v24 offset:416
	ds_read_b128 v[38:41], v24 offset:432
	s_waitcnt vmcnt(59) lgkmcnt(8)
	v_pk_fma_f32 v[12:13], v[48:49], v[100:101], v[12:13] op_sel_hi:[1,0,1]
	v_pk_fma_f32 v[10:11], v[50:51], v[100:101], v[10:11] op_sel_hi:[1,0,1]
	v_pk_fma_f32 v[16:17], v[52:53], v[100:101], v[16:17] op_sel_hi:[1,0,1]
	v_pk_fma_f32 v[14:15], v[54:55], v[100:101], v[14:15] op_sel_hi:[1,0,1]
	v_pk_fma_f32 v[20:21], v[56:57], v[100:101], v[20:21] op_sel_hi:[1,0,1]
	v_pk_fma_f32 v[18:19], v[58:59], v[100:101], v[18:19] op_sel_hi:[1,0,1]
	v_pk_fma_f32 v[6:7], v[60:61], v[100:101], v[6:7] op_sel_hi:[1,0,1]
	v_pk_fma_f32 v[8:9], v[62:63], v[100:101], v[8:9] op_sel_hi:[1,0,1]
	global_load_dword v100, v[46:47], off offset:-4096
	ds_read_b128 v[48:51], v24 offset:448
	ds_read_b128 v[52:55], v24 offset:464
	ds_read_b128 v[56:59], v24 offset:480
	ds_read_b128 v[60:63], v24 offset:496
	s_waitcnt vmcnt(59) lgkmcnt(8)
	v_pk_fma_f32 v[12:13], v[228:229], v[100:101], v[12:13] op_sel:[0,1,0] op_sel_hi:[1,1,1]
	v_pk_fma_f32 v[10:11], v[230:231], v[100:101], v[10:11] op_sel:[0,1,0] op_sel_hi:[1,1,1]
	v_pk_fma_f32 v[16:17], v[232:233], v[100:101], v[16:17] op_sel:[0,1,0] op_sel_hi:[1,1,1]
	v_pk_fma_f32 v[14:15], v[234:235], v[100:101], v[14:15] op_sel:[0,1,0] op_sel_hi:[1,1,1]
	v_pk_fma_f32 v[20:21], v[240:241], v[100:101], v[20:21] op_sel:[0,1,0] op_sel_hi:[1,1,1]
	v_pk_fma_f32 v[18:19], v[242:243], v[100:101], v[18:19] op_sel:[0,1,0] op_sel_hi:[1,1,1]
	v_pk_fma_f32 v[6:7], v[244:245], v[100:101], v[6:7] op_sel:[0,1,0] op_sel_hi:[1,1,1]
	v_pk_fma_f32 v[8:9], v[246:247], v[100:101], v[8:9] op_sel:[0,1,0] op_sel_hi:[1,1,1]
	global_load_dword v101, v[46:47], off
	v_lshl_add_u64 v[46:47], v[46:47], 0, s[86:87]
	ds_read_b128 v[228:231], v24 offset:512
	ds_read_b128 v[232:235], v24 offset:528
	ds_read_b128 v[240:243], v24 offset:544
	ds_read_b128 v[244:247], v24 offset:560
	s_waitcnt vmcnt(59) lgkmcnt(8)
	v_pk_fma_f32 v[12:13], v[26:27], v[102:103], v[12:13] op_sel_hi:[1,0,1]
	v_pk_fma_f32 v[10:11], v[28:29], v[102:103], v[10:11] op_sel_hi:[1,0,1]
	v_pk_fma_f32 v[16:17], v[30:31], v[102:103], v[16:17] op_sel_hi:[1,0,1]
	v_pk_fma_f32 v[14:15], v[32:33], v[102:103], v[14:15] op_sel_hi:[1,0,1]
	v_pk_fma_f32 v[20:21], v[34:35], v[102:103], v[20:21] op_sel_hi:[1,0,1]
	v_pk_fma_f32 v[18:19], v[36:37], v[102:103], v[18:19] op_sel_hi:[1,0,1]
	v_pk_fma_f32 v[6:7], v[38:39], v[102:103], v[6:7] op_sel_hi:[1,0,1]
	v_pk_fma_f32 v[8:9], v[40:41], v[102:103], v[8:9] op_sel_hi:[1,0,1]
	global_load_dword v102, v[46:47], off offset:-4096
	ds_read_b128 v[26:29], v24 offset:576
	ds_read_b128 v[30:33], v24 offset:592
	ds_read_b128 v[34:37], v24 offset:608
	ds_read_b128 v[38:41], v24 offset:624
	s_waitcnt vmcnt(59) lgkmcnt(8)
	v_pk_fma_f32 v[12:13], v[48:49], v[102:103], v[12:13] op_sel:[0,1,0] op_sel_hi:[1,1,1]
	v_pk_fma_f32 v[10:11], v[50:51], v[102:103], v[10:11] op_sel:[0,1,0] op_sel_hi:[1,1,1]
	v_pk_fma_f32 v[16:17], v[52:53], v[102:103], v[16:17] op_sel:[0,1,0] op_sel_hi:[1,1,1]
	v_pk_fma_f32 v[14:15], v[54:55], v[102:103], v[14:15] op_sel:[0,1,0] op_sel_hi:[1,1,1]
	v_pk_fma_f32 v[20:21], v[56:57], v[102:103], v[20:21] op_sel:[0,1,0] op_sel_hi:[1,1,1]
	v_pk_fma_f32 v[18:19], v[58:59], v[102:103], v[18:19] op_sel:[0,1,0] op_sel_hi:[1,1,1]
	v_pk_fma_f32 v[6:7], v[60:61], v[102:103], v[6:7] op_sel:[0,1,0] op_sel_hi:[1,1,1]
	v_pk_fma_f32 v[8:9], v[62:63], v[102:103], v[8:9] op_sel:[0,1,0] op_sel_hi:[1,1,1]
	global_load_dword v103, v[46:47], off
	v_lshl_add_u64 v[46:47], v[46:47], 0, s[86:87]
	ds_read_b128 v[48:51], v24 offset:640
	ds_read_b128 v[52:55], v24 offset:656
	ds_read_b128 v[56:59], v24 offset:672
	ds_read_b128 v[60:63], v24 offset:688
	s_waitcnt vmcnt(59) lgkmcnt(8)
	v_pk_fma_f32 v[12:13], v[228:229], v[104:105], v[12:13] op_sel_hi:[1,0,1]
	v_pk_fma_f32 v[10:11], v[230:231], v[104:105], v[10:11] op_sel_hi:[1,0,1]
	v_pk_fma_f32 v[16:17], v[232:233], v[104:105], v[16:17] op_sel_hi:[1,0,1]
	v_pk_fma_f32 v[14:15], v[234:235], v[104:105], v[14:15] op_sel_hi:[1,0,1]
	v_pk_fma_f32 v[20:21], v[240:241], v[104:105], v[20:21] op_sel_hi:[1,0,1]
	v_pk_fma_f32 v[18:19], v[242:243], v[104:105], v[18:19] op_sel_hi:[1,0,1]
	v_pk_fma_f32 v[6:7], v[244:245], v[104:105], v[6:7] op_sel_hi:[1,0,1]
	v_pk_fma_f32 v[8:9], v[246:247], v[104:105], v[8:9] op_sel_hi:[1,0,1]
	global_load_dword v104, v[46:47], off offset:-4096
	ds_read_b128 v[228:231], v24 offset:704
	ds_read_b128 v[232:235], v24 offset:720
	ds_read_b128 v[240:243], v24 offset:736
	ds_read_b128 v[244:247], v24 offset:752
	s_waitcnt vmcnt(59) lgkmcnt(8)
	v_pk_fma_f32 v[12:13], v[26:27], v[104:105], v[12:13] op_sel:[0,1,0] op_sel_hi:[1,1,1]
	v_pk_fma_f32 v[10:11], v[28:29], v[104:105], v[10:11] op_sel:[0,1,0] op_sel_hi:[1,1,1]
	v_pk_fma_f32 v[16:17], v[30:31], v[104:105], v[16:17] op_sel:[0,1,0] op_sel_hi:[1,1,1]
	v_pk_fma_f32 v[14:15], v[32:33], v[104:105], v[14:15] op_sel:[0,1,0] op_sel_hi:[1,1,1]
	v_pk_fma_f32 v[20:21], v[34:35], v[104:105], v[20:21] op_sel:[0,1,0] op_sel_hi:[1,1,1]
	v_pk_fma_f32 v[18:19], v[36:37], v[104:105], v[18:19] op_sel:[0,1,0] op_sel_hi:[1,1,1]
	v_pk_fma_f32 v[6:7], v[38:39], v[104:105], v[6:7] op_sel:[0,1,0] op_sel_hi:[1,1,1]
	v_pk_fma_f32 v[8:9], v[40:41], v[104:105], v[8:9] op_sel:[0,1,0] op_sel_hi:[1,1,1]
	global_load_dword v105, v[46:47], off
	v_lshl_add_u64 v[46:47], v[46:47], 0, s[86:87]
	ds_read_b128 v[26:29], v24 offset:768
	ds_read_b128 v[30:33], v24 offset:784
	ds_read_b128 v[34:37], v24 offset:800
	ds_read_b128 v[38:41], v24 offset:816
	s_waitcnt vmcnt(59) lgkmcnt(8)
	v_pk_fma_f32 v[12:13], v[48:49], v[106:107], v[12:13] op_sel_hi:[1,0,1]
	v_pk_fma_f32 v[10:11], v[50:51], v[106:107], v[10:11] op_sel_hi:[1,0,1]
	v_pk_fma_f32 v[16:17], v[52:53], v[106:107], v[16:17] op_sel_hi:[1,0,1]
	v_pk_fma_f32 v[14:15], v[54:55], v[106:107], v[14:15] op_sel_hi:[1,0,1]
	v_pk_fma_f32 v[20:21], v[56:57], v[106:107], v[20:21] op_sel_hi:[1,0,1]
	v_pk_fma_f32 v[18:19], v[58:59], v[106:107], v[18:19] op_sel_hi:[1,0,1]
	v_pk_fma_f32 v[6:7], v[60:61], v[106:107], v[6:7] op_sel_hi:[1,0,1]
	v_pk_fma_f32 v[8:9], v[62:63], v[106:107], v[8:9] op_sel_hi:[1,0,1]
	global_load_dword v106, v[46:47], off offset:-4096
	ds_read_b128 v[48:51], v24 offset:832
	ds_read_b128 v[52:55], v24 offset:848
	ds_read_b128 v[56:59], v24 offset:864
	ds_read_b128 v[60:63], v24 offset:880
	s_waitcnt vmcnt(59) lgkmcnt(8)
	v_pk_fma_f32 v[12:13], v[228:229], v[106:107], v[12:13] op_sel:[0,1,0] op_sel_hi:[1,1,1]
	v_pk_fma_f32 v[10:11], v[230:231], v[106:107], v[10:11] op_sel:[0,1,0] op_sel_hi:[1,1,1]
	v_pk_fma_f32 v[16:17], v[232:233], v[106:107], v[16:17] op_sel:[0,1,0] op_sel_hi:[1,1,1]
	v_pk_fma_f32 v[14:15], v[234:235], v[106:107], v[14:15] op_sel:[0,1,0] op_sel_hi:[1,1,1]
	v_pk_fma_f32 v[20:21], v[240:241], v[106:107], v[20:21] op_sel:[0,1,0] op_sel_hi:[1,1,1]
	v_pk_fma_f32 v[18:19], v[242:243], v[106:107], v[18:19] op_sel:[0,1,0] op_sel_hi:[1,1,1]
	v_pk_fma_f32 v[6:7], v[244:245], v[106:107], v[6:7] op_sel:[0,1,0] op_sel_hi:[1,1,1]
	v_pk_fma_f32 v[8:9], v[246:247], v[106:107], v[8:9] op_sel:[0,1,0] op_sel_hi:[1,1,1]
	global_load_dword v107, v[46:47], off
	v_lshl_add_u64 v[46:47], v[46:47], 0, s[86:87]
	ds_read_b128 v[228:231], v24 offset:896
	ds_read_b128 v[232:235], v24 offset:912
	ds_read_b128 v[240:243], v24 offset:928
	ds_read_b128 v[244:247], v24 offset:944
	s_waitcnt vmcnt(59) lgkmcnt(8)
	v_pk_fma_f32 v[12:13], v[26:27], v[108:109], v[12:13] op_sel_hi:[1,0,1]
	v_pk_fma_f32 v[10:11], v[28:29], v[108:109], v[10:11] op_sel_hi:[1,0,1]
	v_pk_fma_f32 v[16:17], v[30:31], v[108:109], v[16:17] op_sel_hi:[1,0,1]
	v_pk_fma_f32 v[14:15], v[32:33], v[108:109], v[14:15] op_sel_hi:[1,0,1]
	v_pk_fma_f32 v[20:21], v[34:35], v[108:109], v[20:21] op_sel_hi:[1,0,1]
	v_pk_fma_f32 v[18:19], v[36:37], v[108:109], v[18:19] op_sel_hi:[1,0,1]
	v_pk_fma_f32 v[6:7], v[38:39], v[108:109], v[6:7] op_sel_hi:[1,0,1]
	v_pk_fma_f32 v[8:9], v[40:41], v[108:109], v[8:9] op_sel_hi:[1,0,1]
	global_load_dword v108, v[46:47], off offset:-4096
	ds_read_b128 v[26:29], v24 offset:960
	ds_read_b128 v[30:33], v24 offset:976
	ds_read_b128 v[34:37], v24 offset:992
	ds_read_b128 v[38:41], v24 offset:1008
	s_waitcnt vmcnt(59) lgkmcnt(8)
	v_pk_fma_f32 v[12:13], v[48:49], v[108:109], v[12:13] op_sel:[0,1,0] op_sel_hi:[1,1,1]
	v_pk_fma_f32 v[10:11], v[50:51], v[108:109], v[10:11] op_sel:[0,1,0] op_sel_hi:[1,1,1]
	v_pk_fma_f32 v[16:17], v[52:53], v[108:109], v[16:17] op_sel:[0,1,0] op_sel_hi:[1,1,1]
	v_pk_fma_f32 v[14:15], v[54:55], v[108:109], v[14:15] op_sel:[0,1,0] op_sel_hi:[1,1,1]
	v_pk_fma_f32 v[20:21], v[56:57], v[108:109], v[20:21] op_sel:[0,1,0] op_sel_hi:[1,1,1]
	v_pk_fma_f32 v[18:19], v[58:59], v[108:109], v[18:19] op_sel:[0,1,0] op_sel_hi:[1,1,1]
	v_pk_fma_f32 v[6:7], v[60:61], v[108:109], v[6:7] op_sel:[0,1,0] op_sel_hi:[1,1,1]
	v_pk_fma_f32 v[8:9], v[62:63], v[108:109], v[8:9] op_sel:[0,1,0] op_sel_hi:[1,1,1]
	global_load_dword v109, v[46:47], off
	v_lshl_add_u64 v[46:47], v[46:47], 0, s[86:87]
	ds_read_b128 v[48:51], v24 offset:1024
	ds_read_b128 v[52:55], v24 offset:1040
	ds_read_b128 v[56:59], v24 offset:1056
	ds_read_b128 v[60:63], v24 offset:1072
	s_waitcnt vmcnt(59) lgkmcnt(8)
	v_pk_fma_f32 v[12:13], v[228:229], v[110:111], v[12:13] op_sel_hi:[1,0,1]
	v_pk_fma_f32 v[10:11], v[230:231], v[110:111], v[10:11] op_sel_hi:[1,0,1]
	v_pk_fma_f32 v[16:17], v[232:233], v[110:111], v[16:17] op_sel_hi:[1,0,1]
	v_pk_fma_f32 v[14:15], v[234:235], v[110:111], v[14:15] op_sel_hi:[1,0,1]
	v_pk_fma_f32 v[20:21], v[240:241], v[110:111], v[20:21] op_sel_hi:[1,0,1]
	v_pk_fma_f32 v[18:19], v[242:243], v[110:111], v[18:19] op_sel_hi:[1,0,1]
	v_pk_fma_f32 v[6:7], v[244:245], v[110:111], v[6:7] op_sel_hi:[1,0,1]
	v_pk_fma_f32 v[8:9], v[246:247], v[110:111], v[8:9] op_sel_hi:[1,0,1]
	global_load_dword v110, v[46:47], off offset:-4096
	ds_read_b128 v[228:231], v24 offset:1088
	ds_read_b128 v[232:235], v24 offset:1104
	ds_read_b128 v[240:243], v24 offset:1120
	ds_read_b128 v[244:247], v24 offset:1136
	s_waitcnt vmcnt(59) lgkmcnt(8)
	v_pk_fma_f32 v[12:13], v[26:27], v[110:111], v[12:13] op_sel:[0,1,0] op_sel_hi:[1,1,1]
	v_pk_fma_f32 v[10:11], v[28:29], v[110:111], v[10:11] op_sel:[0,1,0] op_sel_hi:[1,1,1]
	v_pk_fma_f32 v[16:17], v[30:31], v[110:111], v[16:17] op_sel:[0,1,0] op_sel_hi:[1,1,1]
	v_pk_fma_f32 v[14:15], v[32:33], v[110:111], v[14:15] op_sel:[0,1,0] op_sel_hi:[1,1,1]
	v_pk_fma_f32 v[20:21], v[34:35], v[110:111], v[20:21] op_sel:[0,1,0] op_sel_hi:[1,1,1]
	v_pk_fma_f32 v[18:19], v[36:37], v[110:111], v[18:19] op_sel:[0,1,0] op_sel_hi:[1,1,1]
	v_pk_fma_f32 v[6:7], v[38:39], v[110:111], v[6:7] op_sel:[0,1,0] op_sel_hi:[1,1,1]
	v_pk_fma_f32 v[8:9], v[40:41], v[110:111], v[8:9] op_sel:[0,1,0] op_sel_hi:[1,1,1]
	global_load_dword v111, v[46:47], off
	v_lshl_add_u64 v[46:47], v[46:47], 0, s[86:87]
	ds_read_b128 v[26:29], v24 offset:1152
	ds_read_b128 v[30:33], v24 offset:1168
	ds_read_b128 v[34:37], v24 offset:1184
	ds_read_b128 v[38:41], v24 offset:1200
	s_waitcnt vmcnt(59) lgkmcnt(8)
	v_pk_fma_f32 v[12:13], v[48:49], v[112:113], v[12:13] op_sel_hi:[1,0,1]
	v_pk_fma_f32 v[10:11], v[50:51], v[112:113], v[10:11] op_sel_hi:[1,0,1]
	v_pk_fma_f32 v[16:17], v[52:53], v[112:113], v[16:17] op_sel_hi:[1,0,1]
	v_pk_fma_f32 v[14:15], v[54:55], v[112:113], v[14:15] op_sel_hi:[1,0,1]
	v_pk_fma_f32 v[20:21], v[56:57], v[112:113], v[20:21] op_sel_hi:[1,0,1]
	v_pk_fma_f32 v[18:19], v[58:59], v[112:113], v[18:19] op_sel_hi:[1,0,1]
	v_pk_fma_f32 v[6:7], v[60:61], v[112:113], v[6:7] op_sel_hi:[1,0,1]
	v_pk_fma_f32 v[8:9], v[62:63], v[112:113], v[8:9] op_sel_hi:[1,0,1]
	global_load_dword v112, v[46:47], off offset:-4096
	ds_read_b128 v[48:51], v24 offset:1216
	ds_read_b128 v[52:55], v24 offset:1232
	ds_read_b128 v[56:59], v24 offset:1248
	ds_read_b128 v[60:63], v24 offset:1264
	s_waitcnt vmcnt(59) lgkmcnt(8)
	v_pk_fma_f32 v[12:13], v[228:229], v[112:113], v[12:13] op_sel:[0,1,0] op_sel_hi:[1,1,1]
	v_pk_fma_f32 v[10:11], v[230:231], v[112:113], v[10:11] op_sel:[0,1,0] op_sel_hi:[1,1,1]
	v_pk_fma_f32 v[16:17], v[232:233], v[112:113], v[16:17] op_sel:[0,1,0] op_sel_hi:[1,1,1]
	v_pk_fma_f32 v[14:15], v[234:235], v[112:113], v[14:15] op_sel:[0,1,0] op_sel_hi:[1,1,1]
	v_pk_fma_f32 v[20:21], v[240:241], v[112:113], v[20:21] op_sel:[0,1,0] op_sel_hi:[1,1,1]
	v_pk_fma_f32 v[18:19], v[242:243], v[112:113], v[18:19] op_sel:[0,1,0] op_sel_hi:[1,1,1]
	v_pk_fma_f32 v[6:7], v[244:245], v[112:113], v[6:7] op_sel:[0,1,0] op_sel_hi:[1,1,1]
	v_pk_fma_f32 v[8:9], v[246:247], v[112:113], v[8:9] op_sel:[0,1,0] op_sel_hi:[1,1,1]
	global_load_dword v113, v[46:47], off
	v_lshl_add_u64 v[46:47], v[46:47], 0, s[86:87]
	ds_read_b128 v[228:231], v24 offset:1280
	ds_read_b128 v[232:235], v24 offset:1296
	ds_read_b128 v[240:243], v24 offset:1312
	ds_read_b128 v[244:247], v24 offset:1328
	s_waitcnt vmcnt(59) lgkmcnt(8)
	v_pk_fma_f32 v[12:13], v[26:27], v[114:115], v[12:13] op_sel_hi:[1,0,1]
	v_pk_fma_f32 v[10:11], v[28:29], v[114:115], v[10:11] op_sel_hi:[1,0,1]
	v_pk_fma_f32 v[16:17], v[30:31], v[114:115], v[16:17] op_sel_hi:[1,0,1]
	v_pk_fma_f32 v[14:15], v[32:33], v[114:115], v[14:15] op_sel_hi:[1,0,1]
	v_pk_fma_f32 v[20:21], v[34:35], v[114:115], v[20:21] op_sel_hi:[1,0,1]
	v_pk_fma_f32 v[18:19], v[36:37], v[114:115], v[18:19] op_sel_hi:[1,0,1]
	v_pk_fma_f32 v[6:7], v[38:39], v[114:115], v[6:7] op_sel_hi:[1,0,1]
	v_pk_fma_f32 v[8:9], v[40:41], v[114:115], v[8:9] op_sel_hi:[1,0,1]
	global_load_dword v114, v[46:47], off offset:-4096
	ds_read_b128 v[26:29], v24 offset:1344
	ds_read_b128 v[30:33], v24 offset:1360
	ds_read_b128 v[34:37], v24 offset:1376
	ds_read_b128 v[38:41], v24 offset:1392
	s_waitcnt vmcnt(59) lgkmcnt(8)
	v_pk_fma_f32 v[12:13], v[48:49], v[114:115], v[12:13] op_sel:[0,1,0] op_sel_hi:[1,1,1]
	v_pk_fma_f32 v[10:11], v[50:51], v[114:115], v[10:11] op_sel:[0,1,0] op_sel_hi:[1,1,1]
	v_pk_fma_f32 v[16:17], v[52:53], v[114:115], v[16:17] op_sel:[0,1,0] op_sel_hi:[1,1,1]
	v_pk_fma_f32 v[14:15], v[54:55], v[114:115], v[14:15] op_sel:[0,1,0] op_sel_hi:[1,1,1]
	v_pk_fma_f32 v[20:21], v[56:57], v[114:115], v[20:21] op_sel:[0,1,0] op_sel_hi:[1,1,1]
	v_pk_fma_f32 v[18:19], v[58:59], v[114:115], v[18:19] op_sel:[0,1,0] op_sel_hi:[1,1,1]
	v_pk_fma_f32 v[6:7], v[60:61], v[114:115], v[6:7] op_sel:[0,1,0] op_sel_hi:[1,1,1]
	v_pk_fma_f32 v[8:9], v[62:63], v[114:115], v[8:9] op_sel:[0,1,0] op_sel_hi:[1,1,1]
	global_load_dword v115, v[46:47], off
	v_lshl_add_u64 v[46:47], v[46:47], 0, s[86:87]
	ds_read_b128 v[48:51], v24 offset:1408
	ds_read_b128 v[52:55], v24 offset:1424
	ds_read_b128 v[56:59], v24 offset:1440
	ds_read_b128 v[60:63], v24 offset:1456
	s_waitcnt vmcnt(59) lgkmcnt(8)
	v_pk_fma_f32 v[12:13], v[228:229], v[116:117], v[12:13] op_sel_hi:[1,0,1]
	v_pk_fma_f32 v[10:11], v[230:231], v[116:117], v[10:11] op_sel_hi:[1,0,1]
	v_pk_fma_f32 v[16:17], v[232:233], v[116:117], v[16:17] op_sel_hi:[1,0,1]
	v_pk_fma_f32 v[14:15], v[234:235], v[116:117], v[14:15] op_sel_hi:[1,0,1]
	v_pk_fma_f32 v[20:21], v[240:241], v[116:117], v[20:21] op_sel_hi:[1,0,1]
	v_pk_fma_f32 v[18:19], v[242:243], v[116:117], v[18:19] op_sel_hi:[1,0,1]
	v_pk_fma_f32 v[6:7], v[244:245], v[116:117], v[6:7] op_sel_hi:[1,0,1]
	v_pk_fma_f32 v[8:9], v[246:247], v[116:117], v[8:9] op_sel_hi:[1,0,1]
	global_load_dword v116, v[46:47], off offset:-4096
	ds_read_b128 v[228:231], v24 offset:1472
	ds_read_b128 v[232:235], v24 offset:1488
	ds_read_b128 v[240:243], v24 offset:1504
	ds_read_b128 v[244:247], v24 offset:1520
	s_waitcnt vmcnt(59) lgkmcnt(8)
	v_pk_fma_f32 v[12:13], v[26:27], v[116:117], v[12:13] op_sel:[0,1,0] op_sel_hi:[1,1,1]
	v_pk_fma_f32 v[10:11], v[28:29], v[116:117], v[10:11] op_sel:[0,1,0] op_sel_hi:[1,1,1]
	v_pk_fma_f32 v[16:17], v[30:31], v[116:117], v[16:17] op_sel:[0,1,0] op_sel_hi:[1,1,1]
	v_pk_fma_f32 v[14:15], v[32:33], v[116:117], v[14:15] op_sel:[0,1,0] op_sel_hi:[1,1,1]
	v_pk_fma_f32 v[20:21], v[34:35], v[116:117], v[20:21] op_sel:[0,1,0] op_sel_hi:[1,1,1]
	v_pk_fma_f32 v[18:19], v[36:37], v[116:117], v[18:19] op_sel:[0,1,0] op_sel_hi:[1,1,1]
	v_pk_fma_f32 v[6:7], v[38:39], v[116:117], v[6:7] op_sel:[0,1,0] op_sel_hi:[1,1,1]
	v_pk_fma_f32 v[8:9], v[40:41], v[116:117], v[8:9] op_sel:[0,1,0] op_sel_hi:[1,1,1]
	global_load_dword v117, v[46:47], off
	v_lshl_add_u64 v[46:47], v[46:47], 0, s[86:87]
	ds_read_b128 v[26:29], v24 offset:1536
	ds_read_b128 v[30:33], v24 offset:1552
	ds_read_b128 v[34:37], v24 offset:1568
	ds_read_b128 v[38:41], v24 offset:1584
	s_waitcnt vmcnt(59) lgkmcnt(8)
	v_pk_fma_f32 v[12:13], v[48:49], v[118:119], v[12:13] op_sel_hi:[1,0,1]
	v_pk_fma_f32 v[10:11], v[50:51], v[118:119], v[10:11] op_sel_hi:[1,0,1]
	v_pk_fma_f32 v[16:17], v[52:53], v[118:119], v[16:17] op_sel_hi:[1,0,1]
	v_pk_fma_f32 v[14:15], v[54:55], v[118:119], v[14:15] op_sel_hi:[1,0,1]
	v_pk_fma_f32 v[20:21], v[56:57], v[118:119], v[20:21] op_sel_hi:[1,0,1]
	v_pk_fma_f32 v[18:19], v[58:59], v[118:119], v[18:19] op_sel_hi:[1,0,1]
	v_pk_fma_f32 v[6:7], v[60:61], v[118:119], v[6:7] op_sel_hi:[1,0,1]
	v_pk_fma_f32 v[8:9], v[62:63], v[118:119], v[8:9] op_sel_hi:[1,0,1]
	global_load_dword v118, v[46:47], off offset:-4096
	ds_read_b128 v[48:51], v24 offset:1600
	ds_read_b128 v[52:55], v24 offset:1616
	ds_read_b128 v[56:59], v24 offset:1632
	ds_read_b128 v[60:63], v24 offset:1648
	s_waitcnt vmcnt(59) lgkmcnt(8)
	v_pk_fma_f32 v[12:13], v[228:229], v[118:119], v[12:13] op_sel:[0,1,0] op_sel_hi:[1,1,1]
	v_pk_fma_f32 v[10:11], v[230:231], v[118:119], v[10:11] op_sel:[0,1,0] op_sel_hi:[1,1,1]
	v_pk_fma_f32 v[16:17], v[232:233], v[118:119], v[16:17] op_sel:[0,1,0] op_sel_hi:[1,1,1]
	v_pk_fma_f32 v[14:15], v[234:235], v[118:119], v[14:15] op_sel:[0,1,0] op_sel_hi:[1,1,1]
	v_pk_fma_f32 v[20:21], v[240:241], v[118:119], v[20:21] op_sel:[0,1,0] op_sel_hi:[1,1,1]
	v_pk_fma_f32 v[18:19], v[242:243], v[118:119], v[18:19] op_sel:[0,1,0] op_sel_hi:[1,1,1]
	v_pk_fma_f32 v[6:7], v[244:245], v[118:119], v[6:7] op_sel:[0,1,0] op_sel_hi:[1,1,1]
	v_pk_fma_f32 v[8:9], v[246:247], v[118:119], v[8:9] op_sel:[0,1,0] op_sel_hi:[1,1,1]
	global_load_dword v119, v[46:47], off
	v_lshl_add_u64 v[46:47], v[46:47], 0, s[86:87]
	ds_read_b128 v[228:231], v24 offset:1664
	ds_read_b128 v[232:235], v24 offset:1680
	ds_read_b128 v[240:243], v24 offset:1696
	ds_read_b128 v[244:247], v24 offset:1712
	s_waitcnt vmcnt(59) lgkmcnt(8)
	v_pk_fma_f32 v[12:13], v[26:27], v[120:121], v[12:13] op_sel_hi:[1,0,1]
	v_pk_fma_f32 v[10:11], v[28:29], v[120:121], v[10:11] op_sel_hi:[1,0,1]
	v_pk_fma_f32 v[16:17], v[30:31], v[120:121], v[16:17] op_sel_hi:[1,0,1]
	v_pk_fma_f32 v[14:15], v[32:33], v[120:121], v[14:15] op_sel_hi:[1,0,1]
	v_pk_fma_f32 v[20:21], v[34:35], v[120:121], v[20:21] op_sel_hi:[1,0,1]
	v_pk_fma_f32 v[18:19], v[36:37], v[120:121], v[18:19] op_sel_hi:[1,0,1]
	v_pk_fma_f32 v[6:7], v[38:39], v[120:121], v[6:7] op_sel_hi:[1,0,1]
	v_pk_fma_f32 v[8:9], v[40:41], v[120:121], v[8:9] op_sel_hi:[1,0,1]
	global_load_dword v120, v[46:47], off offset:-4096
	ds_read_b128 v[26:29], v24 offset:1728
	ds_read_b128 v[30:33], v24 offset:1744
	ds_read_b128 v[34:37], v24 offset:1760
	ds_read_b128 v[38:41], v24 offset:1776
	s_waitcnt vmcnt(59) lgkmcnt(8)
	v_pk_fma_f32 v[12:13], v[48:49], v[120:121], v[12:13] op_sel:[0,1,0] op_sel_hi:[1,1,1]
	v_pk_fma_f32 v[10:11], v[50:51], v[120:121], v[10:11] op_sel:[0,1,0] op_sel_hi:[1,1,1]
	v_pk_fma_f32 v[16:17], v[52:53], v[120:121], v[16:17] op_sel:[0,1,0] op_sel_hi:[1,1,1]
	v_pk_fma_f32 v[14:15], v[54:55], v[120:121], v[14:15] op_sel:[0,1,0] op_sel_hi:[1,1,1]
	v_pk_fma_f32 v[20:21], v[56:57], v[120:121], v[20:21] op_sel:[0,1,0] op_sel_hi:[1,1,1]
	v_pk_fma_f32 v[18:19], v[58:59], v[120:121], v[18:19] op_sel:[0,1,0] op_sel_hi:[1,1,1]
	v_pk_fma_f32 v[6:7], v[60:61], v[120:121], v[6:7] op_sel:[0,1,0] op_sel_hi:[1,1,1]
	v_pk_fma_f32 v[8:9], v[62:63], v[120:121], v[8:9] op_sel:[0,1,0] op_sel_hi:[1,1,1]
	global_load_dword v121, v[46:47], off
	v_lshl_add_u64 v[46:47], v[46:47], 0, s[86:87]
	ds_read_b128 v[48:51], v24 offset:1792
	ds_read_b128 v[52:55], v24 offset:1808
	ds_read_b128 v[56:59], v24 offset:1824
	ds_read_b128 v[60:63], v24 offset:1840
	s_waitcnt vmcnt(59) lgkmcnt(8)
	v_pk_fma_f32 v[12:13], v[228:229], v[122:123], v[12:13] op_sel_hi:[1,0,1]
	v_pk_fma_f32 v[10:11], v[230:231], v[122:123], v[10:11] op_sel_hi:[1,0,1]
	v_pk_fma_f32 v[16:17], v[232:233], v[122:123], v[16:17] op_sel_hi:[1,0,1]
	v_pk_fma_f32 v[14:15], v[234:235], v[122:123], v[14:15] op_sel_hi:[1,0,1]
	v_pk_fma_f32 v[20:21], v[240:241], v[122:123], v[20:21] op_sel_hi:[1,0,1]
	v_pk_fma_f32 v[18:19], v[242:243], v[122:123], v[18:19] op_sel_hi:[1,0,1]
	v_pk_fma_f32 v[6:7], v[244:245], v[122:123], v[6:7] op_sel_hi:[1,0,1]
	v_pk_fma_f32 v[8:9], v[246:247], v[122:123], v[8:9] op_sel_hi:[1,0,1]
	global_load_dword v122, v[46:47], off offset:-4096
	ds_read_b128 v[228:231], v24 offset:1856
	ds_read_b128 v[232:235], v24 offset:1872
	ds_read_b128 v[240:243], v24 offset:1888
	ds_read_b128 v[244:247], v24 offset:1904
	s_waitcnt vmcnt(59) lgkmcnt(8)
	v_pk_fma_f32 v[12:13], v[26:27], v[122:123], v[12:13] op_sel:[0,1,0] op_sel_hi:[1,1,1]
	v_pk_fma_f32 v[10:11], v[28:29], v[122:123], v[10:11] op_sel:[0,1,0] op_sel_hi:[1,1,1]
	v_pk_fma_f32 v[16:17], v[30:31], v[122:123], v[16:17] op_sel:[0,1,0] op_sel_hi:[1,1,1]
	v_pk_fma_f32 v[14:15], v[32:33], v[122:123], v[14:15] op_sel:[0,1,0] op_sel_hi:[1,1,1]
	v_pk_fma_f32 v[20:21], v[34:35], v[122:123], v[20:21] op_sel:[0,1,0] op_sel_hi:[1,1,1]
	v_pk_fma_f32 v[18:19], v[36:37], v[122:123], v[18:19] op_sel:[0,1,0] op_sel_hi:[1,1,1]
	v_pk_fma_f32 v[6:7], v[38:39], v[122:123], v[6:7] op_sel:[0,1,0] op_sel_hi:[1,1,1]
	v_pk_fma_f32 v[8:9], v[40:41], v[122:123], v[8:9] op_sel:[0,1,0] op_sel_hi:[1,1,1]
	global_load_dword v123, v[46:47], off
	v_lshl_add_u64 v[46:47], v[46:47], 0, s[86:87]
	ds_read_b128 v[26:29], v24 offset:1920
	ds_read_b128 v[30:33], v24 offset:1936
	ds_read_b128 v[34:37], v24 offset:1952
	ds_read_b128 v[38:41], v24 offset:1968
	s_waitcnt vmcnt(59) lgkmcnt(8)
	v_pk_fma_f32 v[12:13], v[48:49], v[124:125], v[12:13] op_sel_hi:[1,0,1]
	v_pk_fma_f32 v[10:11], v[50:51], v[124:125], v[10:11] op_sel_hi:[1,0,1]
	v_pk_fma_f32 v[16:17], v[52:53], v[124:125], v[16:17] op_sel_hi:[1,0,1]
	v_pk_fma_f32 v[14:15], v[54:55], v[124:125], v[14:15] op_sel_hi:[1,0,1]
	v_pk_fma_f32 v[20:21], v[56:57], v[124:125], v[20:21] op_sel_hi:[1,0,1]
	v_pk_fma_f32 v[18:19], v[58:59], v[124:125], v[18:19] op_sel_hi:[1,0,1]
	v_pk_fma_f32 v[6:7], v[60:61], v[124:125], v[6:7] op_sel_hi:[1,0,1]
	v_pk_fma_f32 v[8:9], v[62:63], v[124:125], v[8:9] op_sel_hi:[1,0,1]
	global_load_dword v124, v[46:47], off offset:-4096
	ds_read_b128 v[48:51], v24 offset:1984
	ds_read_b128 v[52:55], v24 offset:2000
	ds_read_b128 v[56:59], v24 offset:2016
	ds_read_b128 v[60:63], v24 offset:2032
	s_waitcnt vmcnt(59) lgkmcnt(8)
	v_pk_fma_f32 v[12:13], v[228:229], v[124:125], v[12:13] op_sel:[0,1,0] op_sel_hi:[1,1,1]
	v_pk_fma_f32 v[10:11], v[230:231], v[124:125], v[10:11] op_sel:[0,1,0] op_sel_hi:[1,1,1]
	v_pk_fma_f32 v[16:17], v[232:233], v[124:125], v[16:17] op_sel:[0,1,0] op_sel_hi:[1,1,1]
	v_pk_fma_f32 v[14:15], v[234:235], v[124:125], v[14:15] op_sel:[0,1,0] op_sel_hi:[1,1,1]
	v_pk_fma_f32 v[20:21], v[240:241], v[124:125], v[20:21] op_sel:[0,1,0] op_sel_hi:[1,1,1]
	v_pk_fma_f32 v[18:19], v[242:243], v[124:125], v[18:19] op_sel:[0,1,0] op_sel_hi:[1,1,1]
	v_pk_fma_f32 v[6:7], v[244:245], v[124:125], v[6:7] op_sel:[0,1,0] op_sel_hi:[1,1,1]
	v_pk_fma_f32 v[8:9], v[246:247], v[124:125], v[8:9] op_sel:[0,1,0] op_sel_hi:[1,1,1]
	global_load_dword v125, v[46:47], off
	v_lshl_add_u64 v[46:47], v[46:47], 0, s[86:87]
	ds_read_b128 v[228:231], v24 offset:2048
	ds_read_b128 v[232:235], v24 offset:2064
	ds_read_b128 v[240:243], v24 offset:2080
	ds_read_b128 v[244:247], v24 offset:2096
	s_waitcnt vmcnt(59) lgkmcnt(8)
	v_pk_fma_f32 v[12:13], v[26:27], v[126:127], v[12:13] op_sel_hi:[1,0,1]
	v_pk_fma_f32 v[10:11], v[28:29], v[126:127], v[10:11] op_sel_hi:[1,0,1]
	v_pk_fma_f32 v[16:17], v[30:31], v[126:127], v[16:17] op_sel_hi:[1,0,1]
	v_pk_fma_f32 v[14:15], v[32:33], v[126:127], v[14:15] op_sel_hi:[1,0,1]
	v_pk_fma_f32 v[20:21], v[34:35], v[126:127], v[20:21] op_sel_hi:[1,0,1]
	v_pk_fma_f32 v[18:19], v[36:37], v[126:127], v[18:19] op_sel_hi:[1,0,1]
	v_pk_fma_f32 v[6:7], v[38:39], v[126:127], v[6:7] op_sel_hi:[1,0,1]
	v_pk_fma_f32 v[8:9], v[40:41], v[126:127], v[8:9] op_sel_hi:[1,0,1]
	global_load_dword v126, v[46:47], off offset:-4096
	ds_read_b128 v[26:29], v24 offset:2112
	ds_read_b128 v[30:33], v24 offset:2128
	ds_read_b128 v[34:37], v24 offset:2144
	ds_read_b128 v[38:41], v24 offset:2160
	s_waitcnt vmcnt(59) lgkmcnt(8)
	v_pk_fma_f32 v[12:13], v[48:49], v[126:127], v[12:13] op_sel:[0,1,0] op_sel_hi:[1,1,1]
	v_pk_fma_f32 v[10:11], v[50:51], v[126:127], v[10:11] op_sel:[0,1,0] op_sel_hi:[1,1,1]
	v_pk_fma_f32 v[16:17], v[52:53], v[126:127], v[16:17] op_sel:[0,1,0] op_sel_hi:[1,1,1]
	v_pk_fma_f32 v[14:15], v[54:55], v[126:127], v[14:15] op_sel:[0,1,0] op_sel_hi:[1,1,1]
	v_pk_fma_f32 v[20:21], v[56:57], v[126:127], v[20:21] op_sel:[0,1,0] op_sel_hi:[1,1,1]
	v_pk_fma_f32 v[18:19], v[58:59], v[126:127], v[18:19] op_sel:[0,1,0] op_sel_hi:[1,1,1]
	v_pk_fma_f32 v[6:7], v[60:61], v[126:127], v[6:7] op_sel:[0,1,0] op_sel_hi:[1,1,1]
	v_pk_fma_f32 v[8:9], v[62:63], v[126:127], v[8:9] op_sel:[0,1,0] op_sel_hi:[1,1,1]
	global_load_dword v127, v[46:47], off
	v_lshl_add_u64 v[46:47], v[46:47], 0, s[86:87]
	ds_read_b128 v[48:51], v24 offset:2176
	ds_read_b128 v[52:55], v24 offset:2192
	ds_read_b128 v[56:59], v24 offset:2208
	ds_read_b128 v[60:63], v24 offset:2224
	s_waitcnt vmcnt(59) lgkmcnt(8)
	v_pk_fma_f32 v[12:13], v[228:229], v[128:129], v[12:13] op_sel_hi:[1,0,1]
	v_pk_fma_f32 v[10:11], v[230:231], v[128:129], v[10:11] op_sel_hi:[1,0,1]
	v_pk_fma_f32 v[16:17], v[232:233], v[128:129], v[16:17] op_sel_hi:[1,0,1]
	v_pk_fma_f32 v[14:15], v[234:235], v[128:129], v[14:15] op_sel_hi:[1,0,1]
	v_pk_fma_f32 v[20:21], v[240:241], v[128:129], v[20:21] op_sel_hi:[1,0,1]
	v_pk_fma_f32 v[18:19], v[242:243], v[128:129], v[18:19] op_sel_hi:[1,0,1]
	v_pk_fma_f32 v[6:7], v[244:245], v[128:129], v[6:7] op_sel_hi:[1,0,1]
	v_pk_fma_f32 v[8:9], v[246:247], v[128:129], v[8:9] op_sel_hi:[1,0,1]
	global_load_dword v128, v[46:47], off offset:-4096
	ds_read_b128 v[228:231], v24 offset:2240
	ds_read_b128 v[232:235], v24 offset:2256
	ds_read_b128 v[240:243], v24 offset:2272
	ds_read_b128 v[244:247], v24 offset:2288
	s_waitcnt vmcnt(59) lgkmcnt(8)
	v_pk_fma_f32 v[12:13], v[26:27], v[128:129], v[12:13] op_sel:[0,1,0] op_sel_hi:[1,1,1]
	v_pk_fma_f32 v[10:11], v[28:29], v[128:129], v[10:11] op_sel:[0,1,0] op_sel_hi:[1,1,1]
	v_pk_fma_f32 v[16:17], v[30:31], v[128:129], v[16:17] op_sel:[0,1,0] op_sel_hi:[1,1,1]
	v_pk_fma_f32 v[14:15], v[32:33], v[128:129], v[14:15] op_sel:[0,1,0] op_sel_hi:[1,1,1]
	v_pk_fma_f32 v[20:21], v[34:35], v[128:129], v[20:21] op_sel:[0,1,0] op_sel_hi:[1,1,1]
	v_pk_fma_f32 v[18:19], v[36:37], v[128:129], v[18:19] op_sel:[0,1,0] op_sel_hi:[1,1,1]
	v_pk_fma_f32 v[6:7], v[38:39], v[128:129], v[6:7] op_sel:[0,1,0] op_sel_hi:[1,1,1]
	v_pk_fma_f32 v[8:9], v[40:41], v[128:129], v[8:9] op_sel:[0,1,0] op_sel_hi:[1,1,1]
	global_load_dword v129, v[46:47], off
	v_lshl_add_u64 v[46:47], v[46:47], 0, s[86:87]
	ds_read_b128 v[26:29], v24 offset:2304
	ds_read_b128 v[30:33], v24 offset:2320
	ds_read_b128 v[34:37], v24 offset:2336
	ds_read_b128 v[38:41], v24 offset:2352
	s_waitcnt vmcnt(59) lgkmcnt(8)
	v_pk_fma_f32 v[12:13], v[48:49], v[130:131], v[12:13] op_sel_hi:[1,0,1]
	v_pk_fma_f32 v[10:11], v[50:51], v[130:131], v[10:11] op_sel_hi:[1,0,1]
	v_pk_fma_f32 v[16:17], v[52:53], v[130:131], v[16:17] op_sel_hi:[1,0,1]
	v_pk_fma_f32 v[14:15], v[54:55], v[130:131], v[14:15] op_sel_hi:[1,0,1]
	v_pk_fma_f32 v[20:21], v[56:57], v[130:131], v[20:21] op_sel_hi:[1,0,1]
	v_pk_fma_f32 v[18:19], v[58:59], v[130:131], v[18:19] op_sel_hi:[1,0,1]
	v_pk_fma_f32 v[6:7], v[60:61], v[130:131], v[6:7] op_sel_hi:[1,0,1]
	v_pk_fma_f32 v[8:9], v[62:63], v[130:131], v[8:9] op_sel_hi:[1,0,1]
	global_load_dword v130, v[46:47], off offset:-4096
	ds_read_b128 v[48:51], v24 offset:2368
	ds_read_b128 v[52:55], v24 offset:2384
	ds_read_b128 v[56:59], v24 offset:2400
	ds_read_b128 v[60:63], v24 offset:2416
	s_waitcnt vmcnt(59) lgkmcnt(8)
	v_pk_fma_f32 v[12:13], v[228:229], v[130:131], v[12:13] op_sel:[0,1,0] op_sel_hi:[1,1,1]
	v_pk_fma_f32 v[10:11], v[230:231], v[130:131], v[10:11] op_sel:[0,1,0] op_sel_hi:[1,1,1]
	v_pk_fma_f32 v[16:17], v[232:233], v[130:131], v[16:17] op_sel:[0,1,0] op_sel_hi:[1,1,1]
	v_pk_fma_f32 v[14:15], v[234:235], v[130:131], v[14:15] op_sel:[0,1,0] op_sel_hi:[1,1,1]
	v_pk_fma_f32 v[20:21], v[240:241], v[130:131], v[20:21] op_sel:[0,1,0] op_sel_hi:[1,1,1]
	v_pk_fma_f32 v[18:19], v[242:243], v[130:131], v[18:19] op_sel:[0,1,0] op_sel_hi:[1,1,1]
	v_pk_fma_f32 v[6:7], v[244:245], v[130:131], v[6:7] op_sel:[0,1,0] op_sel_hi:[1,1,1]
	v_pk_fma_f32 v[8:9], v[246:247], v[130:131], v[8:9] op_sel:[0,1,0] op_sel_hi:[1,1,1]
	global_load_dword v131, v[46:47], off
	v_lshl_add_u64 v[46:47], v[46:47], 0, s[86:87]
	ds_read_b128 v[228:231], v24 offset:2432
	ds_read_b128 v[232:235], v24 offset:2448
	ds_read_b128 v[240:243], v24 offset:2464
	ds_read_b128 v[244:247], v24 offset:2480
	s_waitcnt vmcnt(59) lgkmcnt(8)
	v_pk_fma_f32 v[12:13], v[26:27], v[132:133], v[12:13] op_sel_hi:[1,0,1]
	v_pk_fma_f32 v[10:11], v[28:29], v[132:133], v[10:11] op_sel_hi:[1,0,1]
	v_pk_fma_f32 v[16:17], v[30:31], v[132:133], v[16:17] op_sel_hi:[1,0,1]
	v_pk_fma_f32 v[14:15], v[32:33], v[132:133], v[14:15] op_sel_hi:[1,0,1]
	v_pk_fma_f32 v[20:21], v[34:35], v[132:133], v[20:21] op_sel_hi:[1,0,1]
	v_pk_fma_f32 v[18:19], v[36:37], v[132:133], v[18:19] op_sel_hi:[1,0,1]
	v_pk_fma_f32 v[6:7], v[38:39], v[132:133], v[6:7] op_sel_hi:[1,0,1]
	v_pk_fma_f32 v[8:9], v[40:41], v[132:133], v[8:9] op_sel_hi:[1,0,1]
	global_load_dword v132, v[46:47], off offset:-4096
	ds_read_b128 v[26:29], v24 offset:2496
	ds_read_b128 v[30:33], v24 offset:2512
	ds_read_b128 v[34:37], v24 offset:2528
	ds_read_b128 v[38:41], v24 offset:2544
	s_waitcnt vmcnt(59) lgkmcnt(8)
	v_pk_fma_f32 v[12:13], v[48:49], v[132:133], v[12:13] op_sel:[0,1,0] op_sel_hi:[1,1,1]
	v_pk_fma_f32 v[10:11], v[50:51], v[132:133], v[10:11] op_sel:[0,1,0] op_sel_hi:[1,1,1]
	v_pk_fma_f32 v[16:17], v[52:53], v[132:133], v[16:17] op_sel:[0,1,0] op_sel_hi:[1,1,1]
	v_pk_fma_f32 v[14:15], v[54:55], v[132:133], v[14:15] op_sel:[0,1,0] op_sel_hi:[1,1,1]
	v_pk_fma_f32 v[20:21], v[56:57], v[132:133], v[20:21] op_sel:[0,1,0] op_sel_hi:[1,1,1]
	v_pk_fma_f32 v[18:19], v[58:59], v[132:133], v[18:19] op_sel:[0,1,0] op_sel_hi:[1,1,1]
	v_pk_fma_f32 v[6:7], v[60:61], v[132:133], v[6:7] op_sel:[0,1,0] op_sel_hi:[1,1,1]
	v_pk_fma_f32 v[8:9], v[62:63], v[132:133], v[8:9] op_sel:[0,1,0] op_sel_hi:[1,1,1]
	global_load_dword v133, v[46:47], off
	v_lshl_add_u64 v[46:47], v[46:47], 0, s[86:87]
	ds_read_b128 v[48:51], v24 offset:2560
	ds_read_b128 v[52:55], v24 offset:2576
	ds_read_b128 v[56:59], v24 offset:2592
	ds_read_b128 v[60:63], v24 offset:2608
	s_waitcnt vmcnt(59) lgkmcnt(8)
	v_pk_fma_f32 v[12:13], v[228:229], v[134:135], v[12:13] op_sel_hi:[1,0,1]
	v_pk_fma_f32 v[10:11], v[230:231], v[134:135], v[10:11] op_sel_hi:[1,0,1]
	v_pk_fma_f32 v[16:17], v[232:233], v[134:135], v[16:17] op_sel_hi:[1,0,1]
	v_pk_fma_f32 v[14:15], v[234:235], v[134:135], v[14:15] op_sel_hi:[1,0,1]
	v_pk_fma_f32 v[20:21], v[240:241], v[134:135], v[20:21] op_sel_hi:[1,0,1]
	v_pk_fma_f32 v[18:19], v[242:243], v[134:135], v[18:19] op_sel_hi:[1,0,1]
	v_pk_fma_f32 v[6:7], v[244:245], v[134:135], v[6:7] op_sel_hi:[1,0,1]
	v_pk_fma_f32 v[8:9], v[246:247], v[134:135], v[8:9] op_sel_hi:[1,0,1]
	global_load_dword v134, v[46:47], off offset:-4096
	ds_read_b128 v[228:231], v24 offset:2624
	ds_read_b128 v[232:235], v24 offset:2640
	ds_read_b128 v[240:243], v24 offset:2656
	ds_read_b128 v[244:247], v24 offset:2672
	s_waitcnt vmcnt(59) lgkmcnt(8)
	v_pk_fma_f32 v[12:13], v[26:27], v[134:135], v[12:13] op_sel:[0,1,0] op_sel_hi:[1,1,1]
	v_pk_fma_f32 v[10:11], v[28:29], v[134:135], v[10:11] op_sel:[0,1,0] op_sel_hi:[1,1,1]
	v_pk_fma_f32 v[16:17], v[30:31], v[134:135], v[16:17] op_sel:[0,1,0] op_sel_hi:[1,1,1]
	v_pk_fma_f32 v[14:15], v[32:33], v[134:135], v[14:15] op_sel:[0,1,0] op_sel_hi:[1,1,1]
	v_pk_fma_f32 v[20:21], v[34:35], v[134:135], v[20:21] op_sel:[0,1,0] op_sel_hi:[1,1,1]
	v_pk_fma_f32 v[18:19], v[36:37], v[134:135], v[18:19] op_sel:[0,1,0] op_sel_hi:[1,1,1]
	v_pk_fma_f32 v[6:7], v[38:39], v[134:135], v[6:7] op_sel:[0,1,0] op_sel_hi:[1,1,1]
	v_pk_fma_f32 v[8:9], v[40:41], v[134:135], v[8:9] op_sel:[0,1,0] op_sel_hi:[1,1,1]
	global_load_dword v135, v[46:47], off
	v_lshl_add_u64 v[46:47], v[46:47], 0, s[86:87]
	ds_read_b128 v[26:29], v24 offset:2688
	ds_read_b128 v[30:33], v24 offset:2704
	ds_read_b128 v[34:37], v24 offset:2720
	ds_read_b128 v[38:41], v24 offset:2736
	s_waitcnt vmcnt(59) lgkmcnt(8)
	v_pk_fma_f32 v[12:13], v[48:49], v[136:137], v[12:13] op_sel_hi:[1,0,1]
	v_pk_fma_f32 v[10:11], v[50:51], v[136:137], v[10:11] op_sel_hi:[1,0,1]
	v_pk_fma_f32 v[16:17], v[52:53], v[136:137], v[16:17] op_sel_hi:[1,0,1]
	v_pk_fma_f32 v[14:15], v[54:55], v[136:137], v[14:15] op_sel_hi:[1,0,1]
	v_pk_fma_f32 v[20:21], v[56:57], v[136:137], v[20:21] op_sel_hi:[1,0,1]
	v_pk_fma_f32 v[18:19], v[58:59], v[136:137], v[18:19] op_sel_hi:[1,0,1]
	v_pk_fma_f32 v[6:7], v[60:61], v[136:137], v[6:7] op_sel_hi:[1,0,1]
	v_pk_fma_f32 v[8:9], v[62:63], v[136:137], v[8:9] op_sel_hi:[1,0,1]
	global_load_dword v136, v[46:47], off offset:-4096
	ds_read_b128 v[48:51], v24 offset:2752
	ds_read_b128 v[52:55], v24 offset:2768
	ds_read_b128 v[56:59], v24 offset:2784
	ds_read_b128 v[60:63], v24 offset:2800
	s_waitcnt vmcnt(59) lgkmcnt(8)
	v_pk_fma_f32 v[12:13], v[228:229], v[136:137], v[12:13] op_sel:[0,1,0] op_sel_hi:[1,1,1]
	v_pk_fma_f32 v[10:11], v[230:231], v[136:137], v[10:11] op_sel:[0,1,0] op_sel_hi:[1,1,1]
	v_pk_fma_f32 v[16:17], v[232:233], v[136:137], v[16:17] op_sel:[0,1,0] op_sel_hi:[1,1,1]
	v_pk_fma_f32 v[14:15], v[234:235], v[136:137], v[14:15] op_sel:[0,1,0] op_sel_hi:[1,1,1]
	v_pk_fma_f32 v[20:21], v[240:241], v[136:137], v[20:21] op_sel:[0,1,0] op_sel_hi:[1,1,1]
	v_pk_fma_f32 v[18:19], v[242:243], v[136:137], v[18:19] op_sel:[0,1,0] op_sel_hi:[1,1,1]
	v_pk_fma_f32 v[6:7], v[244:245], v[136:137], v[6:7] op_sel:[0,1,0] op_sel_hi:[1,1,1]
	v_pk_fma_f32 v[8:9], v[246:247], v[136:137], v[8:9] op_sel:[0,1,0] op_sel_hi:[1,1,1]
	global_load_dword v137, v[46:47], off
	v_lshl_add_u64 v[46:47], v[46:47], 0, s[86:87]
	ds_read_b128 v[228:231], v24 offset:2816
	ds_read_b128 v[232:235], v24 offset:2832
	ds_read_b128 v[240:243], v24 offset:2848
	ds_read_b128 v[244:247], v24 offset:2864
	s_waitcnt vmcnt(59) lgkmcnt(8)
	v_pk_fma_f32 v[12:13], v[26:27], v[138:139], v[12:13] op_sel_hi:[1,0,1]
	v_pk_fma_f32 v[10:11], v[28:29], v[138:139], v[10:11] op_sel_hi:[1,0,1]
	v_pk_fma_f32 v[16:17], v[30:31], v[138:139], v[16:17] op_sel_hi:[1,0,1]
	v_pk_fma_f32 v[14:15], v[32:33], v[138:139], v[14:15] op_sel_hi:[1,0,1]
	v_pk_fma_f32 v[20:21], v[34:35], v[138:139], v[20:21] op_sel_hi:[1,0,1]
	v_pk_fma_f32 v[18:19], v[36:37], v[138:139], v[18:19] op_sel_hi:[1,0,1]
	v_pk_fma_f32 v[6:7], v[38:39], v[138:139], v[6:7] op_sel_hi:[1,0,1]
	v_pk_fma_f32 v[8:9], v[40:41], v[138:139], v[8:9] op_sel_hi:[1,0,1]
	global_load_dword v138, v[46:47], off offset:-4096
	ds_read_b128 v[26:29], v24 offset:2880
	ds_read_b128 v[30:33], v24 offset:2896
	ds_read_b128 v[34:37], v24 offset:2912
	ds_read_b128 v[38:41], v24 offset:2928
	s_waitcnt vmcnt(59) lgkmcnt(8)
	v_pk_fma_f32 v[12:13], v[48:49], v[138:139], v[12:13] op_sel:[0,1,0] op_sel_hi:[1,1,1]
	v_pk_fma_f32 v[10:11], v[50:51], v[138:139], v[10:11] op_sel:[0,1,0] op_sel_hi:[1,1,1]
	v_pk_fma_f32 v[16:17], v[52:53], v[138:139], v[16:17] op_sel:[0,1,0] op_sel_hi:[1,1,1]
	v_pk_fma_f32 v[14:15], v[54:55], v[138:139], v[14:15] op_sel:[0,1,0] op_sel_hi:[1,1,1]
	v_pk_fma_f32 v[20:21], v[56:57], v[138:139], v[20:21] op_sel:[0,1,0] op_sel_hi:[1,1,1]
	v_pk_fma_f32 v[18:19], v[58:59], v[138:139], v[18:19] op_sel:[0,1,0] op_sel_hi:[1,1,1]
	v_pk_fma_f32 v[6:7], v[60:61], v[138:139], v[6:7] op_sel:[0,1,0] op_sel_hi:[1,1,1]
	v_pk_fma_f32 v[8:9], v[62:63], v[138:139], v[8:9] op_sel:[0,1,0] op_sel_hi:[1,1,1]
	global_load_dword v139, v[46:47], off
	v_lshl_add_u64 v[46:47], v[46:47], 0, s[86:87]
	ds_read_b128 v[48:51], v24 offset:2944
	ds_read_b128 v[52:55], v24 offset:2960
	ds_read_b128 v[56:59], v24 offset:2976
	ds_read_b128 v[60:63], v24 offset:2992
	s_waitcnt vmcnt(59) lgkmcnt(8)
	v_pk_fma_f32 v[12:13], v[228:229], v[140:141], v[12:13] op_sel_hi:[1,0,1]
	v_pk_fma_f32 v[10:11], v[230:231], v[140:141], v[10:11] op_sel_hi:[1,0,1]
	v_pk_fma_f32 v[16:17], v[232:233], v[140:141], v[16:17] op_sel_hi:[1,0,1]
	v_pk_fma_f32 v[14:15], v[234:235], v[140:141], v[14:15] op_sel_hi:[1,0,1]
	v_pk_fma_f32 v[20:21], v[240:241], v[140:141], v[20:21] op_sel_hi:[1,0,1]
	v_pk_fma_f32 v[18:19], v[242:243], v[140:141], v[18:19] op_sel_hi:[1,0,1]
	v_pk_fma_f32 v[6:7], v[244:245], v[140:141], v[6:7] op_sel_hi:[1,0,1]
	v_pk_fma_f32 v[8:9], v[246:247], v[140:141], v[8:9] op_sel_hi:[1,0,1]
	global_load_dword v140, v[46:47], off offset:-4096
	ds_read_b128 v[228:231], v24 offset:3008
	ds_read_b128 v[232:235], v24 offset:3024
	ds_read_b128 v[240:243], v24 offset:3040
	ds_read_b128 v[244:247], v24 offset:3056
	s_waitcnt vmcnt(59) lgkmcnt(8)
	v_pk_fma_f32 v[12:13], v[26:27], v[140:141], v[12:13] op_sel:[0,1,0] op_sel_hi:[1,1,1]
	v_pk_fma_f32 v[10:11], v[28:29], v[140:141], v[10:11] op_sel:[0,1,0] op_sel_hi:[1,1,1]
	v_pk_fma_f32 v[16:17], v[30:31], v[140:141], v[16:17] op_sel:[0,1,0] op_sel_hi:[1,1,1]
	v_pk_fma_f32 v[14:15], v[32:33], v[140:141], v[14:15] op_sel:[0,1,0] op_sel_hi:[1,1,1]
	v_pk_fma_f32 v[20:21], v[34:35], v[140:141], v[20:21] op_sel:[0,1,0] op_sel_hi:[1,1,1]
	v_pk_fma_f32 v[18:19], v[36:37], v[140:141], v[18:19] op_sel:[0,1,0] op_sel_hi:[1,1,1]
	v_pk_fma_f32 v[6:7], v[38:39], v[140:141], v[6:7] op_sel:[0,1,0] op_sel_hi:[1,1,1]
	v_pk_fma_f32 v[8:9], v[40:41], v[140:141], v[8:9] op_sel:[0,1,0] op_sel_hi:[1,1,1]
	global_load_dword v141, v[46:47], off
	v_lshl_add_u64 v[46:47], v[46:47], 0, s[86:87]
	ds_read_b128 v[26:29], v24 offset:3072
	ds_read_b128 v[30:33], v24 offset:3088
	ds_read_b128 v[34:37], v24 offset:3104
	ds_read_b128 v[38:41], v24 offset:3120
	s_waitcnt vmcnt(59) lgkmcnt(8)
	v_pk_fma_f32 v[12:13], v[48:49], v[142:143], v[12:13] op_sel_hi:[1,0,1]
	v_pk_fma_f32 v[10:11], v[50:51], v[142:143], v[10:11] op_sel_hi:[1,0,1]
	v_pk_fma_f32 v[16:17], v[52:53], v[142:143], v[16:17] op_sel_hi:[1,0,1]
	v_pk_fma_f32 v[14:15], v[54:55], v[142:143], v[14:15] op_sel_hi:[1,0,1]
	v_pk_fma_f32 v[20:21], v[56:57], v[142:143], v[20:21] op_sel_hi:[1,0,1]
	v_pk_fma_f32 v[18:19], v[58:59], v[142:143], v[18:19] op_sel_hi:[1,0,1]
	v_pk_fma_f32 v[6:7], v[60:61], v[142:143], v[6:7] op_sel_hi:[1,0,1]
	v_pk_fma_f32 v[8:9], v[62:63], v[142:143], v[8:9] op_sel_hi:[1,0,1]
	global_load_dword v142, v[46:47], off offset:-4096
	ds_read_b128 v[48:51], v24 offset:3136
	ds_read_b128 v[52:55], v24 offset:3152
	ds_read_b128 v[56:59], v24 offset:3168
	ds_read_b128 v[60:63], v24 offset:3184
	s_waitcnt vmcnt(59) lgkmcnt(8)
	v_pk_fma_f32 v[12:13], v[228:229], v[142:143], v[12:13] op_sel:[0,1,0] op_sel_hi:[1,1,1]
	v_pk_fma_f32 v[10:11], v[230:231], v[142:143], v[10:11] op_sel:[0,1,0] op_sel_hi:[1,1,1]
	v_pk_fma_f32 v[16:17], v[232:233], v[142:143], v[16:17] op_sel:[0,1,0] op_sel_hi:[1,1,1]
	v_pk_fma_f32 v[14:15], v[234:235], v[142:143], v[14:15] op_sel:[0,1,0] op_sel_hi:[1,1,1]
	v_pk_fma_f32 v[20:21], v[240:241], v[142:143], v[20:21] op_sel:[0,1,0] op_sel_hi:[1,1,1]
	v_pk_fma_f32 v[18:19], v[242:243], v[142:143], v[18:19] op_sel:[0,1,0] op_sel_hi:[1,1,1]
	v_pk_fma_f32 v[6:7], v[244:245], v[142:143], v[6:7] op_sel:[0,1,0] op_sel_hi:[1,1,1]
	v_pk_fma_f32 v[8:9], v[246:247], v[142:143], v[8:9] op_sel:[0,1,0] op_sel_hi:[1,1,1]
	global_load_dword v143, v[46:47], off
	v_lshl_add_u64 v[46:47], v[46:47], 0, s[86:87]
	ds_read_b128 v[228:231], v24 offset:3200
	ds_read_b128 v[232:235], v24 offset:3216
	ds_read_b128 v[240:243], v24 offset:3232
	ds_read_b128 v[244:247], v24 offset:3248
	s_waitcnt vmcnt(59) lgkmcnt(8)
	v_pk_fma_f32 v[12:13], v[26:27], v[144:145], v[12:13] op_sel_hi:[1,0,1]
	v_pk_fma_f32 v[10:11], v[28:29], v[144:145], v[10:11] op_sel_hi:[1,0,1]
	v_pk_fma_f32 v[16:17], v[30:31], v[144:145], v[16:17] op_sel_hi:[1,0,1]
	v_pk_fma_f32 v[14:15], v[32:33], v[144:145], v[14:15] op_sel_hi:[1,0,1]
	v_pk_fma_f32 v[20:21], v[34:35], v[144:145], v[20:21] op_sel_hi:[1,0,1]
	v_pk_fma_f32 v[18:19], v[36:37], v[144:145], v[18:19] op_sel_hi:[1,0,1]
	v_pk_fma_f32 v[6:7], v[38:39], v[144:145], v[6:7] op_sel_hi:[1,0,1]
	v_pk_fma_f32 v[8:9], v[40:41], v[144:145], v[8:9] op_sel_hi:[1,0,1]
	global_load_dword v144, v[46:47], off offset:-4096
	ds_read_b128 v[26:29], v24 offset:3264
	ds_read_b128 v[30:33], v24 offset:3280
	ds_read_b128 v[34:37], v24 offset:3296
	ds_read_b128 v[38:41], v24 offset:3312
	s_waitcnt vmcnt(59) lgkmcnt(8)
	v_pk_fma_f32 v[12:13], v[48:49], v[144:145], v[12:13] op_sel:[0,1,0] op_sel_hi:[1,1,1]
	v_pk_fma_f32 v[10:11], v[50:51], v[144:145], v[10:11] op_sel:[0,1,0] op_sel_hi:[1,1,1]
	v_pk_fma_f32 v[16:17], v[52:53], v[144:145], v[16:17] op_sel:[0,1,0] op_sel_hi:[1,1,1]
	v_pk_fma_f32 v[14:15], v[54:55], v[144:145], v[14:15] op_sel:[0,1,0] op_sel_hi:[1,1,1]
	v_pk_fma_f32 v[20:21], v[56:57], v[144:145], v[20:21] op_sel:[0,1,0] op_sel_hi:[1,1,1]
	v_pk_fma_f32 v[18:19], v[58:59], v[144:145], v[18:19] op_sel:[0,1,0] op_sel_hi:[1,1,1]
	v_pk_fma_f32 v[6:7], v[60:61], v[144:145], v[6:7] op_sel:[0,1,0] op_sel_hi:[1,1,1]
	v_pk_fma_f32 v[8:9], v[62:63], v[144:145], v[8:9] op_sel:[0,1,0] op_sel_hi:[1,1,1]
	global_load_dword v145, v[46:47], off
	v_lshl_add_u64 v[46:47], v[46:47], 0, s[86:87]
	ds_read_b128 v[48:51], v24 offset:3328
	ds_read_b128 v[52:55], v24 offset:3344
	ds_read_b128 v[56:59], v24 offset:3360
	ds_read_b128 v[60:63], v24 offset:3376
	s_waitcnt vmcnt(59) lgkmcnt(8)
	v_pk_fma_f32 v[12:13], v[228:229], v[146:147], v[12:13] op_sel_hi:[1,0,1]
	v_pk_fma_f32 v[10:11], v[230:231], v[146:147], v[10:11] op_sel_hi:[1,0,1]
	v_pk_fma_f32 v[16:17], v[232:233], v[146:147], v[16:17] op_sel_hi:[1,0,1]
	v_pk_fma_f32 v[14:15], v[234:235], v[146:147], v[14:15] op_sel_hi:[1,0,1]
	v_pk_fma_f32 v[20:21], v[240:241], v[146:147], v[20:21] op_sel_hi:[1,0,1]
	v_pk_fma_f32 v[18:19], v[242:243], v[146:147], v[18:19] op_sel_hi:[1,0,1]
	v_pk_fma_f32 v[6:7], v[244:245], v[146:147], v[6:7] op_sel_hi:[1,0,1]
	v_pk_fma_f32 v[8:9], v[246:247], v[146:147], v[8:9] op_sel_hi:[1,0,1]
	global_load_dword v146, v[46:47], off offset:-4096
	ds_read_b128 v[228:231], v24 offset:3392
	ds_read_b128 v[232:235], v24 offset:3408
	ds_read_b128 v[240:243], v24 offset:3424
	ds_read_b128 v[244:247], v24 offset:3440
	s_waitcnt vmcnt(59) lgkmcnt(8)
	v_pk_fma_f32 v[12:13], v[26:27], v[146:147], v[12:13] op_sel:[0,1,0] op_sel_hi:[1,1,1]
	v_pk_fma_f32 v[10:11], v[28:29], v[146:147], v[10:11] op_sel:[0,1,0] op_sel_hi:[1,1,1]
	v_pk_fma_f32 v[16:17], v[30:31], v[146:147], v[16:17] op_sel:[0,1,0] op_sel_hi:[1,1,1]
	v_pk_fma_f32 v[14:15], v[32:33], v[146:147], v[14:15] op_sel:[0,1,0] op_sel_hi:[1,1,1]
	v_pk_fma_f32 v[20:21], v[34:35], v[146:147], v[20:21] op_sel:[0,1,0] op_sel_hi:[1,1,1]
	v_pk_fma_f32 v[18:19], v[36:37], v[146:147], v[18:19] op_sel:[0,1,0] op_sel_hi:[1,1,1]
	v_pk_fma_f32 v[6:7], v[38:39], v[146:147], v[6:7] op_sel:[0,1,0] op_sel_hi:[1,1,1]
	v_pk_fma_f32 v[8:9], v[40:41], v[146:147], v[8:9] op_sel:[0,1,0] op_sel_hi:[1,1,1]
	global_load_dword v147, v[46:47], off
	v_lshl_add_u64 v[46:47], v[46:47], 0, s[86:87]
	ds_read_b128 v[26:29], v24 offset:3456
	ds_read_b128 v[30:33], v24 offset:3472
	ds_read_b128 v[34:37], v24 offset:3488
	ds_read_b128 v[38:41], v24 offset:3504
	s_waitcnt vmcnt(59) lgkmcnt(8)
	v_pk_fma_f32 v[12:13], v[48:49], v[148:149], v[12:13] op_sel_hi:[1,0,1]
	v_pk_fma_f32 v[10:11], v[50:51], v[148:149], v[10:11] op_sel_hi:[1,0,1]
	v_pk_fma_f32 v[16:17], v[52:53], v[148:149], v[16:17] op_sel_hi:[1,0,1]
	v_pk_fma_f32 v[14:15], v[54:55], v[148:149], v[14:15] op_sel_hi:[1,0,1]
	v_pk_fma_f32 v[20:21], v[56:57], v[148:149], v[20:21] op_sel_hi:[1,0,1]
	v_pk_fma_f32 v[18:19], v[58:59], v[148:149], v[18:19] op_sel_hi:[1,0,1]
	v_pk_fma_f32 v[6:7], v[60:61], v[148:149], v[6:7] op_sel_hi:[1,0,1]
	v_pk_fma_f32 v[8:9], v[62:63], v[148:149], v[8:9] op_sel_hi:[1,0,1]
	global_load_dword v148, v[46:47], off offset:-4096
	ds_read_b128 v[48:51], v24 offset:3520
	ds_read_b128 v[52:55], v24 offset:3536
	ds_read_b128 v[56:59], v24 offset:3552
	ds_read_b128 v[60:63], v24 offset:3568
	s_waitcnt vmcnt(59) lgkmcnt(8)
	v_pk_fma_f32 v[12:13], v[228:229], v[148:149], v[12:13] op_sel:[0,1,0] op_sel_hi:[1,1,1]
	v_pk_fma_f32 v[10:11], v[230:231], v[148:149], v[10:11] op_sel:[0,1,0] op_sel_hi:[1,1,1]
	v_pk_fma_f32 v[16:17], v[232:233], v[148:149], v[16:17] op_sel:[0,1,0] op_sel_hi:[1,1,1]
	v_pk_fma_f32 v[14:15], v[234:235], v[148:149], v[14:15] op_sel:[0,1,0] op_sel_hi:[1,1,1]
	v_pk_fma_f32 v[20:21], v[240:241], v[148:149], v[20:21] op_sel:[0,1,0] op_sel_hi:[1,1,1]
	v_pk_fma_f32 v[18:19], v[242:243], v[148:149], v[18:19] op_sel:[0,1,0] op_sel_hi:[1,1,1]
	v_pk_fma_f32 v[6:7], v[244:245], v[148:149], v[6:7] op_sel:[0,1,0] op_sel_hi:[1,1,1]
	v_pk_fma_f32 v[8:9], v[246:247], v[148:149], v[8:9] op_sel:[0,1,0] op_sel_hi:[1,1,1]
	global_load_dword v149, v[46:47], off
	v_lshl_add_u64 v[46:47], v[46:47], 0, s[86:87]
	ds_read_b128 v[228:231], v24 offset:3584
	ds_read_b128 v[232:235], v24 offset:3600
	ds_read_b128 v[240:243], v24 offset:3616
	ds_read_b128 v[244:247], v24 offset:3632
	s_waitcnt vmcnt(59) lgkmcnt(8)
	v_pk_fma_f32 v[12:13], v[26:27], v[150:151], v[12:13] op_sel_hi:[1,0,1]
	v_pk_fma_f32 v[10:11], v[28:29], v[150:151], v[10:11] op_sel_hi:[1,0,1]
	v_pk_fma_f32 v[16:17], v[30:31], v[150:151], v[16:17] op_sel_hi:[1,0,1]
	v_pk_fma_f32 v[14:15], v[32:33], v[150:151], v[14:15] op_sel_hi:[1,0,1]
	v_pk_fma_f32 v[20:21], v[34:35], v[150:151], v[20:21] op_sel_hi:[1,0,1]
	v_pk_fma_f32 v[18:19], v[36:37], v[150:151], v[18:19] op_sel_hi:[1,0,1]
	v_pk_fma_f32 v[6:7], v[38:39], v[150:151], v[6:7] op_sel_hi:[1,0,1]
	v_pk_fma_f32 v[8:9], v[40:41], v[150:151], v[8:9] op_sel_hi:[1,0,1]
	global_load_dword v150, v[46:47], off offset:-4096
	ds_read_b128 v[26:29], v24 offset:3648
	ds_read_b128 v[30:33], v24 offset:3664
	ds_read_b128 v[34:37], v24 offset:3680
	ds_read_b128 v[38:41], v24 offset:3696
	s_waitcnt vmcnt(59) lgkmcnt(8)
	v_pk_fma_f32 v[12:13], v[48:49], v[150:151], v[12:13] op_sel:[0,1,0] op_sel_hi:[1,1,1]
	v_pk_fma_f32 v[10:11], v[50:51], v[150:151], v[10:11] op_sel:[0,1,0] op_sel_hi:[1,1,1]
	v_pk_fma_f32 v[16:17], v[52:53], v[150:151], v[16:17] op_sel:[0,1,0] op_sel_hi:[1,1,1]
	v_pk_fma_f32 v[14:15], v[54:55], v[150:151], v[14:15] op_sel:[0,1,0] op_sel_hi:[1,1,1]
	v_pk_fma_f32 v[20:21], v[56:57], v[150:151], v[20:21] op_sel:[0,1,0] op_sel_hi:[1,1,1]
	v_pk_fma_f32 v[18:19], v[58:59], v[150:151], v[18:19] op_sel:[0,1,0] op_sel_hi:[1,1,1]
	v_pk_fma_f32 v[6:7], v[60:61], v[150:151], v[6:7] op_sel:[0,1,0] op_sel_hi:[1,1,1]
	v_pk_fma_f32 v[8:9], v[62:63], v[150:151], v[8:9] op_sel:[0,1,0] op_sel_hi:[1,1,1]
	global_load_dword v151, v[46:47], off
	v_lshl_add_u64 v[46:47], v[46:47], 0, s[86:87]
	ds_read_b128 v[48:51], v24 offset:3712
	ds_read_b128 v[52:55], v24 offset:3728
	ds_read_b128 v[56:59], v24 offset:3744
	ds_read_b128 v[60:63], v24 offset:3760
	s_waitcnt vmcnt(59) lgkmcnt(8)
	v_pk_fma_f32 v[12:13], v[228:229], v[152:153], v[12:13] op_sel_hi:[1,0,1]
	v_pk_fma_f32 v[10:11], v[230:231], v[152:153], v[10:11] op_sel_hi:[1,0,1]
	v_pk_fma_f32 v[16:17], v[232:233], v[152:153], v[16:17] op_sel_hi:[1,0,1]
	v_pk_fma_f32 v[14:15], v[234:235], v[152:153], v[14:15] op_sel_hi:[1,0,1]
	v_pk_fma_f32 v[20:21], v[240:241], v[152:153], v[20:21] op_sel_hi:[1,0,1]
	v_pk_fma_f32 v[18:19], v[242:243], v[152:153], v[18:19] op_sel_hi:[1,0,1]
	v_pk_fma_f32 v[6:7], v[244:245], v[152:153], v[6:7] op_sel_hi:[1,0,1]
	v_pk_fma_f32 v[8:9], v[246:247], v[152:153], v[8:9] op_sel_hi:[1,0,1]
	global_load_dword v152, v[46:47], off offset:-4096
	ds_read_b128 v[228:231], v24 offset:3776
	ds_read_b128 v[232:235], v24 offset:3792
	ds_read_b128 v[240:243], v24 offset:3808
	ds_read_b128 v[244:247], v24 offset:3824
	s_waitcnt vmcnt(59) lgkmcnt(8)
	v_pk_fma_f32 v[12:13], v[26:27], v[152:153], v[12:13] op_sel:[0,1,0] op_sel_hi:[1,1,1]
	v_pk_fma_f32 v[10:11], v[28:29], v[152:153], v[10:11] op_sel:[0,1,0] op_sel_hi:[1,1,1]
	v_pk_fma_f32 v[16:17], v[30:31], v[152:153], v[16:17] op_sel:[0,1,0] op_sel_hi:[1,1,1]
	v_pk_fma_f32 v[14:15], v[32:33], v[152:153], v[14:15] op_sel:[0,1,0] op_sel_hi:[1,1,1]
	v_pk_fma_f32 v[20:21], v[34:35], v[152:153], v[20:21] op_sel:[0,1,0] op_sel_hi:[1,1,1]
	v_pk_fma_f32 v[18:19], v[36:37], v[152:153], v[18:19] op_sel:[0,1,0] op_sel_hi:[1,1,1]
	v_pk_fma_f32 v[6:7], v[38:39], v[152:153], v[6:7] op_sel:[0,1,0] op_sel_hi:[1,1,1]
	v_pk_fma_f32 v[8:9], v[40:41], v[152:153], v[8:9] op_sel:[0,1,0] op_sel_hi:[1,1,1]
	global_load_dword v153, v[46:47], off
	v_lshl_add_u64 v[46:47], v[46:47], 0, s[86:87]
	ds_read_b128 v[26:29], v24 offset:3840
	ds_read_b128 v[30:33], v24 offset:3856
	ds_read_b128 v[34:37], v24 offset:3872
	ds_read_b128 v[38:41], v24 offset:3888
	s_waitcnt vmcnt(59) lgkmcnt(8)
	v_pk_fma_f32 v[12:13], v[48:49], v[154:155], v[12:13] op_sel_hi:[1,0,1]
	v_pk_fma_f32 v[10:11], v[50:51], v[154:155], v[10:11] op_sel_hi:[1,0,1]
	v_pk_fma_f32 v[16:17], v[52:53], v[154:155], v[16:17] op_sel_hi:[1,0,1]
	v_pk_fma_f32 v[14:15], v[54:55], v[154:155], v[14:15] op_sel_hi:[1,0,1]
	v_pk_fma_f32 v[20:21], v[56:57], v[154:155], v[20:21] op_sel_hi:[1,0,1]
	v_pk_fma_f32 v[18:19], v[58:59], v[154:155], v[18:19] op_sel_hi:[1,0,1]
	v_pk_fma_f32 v[6:7], v[60:61], v[154:155], v[6:7] op_sel_hi:[1,0,1]
	v_pk_fma_f32 v[8:9], v[62:63], v[154:155], v[8:9] op_sel_hi:[1,0,1]
	global_load_dword v154, v[46:47], off offset:-4096
	ds_read_b128 v[48:51], v24 offset:3904
	ds_read_b128 v[52:55], v24 offset:3920
	ds_read_b128 v[56:59], v24 offset:3936
	ds_read_b128 v[60:63], v24 offset:3952
	s_waitcnt vmcnt(59) lgkmcnt(8)
	v_pk_fma_f32 v[12:13], v[228:229], v[154:155], v[12:13] op_sel:[0,1,0] op_sel_hi:[1,1,1]
	v_pk_fma_f32 v[10:11], v[230:231], v[154:155], v[10:11] op_sel:[0,1,0] op_sel_hi:[1,1,1]
	v_pk_fma_f32 v[16:17], v[232:233], v[154:155], v[16:17] op_sel:[0,1,0] op_sel_hi:[1,1,1]
	v_pk_fma_f32 v[14:15], v[234:235], v[154:155], v[14:15] op_sel:[0,1,0] op_sel_hi:[1,1,1]
	v_pk_fma_f32 v[20:21], v[240:241], v[154:155], v[20:21] op_sel:[0,1,0] op_sel_hi:[1,1,1]
	v_pk_fma_f32 v[18:19], v[242:243], v[154:155], v[18:19] op_sel:[0,1,0] op_sel_hi:[1,1,1]
	v_pk_fma_f32 v[6:7], v[244:245], v[154:155], v[6:7] op_sel:[0,1,0] op_sel_hi:[1,1,1]
	v_pk_fma_f32 v[8:9], v[246:247], v[154:155], v[8:9] op_sel:[0,1,0] op_sel_hi:[1,1,1]
	global_load_dword v155, v[46:47], off
	v_lshl_add_u64 v[46:47], v[46:47], 0, s[86:87]
	ds_read_b128 v[228:231], v24 offset:3968
	ds_read_b128 v[232:235], v24 offset:3984
	ds_read_b128 v[240:243], v24 offset:4000
	ds_read_b128 v[244:247], v24 offset:4016
	s_waitcnt vmcnt(59) lgkmcnt(8)
	v_pk_fma_f32 v[12:13], v[26:27], v[96:97], v[12:13] op_sel_hi:[1,0,1]
	v_pk_fma_f32 v[10:11], v[28:29], v[96:97], v[10:11] op_sel_hi:[1,0,1]
	v_pk_fma_f32 v[16:17], v[30:31], v[96:97], v[16:17] op_sel_hi:[1,0,1]
	v_pk_fma_f32 v[14:15], v[32:33], v[96:97], v[14:15] op_sel_hi:[1,0,1]
	v_pk_fma_f32 v[20:21], v[34:35], v[96:97], v[20:21] op_sel_hi:[1,0,1]
	v_pk_fma_f32 v[18:19], v[36:37], v[96:97], v[18:19] op_sel_hi:[1,0,1]
	v_pk_fma_f32 v[6:7], v[38:39], v[96:97], v[6:7] op_sel_hi:[1,0,1]
	v_pk_fma_f32 v[8:9], v[40:41], v[96:97], v[8:9] op_sel_hi:[1,0,1]
	global_load_dword v96, v[46:47], off offset:-4096
	ds_read_b128 v[26:29], v24 offset:4032
	ds_read_b128 v[30:33], v24 offset:4048
	ds_read_b128 v[34:37], v24 offset:4064
	ds_read_b128 v[38:41], v24 offset:4080
	s_waitcnt vmcnt(59) lgkmcnt(8)
	v_pk_fma_f32 v[12:13], v[48:49], v[96:97], v[12:13] op_sel:[0,1,0] op_sel_hi:[1,1,1]
	v_pk_fma_f32 v[10:11], v[50:51], v[96:97], v[10:11] op_sel:[0,1,0] op_sel_hi:[1,1,1]
	v_pk_fma_f32 v[16:17], v[52:53], v[96:97], v[16:17] op_sel:[0,1,0] op_sel_hi:[1,1,1]
	v_pk_fma_f32 v[14:15], v[54:55], v[96:97], v[14:15] op_sel:[0,1,0] op_sel_hi:[1,1,1]
	v_pk_fma_f32 v[20:21], v[56:57], v[96:97], v[20:21] op_sel:[0,1,0] op_sel_hi:[1,1,1]
	v_pk_fma_f32 v[18:19], v[58:59], v[96:97], v[18:19] op_sel:[0,1,0] op_sel_hi:[1,1,1]
	v_pk_fma_f32 v[6:7], v[60:61], v[96:97], v[6:7] op_sel:[0,1,0] op_sel_hi:[1,1,1]
	v_pk_fma_f32 v[8:9], v[62:63], v[96:97], v[8:9] op_sel:[0,1,0] op_sel_hi:[1,1,1]
	global_load_dword v97, v[46:47], off
	v_lshl_add_u64 v[46:47], v[46:47], 0, s[86:87]
	ds_read_b128 v[48:51], v24 offset:4096
	ds_read_b128 v[52:55], v24 offset:4112
	ds_read_b128 v[56:59], v24 offset:4128
	ds_read_b128 v[60:63], v24 offset:4144
	s_waitcnt vmcnt(59) lgkmcnt(8)
	v_pk_fma_f32 v[12:13], v[228:229], v[98:99], v[12:13] op_sel_hi:[1,0,1]
	v_pk_fma_f32 v[10:11], v[230:231], v[98:99], v[10:11] op_sel_hi:[1,0,1]
	v_pk_fma_f32 v[16:17], v[232:233], v[98:99], v[16:17] op_sel_hi:[1,0,1]
	v_pk_fma_f32 v[14:15], v[234:235], v[98:99], v[14:15] op_sel_hi:[1,0,1]
	v_pk_fma_f32 v[20:21], v[240:241], v[98:99], v[20:21] op_sel_hi:[1,0,1]
	v_pk_fma_f32 v[18:19], v[242:243], v[98:99], v[18:19] op_sel_hi:[1,0,1]
	v_pk_fma_f32 v[6:7], v[244:245], v[98:99], v[6:7] op_sel_hi:[1,0,1]
	v_pk_fma_f32 v[8:9], v[246:247], v[98:99], v[8:9] op_sel_hi:[1,0,1]
	global_load_dword v98, v[46:47], off offset:-4096
	ds_read_b128 v[228:231], v24 offset:4160
	ds_read_b128 v[232:235], v24 offset:4176
	ds_read_b128 v[240:243], v24 offset:4192
	ds_read_b128 v[244:247], v24 offset:4208
	s_waitcnt vmcnt(59) lgkmcnt(8)
	v_pk_fma_f32 v[12:13], v[26:27], v[98:99], v[12:13] op_sel:[0,1,0] op_sel_hi:[1,1,1]
	v_pk_fma_f32 v[10:11], v[28:29], v[98:99], v[10:11] op_sel:[0,1,0] op_sel_hi:[1,1,1]
	v_pk_fma_f32 v[16:17], v[30:31], v[98:99], v[16:17] op_sel:[0,1,0] op_sel_hi:[1,1,1]
	v_pk_fma_f32 v[14:15], v[32:33], v[98:99], v[14:15] op_sel:[0,1,0] op_sel_hi:[1,1,1]
	v_pk_fma_f32 v[20:21], v[34:35], v[98:99], v[20:21] op_sel:[0,1,0] op_sel_hi:[1,1,1]
	v_pk_fma_f32 v[18:19], v[36:37], v[98:99], v[18:19] op_sel:[0,1,0] op_sel_hi:[1,1,1]
	v_pk_fma_f32 v[6:7], v[38:39], v[98:99], v[6:7] op_sel:[0,1,0] op_sel_hi:[1,1,1]
	v_pk_fma_f32 v[8:9], v[40:41], v[98:99], v[8:9] op_sel:[0,1,0] op_sel_hi:[1,1,1]
	global_load_dword v99, v[46:47], off
	v_lshl_add_u64 v[46:47], v[46:47], 0, s[86:87]
	ds_read_b128 v[26:29], v24 offset:4224
	ds_read_b128 v[30:33], v24 offset:4240
	ds_read_b128 v[34:37], v24 offset:4256
	ds_read_b128 v[38:41], v24 offset:4272
	s_waitcnt vmcnt(59) lgkmcnt(8)
	v_pk_fma_f32 v[12:13], v[48:49], v[100:101], v[12:13] op_sel_hi:[1,0,1]
	v_pk_fma_f32 v[10:11], v[50:51], v[100:101], v[10:11] op_sel_hi:[1,0,1]
	v_pk_fma_f32 v[16:17], v[52:53], v[100:101], v[16:17] op_sel_hi:[1,0,1]
	v_pk_fma_f32 v[14:15], v[54:55], v[100:101], v[14:15] op_sel_hi:[1,0,1]
	v_pk_fma_f32 v[20:21], v[56:57], v[100:101], v[20:21] op_sel_hi:[1,0,1]
	v_pk_fma_f32 v[18:19], v[58:59], v[100:101], v[18:19] op_sel_hi:[1,0,1]
	v_pk_fma_f32 v[6:7], v[60:61], v[100:101], v[6:7] op_sel_hi:[1,0,1]
	v_pk_fma_f32 v[8:9], v[62:63], v[100:101], v[8:9] op_sel_hi:[1,0,1]
	global_load_dword v100, v[46:47], off offset:-4096
	ds_read_b128 v[48:51], v24 offset:4288
	ds_read_b128 v[52:55], v24 offset:4304
	ds_read_b128 v[56:59], v24 offset:4320
	ds_read_b128 v[60:63], v24 offset:4336
	s_waitcnt vmcnt(59) lgkmcnt(8)
	v_pk_fma_f32 v[12:13], v[228:229], v[100:101], v[12:13] op_sel:[0,1,0] op_sel_hi:[1,1,1]
	v_pk_fma_f32 v[10:11], v[230:231], v[100:101], v[10:11] op_sel:[0,1,0] op_sel_hi:[1,1,1]
	v_pk_fma_f32 v[16:17], v[232:233], v[100:101], v[16:17] op_sel:[0,1,0] op_sel_hi:[1,1,1]
	v_pk_fma_f32 v[14:15], v[234:235], v[100:101], v[14:15] op_sel:[0,1,0] op_sel_hi:[1,1,1]
	v_pk_fma_f32 v[20:21], v[240:241], v[100:101], v[20:21] op_sel:[0,1,0] op_sel_hi:[1,1,1]
	v_pk_fma_f32 v[18:19], v[242:243], v[100:101], v[18:19] op_sel:[0,1,0] op_sel_hi:[1,1,1]
	v_pk_fma_f32 v[6:7], v[244:245], v[100:101], v[6:7] op_sel:[0,1,0] op_sel_hi:[1,1,1]
	v_pk_fma_f32 v[8:9], v[246:247], v[100:101], v[8:9] op_sel:[0,1,0] op_sel_hi:[1,1,1]
	global_load_dword v101, v[46:47], off
	v_lshl_add_u64 v[46:47], v[46:47], 0, s[86:87]
	ds_read_b128 v[228:231], v24 offset:4352
	ds_read_b128 v[232:235], v24 offset:4368
	ds_read_b128 v[240:243], v24 offset:4384
	ds_read_b128 v[244:247], v24 offset:4400
	s_waitcnt vmcnt(59) lgkmcnt(8)
	v_pk_fma_f32 v[12:13], v[26:27], v[102:103], v[12:13] op_sel_hi:[1,0,1]
	v_pk_fma_f32 v[10:11], v[28:29], v[102:103], v[10:11] op_sel_hi:[1,0,1]
	v_pk_fma_f32 v[16:17], v[30:31], v[102:103], v[16:17] op_sel_hi:[1,0,1]
	v_pk_fma_f32 v[14:15], v[32:33], v[102:103], v[14:15] op_sel_hi:[1,0,1]
	v_pk_fma_f32 v[20:21], v[34:35], v[102:103], v[20:21] op_sel_hi:[1,0,1]
	v_pk_fma_f32 v[18:19], v[36:37], v[102:103], v[18:19] op_sel_hi:[1,0,1]
	v_pk_fma_f32 v[6:7], v[38:39], v[102:103], v[6:7] op_sel_hi:[1,0,1]
	v_pk_fma_f32 v[8:9], v[40:41], v[102:103], v[8:9] op_sel_hi:[1,0,1]
	global_load_dword v102, v[46:47], off offset:-4096
	ds_read_b128 v[26:29], v24 offset:4416
	ds_read_b128 v[30:33], v24 offset:4432
	ds_read_b128 v[34:37], v24 offset:4448
	ds_read_b128 v[38:41], v24 offset:4464
	s_waitcnt vmcnt(59) lgkmcnt(8)
	v_pk_fma_f32 v[12:13], v[48:49], v[102:103], v[12:13] op_sel:[0,1,0] op_sel_hi:[1,1,1]
	v_pk_fma_f32 v[10:11], v[50:51], v[102:103], v[10:11] op_sel:[0,1,0] op_sel_hi:[1,1,1]
	v_pk_fma_f32 v[16:17], v[52:53], v[102:103], v[16:17] op_sel:[0,1,0] op_sel_hi:[1,1,1]
	v_pk_fma_f32 v[14:15], v[54:55], v[102:103], v[14:15] op_sel:[0,1,0] op_sel_hi:[1,1,1]
	v_pk_fma_f32 v[20:21], v[56:57], v[102:103], v[20:21] op_sel:[0,1,0] op_sel_hi:[1,1,1]
	v_pk_fma_f32 v[18:19], v[58:59], v[102:103], v[18:19] op_sel:[0,1,0] op_sel_hi:[1,1,1]
	v_pk_fma_f32 v[6:7], v[60:61], v[102:103], v[6:7] op_sel:[0,1,0] op_sel_hi:[1,1,1]
	v_pk_fma_f32 v[8:9], v[62:63], v[102:103], v[8:9] op_sel:[0,1,0] op_sel_hi:[1,1,1]
	global_load_dword v103, v[46:47], off
	v_lshl_add_u64 v[46:47], v[46:47], 0, s[86:87]
	ds_read_b128 v[48:51], v24 offset:4480
	ds_read_b128 v[52:55], v24 offset:4496
	ds_read_b128 v[56:59], v24 offset:4512
	ds_read_b128 v[60:63], v24 offset:4528
	s_waitcnt vmcnt(59) lgkmcnt(8)
	v_pk_fma_f32 v[12:13], v[228:229], v[104:105], v[12:13] op_sel_hi:[1,0,1]
	v_pk_fma_f32 v[10:11], v[230:231], v[104:105], v[10:11] op_sel_hi:[1,0,1]
	v_pk_fma_f32 v[16:17], v[232:233], v[104:105], v[16:17] op_sel_hi:[1,0,1]
	v_pk_fma_f32 v[14:15], v[234:235], v[104:105], v[14:15] op_sel_hi:[1,0,1]
	v_pk_fma_f32 v[20:21], v[240:241], v[104:105], v[20:21] op_sel_hi:[1,0,1]
	v_pk_fma_f32 v[18:19], v[242:243], v[104:105], v[18:19] op_sel_hi:[1,0,1]
	v_pk_fma_f32 v[6:7], v[244:245], v[104:105], v[6:7] op_sel_hi:[1,0,1]
	v_pk_fma_f32 v[8:9], v[246:247], v[104:105], v[8:9] op_sel_hi:[1,0,1]
	ds_read_b128 v[228:231], v24 offset:4544
	ds_read_b128 v[232:235], v24 offset:4560
	ds_read_b128 v[240:243], v24 offset:4576
	ds_read_b128 v[244:247], v24 offset:4592
	s_waitcnt vmcnt(58) lgkmcnt(8)
	v_pk_fma_f32 v[12:13], v[26:27], v[104:105], v[12:13] op_sel:[0,1,0] op_sel_hi:[1,1,1]
	v_pk_fma_f32 v[10:11], v[28:29], v[104:105], v[10:11] op_sel:[0,1,0] op_sel_hi:[1,1,1]
	v_pk_fma_f32 v[16:17], v[30:31], v[104:105], v[16:17] op_sel:[0,1,0] op_sel_hi:[1,1,1]
	v_pk_fma_f32 v[14:15], v[32:33], v[104:105], v[14:15] op_sel:[0,1,0] op_sel_hi:[1,1,1]
	v_pk_fma_f32 v[20:21], v[34:35], v[104:105], v[20:21] op_sel:[0,1,0] op_sel_hi:[1,1,1]
	v_pk_fma_f32 v[18:19], v[36:37], v[104:105], v[18:19] op_sel:[0,1,0] op_sel_hi:[1,1,1]
	v_pk_fma_f32 v[6:7], v[38:39], v[104:105], v[6:7] op_sel:[0,1,0] op_sel_hi:[1,1,1]
	v_pk_fma_f32 v[8:9], v[40:41], v[104:105], v[8:9] op_sel:[0,1,0] op_sel_hi:[1,1,1]
	ds_read_b128 v[26:29], v24 offset:4608
	ds_read_b128 v[30:33], v24 offset:4624
	ds_read_b128 v[34:37], v24 offset:4640
	ds_read_b128 v[38:41], v24 offset:4656
	s_waitcnt vmcnt(57) lgkmcnt(8)
	v_pk_fma_f32 v[12:13], v[48:49], v[106:107], v[12:13] op_sel_hi:[1,0,1]
	v_pk_fma_f32 v[10:11], v[50:51], v[106:107], v[10:11] op_sel_hi:[1,0,1]
	v_pk_fma_f32 v[16:17], v[52:53], v[106:107], v[16:17] op_sel_hi:[1,0,1]
	v_pk_fma_f32 v[14:15], v[54:55], v[106:107], v[14:15] op_sel_hi:[1,0,1]
	v_pk_fma_f32 v[20:21], v[56:57], v[106:107], v[20:21] op_sel_hi:[1,0,1]
	v_pk_fma_f32 v[18:19], v[58:59], v[106:107], v[18:19] op_sel_hi:[1,0,1]
	v_pk_fma_f32 v[6:7], v[60:61], v[106:107], v[6:7] op_sel_hi:[1,0,1]
	v_pk_fma_f32 v[8:9], v[62:63], v[106:107], v[8:9] op_sel_hi:[1,0,1]
	ds_read_b128 v[48:51], v24 offset:4672
	ds_read_b128 v[52:55], v24 offset:4688
	ds_read_b128 v[56:59], v24 offset:4704
	ds_read_b128 v[60:63], v24 offset:4720
	s_waitcnt vmcnt(56) lgkmcnt(8)
	v_pk_fma_f32 v[12:13], v[228:229], v[106:107], v[12:13] op_sel:[0,1,0] op_sel_hi:[1,1,1]
	v_pk_fma_f32 v[10:11], v[230:231], v[106:107], v[10:11] op_sel:[0,1,0] op_sel_hi:[1,1,1]
	v_pk_fma_f32 v[16:17], v[232:233], v[106:107], v[16:17] op_sel:[0,1,0] op_sel_hi:[1,1,1]
	v_pk_fma_f32 v[14:15], v[234:235], v[106:107], v[14:15] op_sel:[0,1,0] op_sel_hi:[1,1,1]
	v_pk_fma_f32 v[20:21], v[240:241], v[106:107], v[20:21] op_sel:[0,1,0] op_sel_hi:[1,1,1]
	v_pk_fma_f32 v[18:19], v[242:243], v[106:107], v[18:19] op_sel:[0,1,0] op_sel_hi:[1,1,1]
	v_pk_fma_f32 v[6:7], v[244:245], v[106:107], v[6:7] op_sel:[0,1,0] op_sel_hi:[1,1,1]
	v_pk_fma_f32 v[8:9], v[246:247], v[106:107], v[8:9] op_sel:[0,1,0] op_sel_hi:[1,1,1]
	ds_read_b128 v[228:231], v24 offset:4736
	ds_read_b128 v[232:235], v24 offset:4752
	ds_read_b128 v[240:243], v24 offset:4768
	ds_read_b128 v[244:247], v24 offset:4784
	s_waitcnt vmcnt(55) lgkmcnt(8)
	v_pk_fma_f32 v[12:13], v[26:27], v[108:109], v[12:13] op_sel_hi:[1,0,1]
	v_pk_fma_f32 v[10:11], v[28:29], v[108:109], v[10:11] op_sel_hi:[1,0,1]
	v_pk_fma_f32 v[16:17], v[30:31], v[108:109], v[16:17] op_sel_hi:[1,0,1]
	v_pk_fma_f32 v[14:15], v[32:33], v[108:109], v[14:15] op_sel_hi:[1,0,1]
	v_pk_fma_f32 v[20:21], v[34:35], v[108:109], v[20:21] op_sel_hi:[1,0,1]
	v_pk_fma_f32 v[18:19], v[36:37], v[108:109], v[18:19] op_sel_hi:[1,0,1]
	v_pk_fma_f32 v[6:7], v[38:39], v[108:109], v[6:7] op_sel_hi:[1,0,1]
	v_pk_fma_f32 v[8:9], v[40:41], v[108:109], v[8:9] op_sel_hi:[1,0,1]
	ds_read_b128 v[26:29], v24 offset:4800
	ds_read_b128 v[30:33], v24 offset:4816
	ds_read_b128 v[34:37], v24 offset:4832
	ds_read_b128 v[38:41], v24 offset:4848
	s_waitcnt vmcnt(54) lgkmcnt(8)
	v_pk_fma_f32 v[12:13], v[48:49], v[108:109], v[12:13] op_sel:[0,1,0] op_sel_hi:[1,1,1]
	v_pk_fma_f32 v[10:11], v[50:51], v[108:109], v[10:11] op_sel:[0,1,0] op_sel_hi:[1,1,1]
	v_pk_fma_f32 v[16:17], v[52:53], v[108:109], v[16:17] op_sel:[0,1,0] op_sel_hi:[1,1,1]
	v_pk_fma_f32 v[14:15], v[54:55], v[108:109], v[14:15] op_sel:[0,1,0] op_sel_hi:[1,1,1]
	v_pk_fma_f32 v[20:21], v[56:57], v[108:109], v[20:21] op_sel:[0,1,0] op_sel_hi:[1,1,1]
	v_pk_fma_f32 v[18:19], v[58:59], v[108:109], v[18:19] op_sel:[0,1,0] op_sel_hi:[1,1,1]
	v_pk_fma_f32 v[6:7], v[60:61], v[108:109], v[6:7] op_sel:[0,1,0] op_sel_hi:[1,1,1]
	v_pk_fma_f32 v[8:9], v[62:63], v[108:109], v[8:9] op_sel:[0,1,0] op_sel_hi:[1,1,1]
	ds_read_b128 v[48:51], v24 offset:4864
	ds_read_b128 v[52:55], v24 offset:4880
	ds_read_b128 v[56:59], v24 offset:4896
	ds_read_b128 v[60:63], v24 offset:4912
	s_waitcnt vmcnt(53) lgkmcnt(8)
	v_pk_fma_f32 v[12:13], v[228:229], v[110:111], v[12:13] op_sel_hi:[1,0,1]
	v_pk_fma_f32 v[10:11], v[230:231], v[110:111], v[10:11] op_sel_hi:[1,0,1]
	v_pk_fma_f32 v[16:17], v[232:233], v[110:111], v[16:17] op_sel_hi:[1,0,1]
	v_pk_fma_f32 v[14:15], v[234:235], v[110:111], v[14:15] op_sel_hi:[1,0,1]
	v_pk_fma_f32 v[20:21], v[240:241], v[110:111], v[20:21] op_sel_hi:[1,0,1]
	v_pk_fma_f32 v[18:19], v[242:243], v[110:111], v[18:19] op_sel_hi:[1,0,1]
	v_pk_fma_f32 v[6:7], v[244:245], v[110:111], v[6:7] op_sel_hi:[1,0,1]
	v_pk_fma_f32 v[8:9], v[246:247], v[110:111], v[8:9] op_sel_hi:[1,0,1]
	ds_read_b128 v[228:231], v24 offset:4928
	ds_read_b128 v[232:235], v24 offset:4944
	ds_read_b128 v[240:243], v24 offset:4960
	ds_read_b128 v[244:247], v24 offset:4976
	s_waitcnt vmcnt(52) lgkmcnt(8)
	v_pk_fma_f32 v[12:13], v[26:27], v[110:111], v[12:13] op_sel:[0,1,0] op_sel_hi:[1,1,1]
	v_pk_fma_f32 v[10:11], v[28:29], v[110:111], v[10:11] op_sel:[0,1,0] op_sel_hi:[1,1,1]
	v_pk_fma_f32 v[16:17], v[30:31], v[110:111], v[16:17] op_sel:[0,1,0] op_sel_hi:[1,1,1]
	v_pk_fma_f32 v[14:15], v[32:33], v[110:111], v[14:15] op_sel:[0,1,0] op_sel_hi:[1,1,1]
	v_pk_fma_f32 v[20:21], v[34:35], v[110:111], v[20:21] op_sel:[0,1,0] op_sel_hi:[1,1,1]
	v_pk_fma_f32 v[18:19], v[36:37], v[110:111], v[18:19] op_sel:[0,1,0] op_sel_hi:[1,1,1]
	v_pk_fma_f32 v[6:7], v[38:39], v[110:111], v[6:7] op_sel:[0,1,0] op_sel_hi:[1,1,1]
	v_pk_fma_f32 v[8:9], v[40:41], v[110:111], v[8:9] op_sel:[0,1,0] op_sel_hi:[1,1,1]
	ds_read_b128 v[26:29], v24 offset:4992
	ds_read_b128 v[30:33], v24 offset:5008
	ds_read_b128 v[34:37], v24 offset:5024
	ds_read_b128 v[38:41], v24 offset:5040
	s_waitcnt vmcnt(51) lgkmcnt(8)
	v_pk_fma_f32 v[12:13], v[48:49], v[112:113], v[12:13] op_sel_hi:[1,0,1]
	v_pk_fma_f32 v[10:11], v[50:51], v[112:113], v[10:11] op_sel_hi:[1,0,1]
	v_pk_fma_f32 v[16:17], v[52:53], v[112:113], v[16:17] op_sel_hi:[1,0,1]
	v_pk_fma_f32 v[14:15], v[54:55], v[112:113], v[14:15] op_sel_hi:[1,0,1]
	v_pk_fma_f32 v[20:21], v[56:57], v[112:113], v[20:21] op_sel_hi:[1,0,1]
	v_pk_fma_f32 v[18:19], v[58:59], v[112:113], v[18:19] op_sel_hi:[1,0,1]
	v_pk_fma_f32 v[6:7], v[60:61], v[112:113], v[6:7] op_sel_hi:[1,0,1]
	v_pk_fma_f32 v[8:9], v[62:63], v[112:113], v[8:9] op_sel_hi:[1,0,1]
	ds_read_b128 v[48:51], v24 offset:5056
	ds_read_b128 v[52:55], v24 offset:5072
	ds_read_b128 v[56:59], v24 offset:5088
	ds_read_b128 v[60:63], v24 offset:5104
	s_waitcnt vmcnt(50) lgkmcnt(8)
	v_pk_fma_f32 v[12:13], v[228:229], v[112:113], v[12:13] op_sel:[0,1,0] op_sel_hi:[1,1,1]
	v_pk_fma_f32 v[10:11], v[230:231], v[112:113], v[10:11] op_sel:[0,1,0] op_sel_hi:[1,1,1]
	v_pk_fma_f32 v[16:17], v[232:233], v[112:113], v[16:17] op_sel:[0,1,0] op_sel_hi:[1,1,1]
	v_pk_fma_f32 v[14:15], v[234:235], v[112:113], v[14:15] op_sel:[0,1,0] op_sel_hi:[1,1,1]
	v_pk_fma_f32 v[20:21], v[240:241], v[112:113], v[20:21] op_sel:[0,1,0] op_sel_hi:[1,1,1]
	v_pk_fma_f32 v[18:19], v[242:243], v[112:113], v[18:19] op_sel:[0,1,0] op_sel_hi:[1,1,1]
	v_pk_fma_f32 v[6:7], v[244:245], v[112:113], v[6:7] op_sel:[0,1,0] op_sel_hi:[1,1,1]
	v_pk_fma_f32 v[8:9], v[246:247], v[112:113], v[8:9] op_sel:[0,1,0] op_sel_hi:[1,1,1]
	ds_read_b128 v[228:231], v24 offset:5120
	ds_read_b128 v[232:235], v24 offset:5136
	ds_read_b128 v[240:243], v24 offset:5152
	ds_read_b128 v[244:247], v24 offset:5168
	s_waitcnt vmcnt(49) lgkmcnt(8)
	v_pk_fma_f32 v[12:13], v[26:27], v[114:115], v[12:13] op_sel_hi:[1,0,1]
	v_pk_fma_f32 v[10:11], v[28:29], v[114:115], v[10:11] op_sel_hi:[1,0,1]
	v_pk_fma_f32 v[16:17], v[30:31], v[114:115], v[16:17] op_sel_hi:[1,0,1]
	v_pk_fma_f32 v[14:15], v[32:33], v[114:115], v[14:15] op_sel_hi:[1,0,1]
	v_pk_fma_f32 v[20:21], v[34:35], v[114:115], v[20:21] op_sel_hi:[1,0,1]
	v_pk_fma_f32 v[18:19], v[36:37], v[114:115], v[18:19] op_sel_hi:[1,0,1]
	v_pk_fma_f32 v[6:7], v[38:39], v[114:115], v[6:7] op_sel_hi:[1,0,1]
	v_pk_fma_f32 v[8:9], v[40:41], v[114:115], v[8:9] op_sel_hi:[1,0,1]
	ds_read_b128 v[26:29], v24 offset:5184
	ds_read_b128 v[30:33], v24 offset:5200
	ds_read_b128 v[34:37], v24 offset:5216
	ds_read_b128 v[38:41], v24 offset:5232
	s_waitcnt vmcnt(48) lgkmcnt(8)
	v_pk_fma_f32 v[12:13], v[48:49], v[114:115], v[12:13] op_sel:[0,1,0] op_sel_hi:[1,1,1]
	v_pk_fma_f32 v[10:11], v[50:51], v[114:115], v[10:11] op_sel:[0,1,0] op_sel_hi:[1,1,1]
	v_pk_fma_f32 v[16:17], v[52:53], v[114:115], v[16:17] op_sel:[0,1,0] op_sel_hi:[1,1,1]
	v_pk_fma_f32 v[14:15], v[54:55], v[114:115], v[14:15] op_sel:[0,1,0] op_sel_hi:[1,1,1]
	v_pk_fma_f32 v[20:21], v[56:57], v[114:115], v[20:21] op_sel:[0,1,0] op_sel_hi:[1,1,1]
	v_pk_fma_f32 v[18:19], v[58:59], v[114:115], v[18:19] op_sel:[0,1,0] op_sel_hi:[1,1,1]
	v_pk_fma_f32 v[6:7], v[60:61], v[114:115], v[6:7] op_sel:[0,1,0] op_sel_hi:[1,1,1]
	v_pk_fma_f32 v[8:9], v[62:63], v[114:115], v[8:9] op_sel:[0,1,0] op_sel_hi:[1,1,1]
	ds_read_b128 v[48:51], v24 offset:5248
	ds_read_b128 v[52:55], v24 offset:5264
	ds_read_b128 v[56:59], v24 offset:5280
	ds_read_b128 v[60:63], v24 offset:5296
	s_waitcnt vmcnt(47) lgkmcnt(8)
	v_pk_fma_f32 v[12:13], v[228:229], v[116:117], v[12:13] op_sel_hi:[1,0,1]
	v_pk_fma_f32 v[10:11], v[230:231], v[116:117], v[10:11] op_sel_hi:[1,0,1]
	v_pk_fma_f32 v[16:17], v[232:233], v[116:117], v[16:17] op_sel_hi:[1,0,1]
	v_pk_fma_f32 v[14:15], v[234:235], v[116:117], v[14:15] op_sel_hi:[1,0,1]
	v_pk_fma_f32 v[20:21], v[240:241], v[116:117], v[20:21] op_sel_hi:[1,0,1]
	v_pk_fma_f32 v[18:19], v[242:243], v[116:117], v[18:19] op_sel_hi:[1,0,1]
	v_pk_fma_f32 v[6:7], v[244:245], v[116:117], v[6:7] op_sel_hi:[1,0,1]
	v_pk_fma_f32 v[8:9], v[246:247], v[116:117], v[8:9] op_sel_hi:[1,0,1]
	ds_read_b128 v[228:231], v24 offset:5312
	ds_read_b128 v[232:235], v24 offset:5328
	ds_read_b128 v[240:243], v24 offset:5344
	ds_read_b128 v[244:247], v24 offset:5360
	s_waitcnt vmcnt(46) lgkmcnt(8)
	v_pk_fma_f32 v[12:13], v[26:27], v[116:117], v[12:13] op_sel:[0,1,0] op_sel_hi:[1,1,1]
	v_pk_fma_f32 v[10:11], v[28:29], v[116:117], v[10:11] op_sel:[0,1,0] op_sel_hi:[1,1,1]
	v_pk_fma_f32 v[16:17], v[30:31], v[116:117], v[16:17] op_sel:[0,1,0] op_sel_hi:[1,1,1]
	v_pk_fma_f32 v[14:15], v[32:33], v[116:117], v[14:15] op_sel:[0,1,0] op_sel_hi:[1,1,1]
	v_pk_fma_f32 v[20:21], v[34:35], v[116:117], v[20:21] op_sel:[0,1,0] op_sel_hi:[1,1,1]
	v_pk_fma_f32 v[18:19], v[36:37], v[116:117], v[18:19] op_sel:[0,1,0] op_sel_hi:[1,1,1]
	v_pk_fma_f32 v[6:7], v[38:39], v[116:117], v[6:7] op_sel:[0,1,0] op_sel_hi:[1,1,1]
	v_pk_fma_f32 v[8:9], v[40:41], v[116:117], v[8:9] op_sel:[0,1,0] op_sel_hi:[1,1,1]
	ds_read_b128 v[26:29], v24 offset:5376
	ds_read_b128 v[30:33], v24 offset:5392
	ds_read_b128 v[34:37], v24 offset:5408
	ds_read_b128 v[38:41], v24 offset:5424
	s_waitcnt vmcnt(45) lgkmcnt(8)
	v_pk_fma_f32 v[12:13], v[48:49], v[118:119], v[12:13] op_sel_hi:[1,0,1]
	v_pk_fma_f32 v[10:11], v[50:51], v[118:119], v[10:11] op_sel_hi:[1,0,1]
	v_pk_fma_f32 v[16:17], v[52:53], v[118:119], v[16:17] op_sel_hi:[1,0,1]
	v_pk_fma_f32 v[14:15], v[54:55], v[118:119], v[14:15] op_sel_hi:[1,0,1]
	v_pk_fma_f32 v[20:21], v[56:57], v[118:119], v[20:21] op_sel_hi:[1,0,1]
	v_pk_fma_f32 v[18:19], v[58:59], v[118:119], v[18:19] op_sel_hi:[1,0,1]
	v_pk_fma_f32 v[6:7], v[60:61], v[118:119], v[6:7] op_sel_hi:[1,0,1]
	v_pk_fma_f32 v[8:9], v[62:63], v[118:119], v[8:9] op_sel_hi:[1,0,1]
	ds_read_b128 v[48:51], v24 offset:5440
	ds_read_b128 v[52:55], v24 offset:5456
	ds_read_b128 v[56:59], v24 offset:5472
	ds_read_b128 v[60:63], v24 offset:5488
	s_waitcnt vmcnt(44) lgkmcnt(8)
	v_pk_fma_f32 v[12:13], v[228:229], v[118:119], v[12:13] op_sel:[0,1,0] op_sel_hi:[1,1,1]
	v_pk_fma_f32 v[10:11], v[230:231], v[118:119], v[10:11] op_sel:[0,1,0] op_sel_hi:[1,1,1]
	v_pk_fma_f32 v[16:17], v[232:233], v[118:119], v[16:17] op_sel:[0,1,0] op_sel_hi:[1,1,1]
	v_pk_fma_f32 v[14:15], v[234:235], v[118:119], v[14:15] op_sel:[0,1,0] op_sel_hi:[1,1,1]
	v_pk_fma_f32 v[20:21], v[240:241], v[118:119], v[20:21] op_sel:[0,1,0] op_sel_hi:[1,1,1]
	v_pk_fma_f32 v[18:19], v[242:243], v[118:119], v[18:19] op_sel:[0,1,0] op_sel_hi:[1,1,1]
	v_pk_fma_f32 v[6:7], v[244:245], v[118:119], v[6:7] op_sel:[0,1,0] op_sel_hi:[1,1,1]
	v_pk_fma_f32 v[8:9], v[246:247], v[118:119], v[8:9] op_sel:[0,1,0] op_sel_hi:[1,1,1]
	ds_read_b128 v[228:231], v24 offset:5504
	ds_read_b128 v[232:235], v24 offset:5520
	ds_read_b128 v[240:243], v24 offset:5536
	ds_read_b128 v[244:247], v24 offset:5552
	s_waitcnt vmcnt(43) lgkmcnt(8)
	v_pk_fma_f32 v[12:13], v[26:27], v[120:121], v[12:13] op_sel_hi:[1,0,1]
	v_pk_fma_f32 v[10:11], v[28:29], v[120:121], v[10:11] op_sel_hi:[1,0,1]
	v_pk_fma_f32 v[16:17], v[30:31], v[120:121], v[16:17] op_sel_hi:[1,0,1]
	v_pk_fma_f32 v[14:15], v[32:33], v[120:121], v[14:15] op_sel_hi:[1,0,1]
	v_pk_fma_f32 v[20:21], v[34:35], v[120:121], v[20:21] op_sel_hi:[1,0,1]
	v_pk_fma_f32 v[18:19], v[36:37], v[120:121], v[18:19] op_sel_hi:[1,0,1]
	v_pk_fma_f32 v[6:7], v[38:39], v[120:121], v[6:7] op_sel_hi:[1,0,1]
	v_pk_fma_f32 v[8:9], v[40:41], v[120:121], v[8:9] op_sel_hi:[1,0,1]
	ds_read_b128 v[26:29], v24 offset:5568
	ds_read_b128 v[30:33], v24 offset:5584
	ds_read_b128 v[34:37], v24 offset:5600
	ds_read_b128 v[38:41], v24 offset:5616
	s_waitcnt vmcnt(42) lgkmcnt(8)
	v_pk_fma_f32 v[12:13], v[48:49], v[120:121], v[12:13] op_sel:[0,1,0] op_sel_hi:[1,1,1]
	v_pk_fma_f32 v[10:11], v[50:51], v[120:121], v[10:11] op_sel:[0,1,0] op_sel_hi:[1,1,1]
	v_pk_fma_f32 v[16:17], v[52:53], v[120:121], v[16:17] op_sel:[0,1,0] op_sel_hi:[1,1,1]
	v_pk_fma_f32 v[14:15], v[54:55], v[120:121], v[14:15] op_sel:[0,1,0] op_sel_hi:[1,1,1]
	v_pk_fma_f32 v[20:21], v[56:57], v[120:121], v[20:21] op_sel:[0,1,0] op_sel_hi:[1,1,1]
	v_pk_fma_f32 v[18:19], v[58:59], v[120:121], v[18:19] op_sel:[0,1,0] op_sel_hi:[1,1,1]
	v_pk_fma_f32 v[6:7], v[60:61], v[120:121], v[6:7] op_sel:[0,1,0] op_sel_hi:[1,1,1]
	v_pk_fma_f32 v[8:9], v[62:63], v[120:121], v[8:9] op_sel:[0,1,0] op_sel_hi:[1,1,1]
	ds_read_b128 v[48:51], v24 offset:5632
	ds_read_b128 v[52:55], v24 offset:5648
	ds_read_b128 v[56:59], v24 offset:5664
	ds_read_b128 v[60:63], v24 offset:5680
	s_waitcnt vmcnt(41) lgkmcnt(8)
	v_pk_fma_f32 v[12:13], v[228:229], v[122:123], v[12:13] op_sel_hi:[1,0,1]
	v_pk_fma_f32 v[10:11], v[230:231], v[122:123], v[10:11] op_sel_hi:[1,0,1]
	v_pk_fma_f32 v[16:17], v[232:233], v[122:123], v[16:17] op_sel_hi:[1,0,1]
	v_pk_fma_f32 v[14:15], v[234:235], v[122:123], v[14:15] op_sel_hi:[1,0,1]
	v_pk_fma_f32 v[20:21], v[240:241], v[122:123], v[20:21] op_sel_hi:[1,0,1]
	v_pk_fma_f32 v[18:19], v[242:243], v[122:123], v[18:19] op_sel_hi:[1,0,1]
	v_pk_fma_f32 v[6:7], v[244:245], v[122:123], v[6:7] op_sel_hi:[1,0,1]
	v_pk_fma_f32 v[8:9], v[246:247], v[122:123], v[8:9] op_sel_hi:[1,0,1]
	ds_read_b128 v[228:231], v24 offset:5696
	ds_read_b128 v[232:235], v24 offset:5712
	ds_read_b128 v[240:243], v24 offset:5728
	ds_read_b128 v[244:247], v24 offset:5744
	s_waitcnt vmcnt(40) lgkmcnt(8)
	v_pk_fma_f32 v[12:13], v[26:27], v[122:123], v[12:13] op_sel:[0,1,0] op_sel_hi:[1,1,1]
	v_pk_fma_f32 v[10:11], v[28:29], v[122:123], v[10:11] op_sel:[0,1,0] op_sel_hi:[1,1,1]
	v_pk_fma_f32 v[16:17], v[30:31], v[122:123], v[16:17] op_sel:[0,1,0] op_sel_hi:[1,1,1]
	v_pk_fma_f32 v[14:15], v[32:33], v[122:123], v[14:15] op_sel:[0,1,0] op_sel_hi:[1,1,1]
	v_pk_fma_f32 v[20:21], v[34:35], v[122:123], v[20:21] op_sel:[0,1,0] op_sel_hi:[1,1,1]
	v_pk_fma_f32 v[18:19], v[36:37], v[122:123], v[18:19] op_sel:[0,1,0] op_sel_hi:[1,1,1]
	v_pk_fma_f32 v[6:7], v[38:39], v[122:123], v[6:7] op_sel:[0,1,0] op_sel_hi:[1,1,1]
	v_pk_fma_f32 v[8:9], v[40:41], v[122:123], v[8:9] op_sel:[0,1,0] op_sel_hi:[1,1,1]
	ds_read_b128 v[26:29], v24 offset:5760
	ds_read_b128 v[30:33], v24 offset:5776
	ds_read_b128 v[34:37], v24 offset:5792
	ds_read_b128 v[38:41], v24 offset:5808
	s_waitcnt vmcnt(39) lgkmcnt(8)
	v_pk_fma_f32 v[12:13], v[48:49], v[124:125], v[12:13] op_sel_hi:[1,0,1]
	v_pk_fma_f32 v[10:11], v[50:51], v[124:125], v[10:11] op_sel_hi:[1,0,1]
	v_pk_fma_f32 v[16:17], v[52:53], v[124:125], v[16:17] op_sel_hi:[1,0,1]
	v_pk_fma_f32 v[14:15], v[54:55], v[124:125], v[14:15] op_sel_hi:[1,0,1]
	v_pk_fma_f32 v[20:21], v[56:57], v[124:125], v[20:21] op_sel_hi:[1,0,1]
	v_pk_fma_f32 v[18:19], v[58:59], v[124:125], v[18:19] op_sel_hi:[1,0,1]
	v_pk_fma_f32 v[6:7], v[60:61], v[124:125], v[6:7] op_sel_hi:[1,0,1]
	v_pk_fma_f32 v[8:9], v[62:63], v[124:125], v[8:9] op_sel_hi:[1,0,1]
	ds_read_b128 v[48:51], v24 offset:5824
	ds_read_b128 v[52:55], v24 offset:5840
	ds_read_b128 v[56:59], v24 offset:5856
	ds_read_b128 v[60:63], v24 offset:5872
	s_waitcnt vmcnt(38) lgkmcnt(8)
	v_pk_fma_f32 v[12:13], v[228:229], v[124:125], v[12:13] op_sel:[0,1,0] op_sel_hi:[1,1,1]
	v_pk_fma_f32 v[10:11], v[230:231], v[124:125], v[10:11] op_sel:[0,1,0] op_sel_hi:[1,1,1]
	v_pk_fma_f32 v[16:17], v[232:233], v[124:125], v[16:17] op_sel:[0,1,0] op_sel_hi:[1,1,1]
	v_pk_fma_f32 v[14:15], v[234:235], v[124:125], v[14:15] op_sel:[0,1,0] op_sel_hi:[1,1,1]
	v_pk_fma_f32 v[20:21], v[240:241], v[124:125], v[20:21] op_sel:[0,1,0] op_sel_hi:[1,1,1]
	v_pk_fma_f32 v[18:19], v[242:243], v[124:125], v[18:19] op_sel:[0,1,0] op_sel_hi:[1,1,1]
	v_pk_fma_f32 v[6:7], v[244:245], v[124:125], v[6:7] op_sel:[0,1,0] op_sel_hi:[1,1,1]
	v_pk_fma_f32 v[8:9], v[246:247], v[124:125], v[8:9] op_sel:[0,1,0] op_sel_hi:[1,1,1]
	ds_read_b128 v[228:231], v24 offset:5888
	ds_read_b128 v[232:235], v24 offset:5904
	ds_read_b128 v[240:243], v24 offset:5920
	ds_read_b128 v[244:247], v24 offset:5936
	s_waitcnt vmcnt(37) lgkmcnt(8)
	v_pk_fma_f32 v[12:13], v[26:27], v[126:127], v[12:13] op_sel_hi:[1,0,1]
	v_pk_fma_f32 v[10:11], v[28:29], v[126:127], v[10:11] op_sel_hi:[1,0,1]
	v_pk_fma_f32 v[16:17], v[30:31], v[126:127], v[16:17] op_sel_hi:[1,0,1]
	v_pk_fma_f32 v[14:15], v[32:33], v[126:127], v[14:15] op_sel_hi:[1,0,1]
	v_pk_fma_f32 v[20:21], v[34:35], v[126:127], v[20:21] op_sel_hi:[1,0,1]
	v_pk_fma_f32 v[18:19], v[36:37], v[126:127], v[18:19] op_sel_hi:[1,0,1]
	v_pk_fma_f32 v[6:7], v[38:39], v[126:127], v[6:7] op_sel_hi:[1,0,1]
	v_pk_fma_f32 v[8:9], v[40:41], v[126:127], v[8:9] op_sel_hi:[1,0,1]
	ds_read_b128 v[26:29], v24 offset:5952
	ds_read_b128 v[30:33], v24 offset:5968
	ds_read_b128 v[34:37], v24 offset:5984
	ds_read_b128 v[38:41], v24 offset:6000
	s_waitcnt vmcnt(36) lgkmcnt(8)
	v_pk_fma_f32 v[12:13], v[48:49], v[126:127], v[12:13] op_sel:[0,1,0] op_sel_hi:[1,1,1]
	v_pk_fma_f32 v[10:11], v[50:51], v[126:127], v[10:11] op_sel:[0,1,0] op_sel_hi:[1,1,1]
	v_pk_fma_f32 v[16:17], v[52:53], v[126:127], v[16:17] op_sel:[0,1,0] op_sel_hi:[1,1,1]
	v_pk_fma_f32 v[14:15], v[54:55], v[126:127], v[14:15] op_sel:[0,1,0] op_sel_hi:[1,1,1]
	v_pk_fma_f32 v[20:21], v[56:57], v[126:127], v[20:21] op_sel:[0,1,0] op_sel_hi:[1,1,1]
	v_pk_fma_f32 v[18:19], v[58:59], v[126:127], v[18:19] op_sel:[0,1,0] op_sel_hi:[1,1,1]
	v_pk_fma_f32 v[6:7], v[60:61], v[126:127], v[6:7] op_sel:[0,1,0] op_sel_hi:[1,1,1]
	v_pk_fma_f32 v[8:9], v[62:63], v[126:127], v[8:9] op_sel:[0,1,0] op_sel_hi:[1,1,1]
	ds_read_b128 v[48:51], v24 offset:6016
	ds_read_b128 v[52:55], v24 offset:6032
	ds_read_b128 v[56:59], v24 offset:6048
	ds_read_b128 v[60:63], v24 offset:6064
	s_waitcnt vmcnt(35) lgkmcnt(8)
	v_pk_fma_f32 v[12:13], v[228:229], v[128:129], v[12:13] op_sel_hi:[1,0,1]
	v_pk_fma_f32 v[10:11], v[230:231], v[128:129], v[10:11] op_sel_hi:[1,0,1]
	v_pk_fma_f32 v[16:17], v[232:233], v[128:129], v[16:17] op_sel_hi:[1,0,1]
	v_pk_fma_f32 v[14:15], v[234:235], v[128:129], v[14:15] op_sel_hi:[1,0,1]
	v_pk_fma_f32 v[20:21], v[240:241], v[128:129], v[20:21] op_sel_hi:[1,0,1]
	v_pk_fma_f32 v[18:19], v[242:243], v[128:129], v[18:19] op_sel_hi:[1,0,1]
	v_pk_fma_f32 v[6:7], v[244:245], v[128:129], v[6:7] op_sel_hi:[1,0,1]
	v_pk_fma_f32 v[8:9], v[246:247], v[128:129], v[8:9] op_sel_hi:[1,0,1]
	ds_read_b128 v[228:231], v24 offset:6080
	ds_read_b128 v[232:235], v24 offset:6096
	ds_read_b128 v[240:243], v24 offset:6112
	ds_read_b128 v[244:247], v24 offset:6128
	s_waitcnt vmcnt(34) lgkmcnt(8)
	v_pk_fma_f32 v[12:13], v[26:27], v[128:129], v[12:13] op_sel:[0,1,0] op_sel_hi:[1,1,1]
	v_pk_fma_f32 v[10:11], v[28:29], v[128:129], v[10:11] op_sel:[0,1,0] op_sel_hi:[1,1,1]
	v_pk_fma_f32 v[16:17], v[30:31], v[128:129], v[16:17] op_sel:[0,1,0] op_sel_hi:[1,1,1]
	v_pk_fma_f32 v[14:15], v[32:33], v[128:129], v[14:15] op_sel:[0,1,0] op_sel_hi:[1,1,1]
	v_pk_fma_f32 v[20:21], v[34:35], v[128:129], v[20:21] op_sel:[0,1,0] op_sel_hi:[1,1,1]
	v_pk_fma_f32 v[18:19], v[36:37], v[128:129], v[18:19] op_sel:[0,1,0] op_sel_hi:[1,1,1]
	v_pk_fma_f32 v[6:7], v[38:39], v[128:129], v[6:7] op_sel:[0,1,0] op_sel_hi:[1,1,1]
	v_pk_fma_f32 v[8:9], v[40:41], v[128:129], v[8:9] op_sel:[0,1,0] op_sel_hi:[1,1,1]
	ds_read_b128 v[26:29], v24 offset:6144
	ds_read_b128 v[30:33], v24 offset:6160
	ds_read_b128 v[34:37], v24 offset:6176
	ds_read_b128 v[38:41], v24 offset:6192
	s_waitcnt vmcnt(33) lgkmcnt(8)
	v_pk_fma_f32 v[12:13], v[48:49], v[130:131], v[12:13] op_sel_hi:[1,0,1]
	v_pk_fma_f32 v[10:11], v[50:51], v[130:131], v[10:11] op_sel_hi:[1,0,1]
	v_pk_fma_f32 v[16:17], v[52:53], v[130:131], v[16:17] op_sel_hi:[1,0,1]
	v_pk_fma_f32 v[14:15], v[54:55], v[130:131], v[14:15] op_sel_hi:[1,0,1]
	v_pk_fma_f32 v[20:21], v[56:57], v[130:131], v[20:21] op_sel_hi:[1,0,1]
	v_pk_fma_f32 v[18:19], v[58:59], v[130:131], v[18:19] op_sel_hi:[1,0,1]
	v_pk_fma_f32 v[6:7], v[60:61], v[130:131], v[6:7] op_sel_hi:[1,0,1]
	v_pk_fma_f32 v[8:9], v[62:63], v[130:131], v[8:9] op_sel_hi:[1,0,1]
	ds_read_b128 v[48:51], v24 offset:6208
	ds_read_b128 v[52:55], v24 offset:6224
	ds_read_b128 v[56:59], v24 offset:6240
	ds_read_b128 v[60:63], v24 offset:6256
	s_waitcnt vmcnt(32) lgkmcnt(8)
	v_pk_fma_f32 v[12:13], v[228:229], v[130:131], v[12:13] op_sel:[0,1,0] op_sel_hi:[1,1,1]
	v_pk_fma_f32 v[10:11], v[230:231], v[130:131], v[10:11] op_sel:[0,1,0] op_sel_hi:[1,1,1]
	v_pk_fma_f32 v[16:17], v[232:233], v[130:131], v[16:17] op_sel:[0,1,0] op_sel_hi:[1,1,1]
	v_pk_fma_f32 v[14:15], v[234:235], v[130:131], v[14:15] op_sel:[0,1,0] op_sel_hi:[1,1,1]
	v_pk_fma_f32 v[20:21], v[240:241], v[130:131], v[20:21] op_sel:[0,1,0] op_sel_hi:[1,1,1]
	v_pk_fma_f32 v[18:19], v[242:243], v[130:131], v[18:19] op_sel:[0,1,0] op_sel_hi:[1,1,1]
	v_pk_fma_f32 v[6:7], v[244:245], v[130:131], v[6:7] op_sel:[0,1,0] op_sel_hi:[1,1,1]
	v_pk_fma_f32 v[8:9], v[246:247], v[130:131], v[8:9] op_sel:[0,1,0] op_sel_hi:[1,1,1]
	ds_read_b128 v[228:231], v24 offset:6272
	ds_read_b128 v[232:235], v24 offset:6288
	ds_read_b128 v[240:243], v24 offset:6304
	ds_read_b128 v[244:247], v24 offset:6320
	s_waitcnt vmcnt(31) lgkmcnt(8)
	v_pk_fma_f32 v[12:13], v[26:27], v[132:133], v[12:13] op_sel_hi:[1,0,1]
	v_pk_fma_f32 v[10:11], v[28:29], v[132:133], v[10:11] op_sel_hi:[1,0,1]
	v_pk_fma_f32 v[16:17], v[30:31], v[132:133], v[16:17] op_sel_hi:[1,0,1]
	v_pk_fma_f32 v[14:15], v[32:33], v[132:133], v[14:15] op_sel_hi:[1,0,1]
	v_pk_fma_f32 v[20:21], v[34:35], v[132:133], v[20:21] op_sel_hi:[1,0,1]
	v_pk_fma_f32 v[18:19], v[36:37], v[132:133], v[18:19] op_sel_hi:[1,0,1]
	v_pk_fma_f32 v[6:7], v[38:39], v[132:133], v[6:7] op_sel_hi:[1,0,1]
	v_pk_fma_f32 v[8:9], v[40:41], v[132:133], v[8:9] op_sel_hi:[1,0,1]
	ds_read_b128 v[26:29], v24 offset:6336
	ds_read_b128 v[30:33], v24 offset:6352
	ds_read_b128 v[34:37], v24 offset:6368
	ds_read_b128 v[38:41], v24 offset:6384
	s_waitcnt vmcnt(30) lgkmcnt(8)
	v_pk_fma_f32 v[12:13], v[48:49], v[132:133], v[12:13] op_sel:[0,1,0] op_sel_hi:[1,1,1]
	v_pk_fma_f32 v[10:11], v[50:51], v[132:133], v[10:11] op_sel:[0,1,0] op_sel_hi:[1,1,1]
	v_pk_fma_f32 v[16:17], v[52:53], v[132:133], v[16:17] op_sel:[0,1,0] op_sel_hi:[1,1,1]
	v_pk_fma_f32 v[14:15], v[54:55], v[132:133], v[14:15] op_sel:[0,1,0] op_sel_hi:[1,1,1]
	v_pk_fma_f32 v[20:21], v[56:57], v[132:133], v[20:21] op_sel:[0,1,0] op_sel_hi:[1,1,1]
	v_pk_fma_f32 v[18:19], v[58:59], v[132:133], v[18:19] op_sel:[0,1,0] op_sel_hi:[1,1,1]
	v_pk_fma_f32 v[6:7], v[60:61], v[132:133], v[6:7] op_sel:[0,1,0] op_sel_hi:[1,1,1]
	v_pk_fma_f32 v[8:9], v[62:63], v[132:133], v[8:9] op_sel:[0,1,0] op_sel_hi:[1,1,1]
	ds_read_b128 v[48:51], v24 offset:6400
	ds_read_b128 v[52:55], v24 offset:6416
	ds_read_b128 v[56:59], v24 offset:6432
	ds_read_b128 v[60:63], v24 offset:6448
	s_waitcnt vmcnt(29) lgkmcnt(8)
	v_pk_fma_f32 v[12:13], v[228:229], v[134:135], v[12:13] op_sel_hi:[1,0,1]
	v_pk_fma_f32 v[10:11], v[230:231], v[134:135], v[10:11] op_sel_hi:[1,0,1]
	v_pk_fma_f32 v[16:17], v[232:233], v[134:135], v[16:17] op_sel_hi:[1,0,1]
	v_pk_fma_f32 v[14:15], v[234:235], v[134:135], v[14:15] op_sel_hi:[1,0,1]
	v_pk_fma_f32 v[20:21], v[240:241], v[134:135], v[20:21] op_sel_hi:[1,0,1]
	v_pk_fma_f32 v[18:19], v[242:243], v[134:135], v[18:19] op_sel_hi:[1,0,1]
	v_pk_fma_f32 v[6:7], v[244:245], v[134:135], v[6:7] op_sel_hi:[1,0,1]
	v_pk_fma_f32 v[8:9], v[246:247], v[134:135], v[8:9] op_sel_hi:[1,0,1]
	ds_read_b128 v[228:231], v24 offset:6464
	ds_read_b128 v[232:235], v24 offset:6480
	ds_read_b128 v[240:243], v24 offset:6496
	ds_read_b128 v[244:247], v24 offset:6512
	s_waitcnt vmcnt(28) lgkmcnt(8)
	v_pk_fma_f32 v[12:13], v[26:27], v[134:135], v[12:13] op_sel:[0,1,0] op_sel_hi:[1,1,1]
	v_pk_fma_f32 v[10:11], v[28:29], v[134:135], v[10:11] op_sel:[0,1,0] op_sel_hi:[1,1,1]
	v_pk_fma_f32 v[16:17], v[30:31], v[134:135], v[16:17] op_sel:[0,1,0] op_sel_hi:[1,1,1]
	v_pk_fma_f32 v[14:15], v[32:33], v[134:135], v[14:15] op_sel:[0,1,0] op_sel_hi:[1,1,1]
	v_pk_fma_f32 v[20:21], v[34:35], v[134:135], v[20:21] op_sel:[0,1,0] op_sel_hi:[1,1,1]
	v_pk_fma_f32 v[18:19], v[36:37], v[134:135], v[18:19] op_sel:[0,1,0] op_sel_hi:[1,1,1]
	v_pk_fma_f32 v[6:7], v[38:39], v[134:135], v[6:7] op_sel:[0,1,0] op_sel_hi:[1,1,1]
	v_pk_fma_f32 v[8:9], v[40:41], v[134:135], v[8:9] op_sel:[0,1,0] op_sel_hi:[1,1,1]
	ds_read_b128 v[26:29], v24 offset:6528
	ds_read_b128 v[30:33], v24 offset:6544
	ds_read_b128 v[34:37], v24 offset:6560
	ds_read_b128 v[38:41], v24 offset:6576
	s_waitcnt vmcnt(27) lgkmcnt(8)
	v_pk_fma_f32 v[12:13], v[48:49], v[136:137], v[12:13] op_sel_hi:[1,0,1]
	v_pk_fma_f32 v[10:11], v[50:51], v[136:137], v[10:11] op_sel_hi:[1,0,1]
	v_pk_fma_f32 v[16:17], v[52:53], v[136:137], v[16:17] op_sel_hi:[1,0,1]
	v_pk_fma_f32 v[14:15], v[54:55], v[136:137], v[14:15] op_sel_hi:[1,0,1]
	v_pk_fma_f32 v[20:21], v[56:57], v[136:137], v[20:21] op_sel_hi:[1,0,1]
	v_pk_fma_f32 v[18:19], v[58:59], v[136:137], v[18:19] op_sel_hi:[1,0,1]
	v_pk_fma_f32 v[6:7], v[60:61], v[136:137], v[6:7] op_sel_hi:[1,0,1]
	v_pk_fma_f32 v[8:9], v[62:63], v[136:137], v[8:9] op_sel_hi:[1,0,1]
	ds_read_b128 v[48:51], v24 offset:6592
	ds_read_b128 v[52:55], v24 offset:6608
	ds_read_b128 v[56:59], v24 offset:6624
	ds_read_b128 v[60:63], v24 offset:6640
	s_waitcnt vmcnt(26) lgkmcnt(8)
	v_pk_fma_f32 v[12:13], v[228:229], v[136:137], v[12:13] op_sel:[0,1,0] op_sel_hi:[1,1,1]
	v_pk_fma_f32 v[10:11], v[230:231], v[136:137], v[10:11] op_sel:[0,1,0] op_sel_hi:[1,1,1]
	v_pk_fma_f32 v[16:17], v[232:233], v[136:137], v[16:17] op_sel:[0,1,0] op_sel_hi:[1,1,1]
	v_pk_fma_f32 v[14:15], v[234:235], v[136:137], v[14:15] op_sel:[0,1,0] op_sel_hi:[1,1,1]
	v_pk_fma_f32 v[20:21], v[240:241], v[136:137], v[20:21] op_sel:[0,1,0] op_sel_hi:[1,1,1]
	v_pk_fma_f32 v[18:19], v[242:243], v[136:137], v[18:19] op_sel:[0,1,0] op_sel_hi:[1,1,1]
	v_pk_fma_f32 v[6:7], v[244:245], v[136:137], v[6:7] op_sel:[0,1,0] op_sel_hi:[1,1,1]
	v_pk_fma_f32 v[8:9], v[246:247], v[136:137], v[8:9] op_sel:[0,1,0] op_sel_hi:[1,1,1]
	ds_read_b128 v[228:231], v24 offset:6656
	ds_read_b128 v[232:235], v24 offset:6672
	ds_read_b128 v[240:243], v24 offset:6688
	ds_read_b128 v[244:247], v24 offset:6704
	s_waitcnt vmcnt(25) lgkmcnt(8)
	v_pk_fma_f32 v[12:13], v[26:27], v[138:139], v[12:13] op_sel_hi:[1,0,1]
	v_pk_fma_f32 v[10:11], v[28:29], v[138:139], v[10:11] op_sel_hi:[1,0,1]
	v_pk_fma_f32 v[16:17], v[30:31], v[138:139], v[16:17] op_sel_hi:[1,0,1]
	v_pk_fma_f32 v[14:15], v[32:33], v[138:139], v[14:15] op_sel_hi:[1,0,1]
	v_pk_fma_f32 v[20:21], v[34:35], v[138:139], v[20:21] op_sel_hi:[1,0,1]
	v_pk_fma_f32 v[18:19], v[36:37], v[138:139], v[18:19] op_sel_hi:[1,0,1]
	v_pk_fma_f32 v[6:7], v[38:39], v[138:139], v[6:7] op_sel_hi:[1,0,1]
	v_pk_fma_f32 v[8:9], v[40:41], v[138:139], v[8:9] op_sel_hi:[1,0,1]
	ds_read_b128 v[26:29], v24 offset:6720
	ds_read_b128 v[30:33], v24 offset:6736
	ds_read_b128 v[34:37], v24 offset:6752
	ds_read_b128 v[38:41], v24 offset:6768
	s_waitcnt vmcnt(24) lgkmcnt(8)
	v_pk_fma_f32 v[12:13], v[48:49], v[138:139], v[12:13] op_sel:[0,1,0] op_sel_hi:[1,1,1]
	v_pk_fma_f32 v[10:11], v[50:51], v[138:139], v[10:11] op_sel:[0,1,0] op_sel_hi:[1,1,1]
	v_pk_fma_f32 v[16:17], v[52:53], v[138:139], v[16:17] op_sel:[0,1,0] op_sel_hi:[1,1,1]
	v_pk_fma_f32 v[14:15], v[54:55], v[138:139], v[14:15] op_sel:[0,1,0] op_sel_hi:[1,1,1]
	v_pk_fma_f32 v[20:21], v[56:57], v[138:139], v[20:21] op_sel:[0,1,0] op_sel_hi:[1,1,1]
	v_pk_fma_f32 v[18:19], v[58:59], v[138:139], v[18:19] op_sel:[0,1,0] op_sel_hi:[1,1,1]
	v_pk_fma_f32 v[6:7], v[60:61], v[138:139], v[6:7] op_sel:[0,1,0] op_sel_hi:[1,1,1]
	v_pk_fma_f32 v[8:9], v[62:63], v[138:139], v[8:9] op_sel:[0,1,0] op_sel_hi:[1,1,1]
	ds_read_b128 v[48:51], v24 offset:6784
	ds_read_b128 v[52:55], v24 offset:6800
	ds_read_b128 v[56:59], v24 offset:6816
	ds_read_b128 v[60:63], v24 offset:6832
	s_waitcnt vmcnt(23) lgkmcnt(8)
	v_pk_fma_f32 v[12:13], v[228:229], v[140:141], v[12:13] op_sel_hi:[1,0,1]
	v_pk_fma_f32 v[10:11], v[230:231], v[140:141], v[10:11] op_sel_hi:[1,0,1]
	v_pk_fma_f32 v[16:17], v[232:233], v[140:141], v[16:17] op_sel_hi:[1,0,1]
	v_pk_fma_f32 v[14:15], v[234:235], v[140:141], v[14:15] op_sel_hi:[1,0,1]
	v_pk_fma_f32 v[20:21], v[240:241], v[140:141], v[20:21] op_sel_hi:[1,0,1]
	v_pk_fma_f32 v[18:19], v[242:243], v[140:141], v[18:19] op_sel_hi:[1,0,1]
	v_pk_fma_f32 v[6:7], v[244:245], v[140:141], v[6:7] op_sel_hi:[1,0,1]
	v_pk_fma_f32 v[8:9], v[246:247], v[140:141], v[8:9] op_sel_hi:[1,0,1]
	ds_read_b128 v[228:231], v24 offset:6848
	ds_read_b128 v[232:235], v24 offset:6864
	ds_read_b128 v[240:243], v24 offset:6880
	ds_read_b128 v[244:247], v24 offset:6896
	s_waitcnt vmcnt(22) lgkmcnt(8)
	v_pk_fma_f32 v[12:13], v[26:27], v[140:141], v[12:13] op_sel:[0,1,0] op_sel_hi:[1,1,1]
	v_pk_fma_f32 v[10:11], v[28:29], v[140:141], v[10:11] op_sel:[0,1,0] op_sel_hi:[1,1,1]
	v_pk_fma_f32 v[16:17], v[30:31], v[140:141], v[16:17] op_sel:[0,1,0] op_sel_hi:[1,1,1]
	v_pk_fma_f32 v[14:15], v[32:33], v[140:141], v[14:15] op_sel:[0,1,0] op_sel_hi:[1,1,1]
	v_pk_fma_f32 v[20:21], v[34:35], v[140:141], v[20:21] op_sel:[0,1,0] op_sel_hi:[1,1,1]
	v_pk_fma_f32 v[18:19], v[36:37], v[140:141], v[18:19] op_sel:[0,1,0] op_sel_hi:[1,1,1]
	v_pk_fma_f32 v[6:7], v[38:39], v[140:141], v[6:7] op_sel:[0,1,0] op_sel_hi:[1,1,1]
	v_pk_fma_f32 v[8:9], v[40:41], v[140:141], v[8:9] op_sel:[0,1,0] op_sel_hi:[1,1,1]
	ds_read_b128 v[26:29], v24 offset:6912
	ds_read_b128 v[30:33], v24 offset:6928
	ds_read_b128 v[34:37], v24 offset:6944
	ds_read_b128 v[38:41], v24 offset:6960
	s_waitcnt vmcnt(21) lgkmcnt(8)
	v_pk_fma_f32 v[12:13], v[48:49], v[142:143], v[12:13] op_sel_hi:[1,0,1]
	v_pk_fma_f32 v[10:11], v[50:51], v[142:143], v[10:11] op_sel_hi:[1,0,1]
	v_pk_fma_f32 v[16:17], v[52:53], v[142:143], v[16:17] op_sel_hi:[1,0,1]
	v_pk_fma_f32 v[14:15], v[54:55], v[142:143], v[14:15] op_sel_hi:[1,0,1]
	v_pk_fma_f32 v[20:21], v[56:57], v[142:143], v[20:21] op_sel_hi:[1,0,1]
	v_pk_fma_f32 v[18:19], v[58:59], v[142:143], v[18:19] op_sel_hi:[1,0,1]
	v_pk_fma_f32 v[6:7], v[60:61], v[142:143], v[6:7] op_sel_hi:[1,0,1]
	v_pk_fma_f32 v[8:9], v[62:63], v[142:143], v[8:9] op_sel_hi:[1,0,1]
	ds_read_b128 v[48:51], v24 offset:6976
	ds_read_b128 v[52:55], v24 offset:6992
	ds_read_b128 v[56:59], v24 offset:7008
	ds_read_b128 v[60:63], v24 offset:7024
	s_waitcnt vmcnt(20) lgkmcnt(8)
	v_pk_fma_f32 v[12:13], v[228:229], v[142:143], v[12:13] op_sel:[0,1,0] op_sel_hi:[1,1,1]
	v_pk_fma_f32 v[10:11], v[230:231], v[142:143], v[10:11] op_sel:[0,1,0] op_sel_hi:[1,1,1]
	v_pk_fma_f32 v[16:17], v[232:233], v[142:143], v[16:17] op_sel:[0,1,0] op_sel_hi:[1,1,1]
	v_pk_fma_f32 v[14:15], v[234:235], v[142:143], v[14:15] op_sel:[0,1,0] op_sel_hi:[1,1,1]
	v_pk_fma_f32 v[20:21], v[240:241], v[142:143], v[20:21] op_sel:[0,1,0] op_sel_hi:[1,1,1]
	v_pk_fma_f32 v[18:19], v[242:243], v[142:143], v[18:19] op_sel:[0,1,0] op_sel_hi:[1,1,1]
	v_pk_fma_f32 v[6:7], v[244:245], v[142:143], v[6:7] op_sel:[0,1,0] op_sel_hi:[1,1,1]
	v_pk_fma_f32 v[8:9], v[246:247], v[142:143], v[8:9] op_sel:[0,1,0] op_sel_hi:[1,1,1]
	ds_read_b128 v[228:231], v24 offset:7040
	ds_read_b128 v[232:235], v24 offset:7056
	ds_read_b128 v[240:243], v24 offset:7072
	ds_read_b128 v[244:247], v24 offset:7088
	s_waitcnt vmcnt(19) lgkmcnt(8)
	v_pk_fma_f32 v[12:13], v[26:27], v[144:145], v[12:13] op_sel_hi:[1,0,1]
	v_pk_fma_f32 v[10:11], v[28:29], v[144:145], v[10:11] op_sel_hi:[1,0,1]
	v_pk_fma_f32 v[16:17], v[30:31], v[144:145], v[16:17] op_sel_hi:[1,0,1]
	v_pk_fma_f32 v[14:15], v[32:33], v[144:145], v[14:15] op_sel_hi:[1,0,1]
	v_pk_fma_f32 v[20:21], v[34:35], v[144:145], v[20:21] op_sel_hi:[1,0,1]
	v_pk_fma_f32 v[18:19], v[36:37], v[144:145], v[18:19] op_sel_hi:[1,0,1]
	v_pk_fma_f32 v[6:7], v[38:39], v[144:145], v[6:7] op_sel_hi:[1,0,1]
	v_pk_fma_f32 v[8:9], v[40:41], v[144:145], v[8:9] op_sel_hi:[1,0,1]
	ds_read_b128 v[26:29], v24 offset:7104
	ds_read_b128 v[30:33], v24 offset:7120
	ds_read_b128 v[34:37], v24 offset:7136
	ds_read_b128 v[38:41], v24 offset:7152
	s_waitcnt vmcnt(18) lgkmcnt(8)
	v_pk_fma_f32 v[12:13], v[48:49], v[144:145], v[12:13] op_sel:[0,1,0] op_sel_hi:[1,1,1]
	v_pk_fma_f32 v[10:11], v[50:51], v[144:145], v[10:11] op_sel:[0,1,0] op_sel_hi:[1,1,1]
	v_pk_fma_f32 v[16:17], v[52:53], v[144:145], v[16:17] op_sel:[0,1,0] op_sel_hi:[1,1,1]
	v_pk_fma_f32 v[14:15], v[54:55], v[144:145], v[14:15] op_sel:[0,1,0] op_sel_hi:[1,1,1]
	v_pk_fma_f32 v[20:21], v[56:57], v[144:145], v[20:21] op_sel:[0,1,0] op_sel_hi:[1,1,1]
	v_pk_fma_f32 v[18:19], v[58:59], v[144:145], v[18:19] op_sel:[0,1,0] op_sel_hi:[1,1,1]
	v_pk_fma_f32 v[6:7], v[60:61], v[144:145], v[6:7] op_sel:[0,1,0] op_sel_hi:[1,1,1]
	v_pk_fma_f32 v[8:9], v[62:63], v[144:145], v[8:9] op_sel:[0,1,0] op_sel_hi:[1,1,1]
	ds_read_b128 v[48:51], v24 offset:7168
	ds_read_b128 v[52:55], v24 offset:7184
	ds_read_b128 v[56:59], v24 offset:7200
	ds_read_b128 v[60:63], v24 offset:7216
	s_waitcnt vmcnt(17) lgkmcnt(8)
	v_pk_fma_f32 v[12:13], v[228:229], v[146:147], v[12:13] op_sel_hi:[1,0,1]
	v_pk_fma_f32 v[10:11], v[230:231], v[146:147], v[10:11] op_sel_hi:[1,0,1]
	v_pk_fma_f32 v[16:17], v[232:233], v[146:147], v[16:17] op_sel_hi:[1,0,1]
	v_pk_fma_f32 v[14:15], v[234:235], v[146:147], v[14:15] op_sel_hi:[1,0,1]
	v_pk_fma_f32 v[20:21], v[240:241], v[146:147], v[20:21] op_sel_hi:[1,0,1]
	v_pk_fma_f32 v[18:19], v[242:243], v[146:147], v[18:19] op_sel_hi:[1,0,1]
	v_pk_fma_f32 v[6:7], v[244:245], v[146:147], v[6:7] op_sel_hi:[1,0,1]
	v_pk_fma_f32 v[8:9], v[246:247], v[146:147], v[8:9] op_sel_hi:[1,0,1]
	ds_read_b128 v[228:231], v24 offset:7232
	ds_read_b128 v[232:235], v24 offset:7248
	ds_read_b128 v[240:243], v24 offset:7264
	ds_read_b128 v[244:247], v24 offset:7280
	s_waitcnt vmcnt(16) lgkmcnt(8)
	v_pk_fma_f32 v[12:13], v[26:27], v[146:147], v[12:13] op_sel:[0,1,0] op_sel_hi:[1,1,1]
	v_pk_fma_f32 v[10:11], v[28:29], v[146:147], v[10:11] op_sel:[0,1,0] op_sel_hi:[1,1,1]
	v_pk_fma_f32 v[16:17], v[30:31], v[146:147], v[16:17] op_sel:[0,1,0] op_sel_hi:[1,1,1]
	v_pk_fma_f32 v[14:15], v[32:33], v[146:147], v[14:15] op_sel:[0,1,0] op_sel_hi:[1,1,1]
	v_pk_fma_f32 v[20:21], v[34:35], v[146:147], v[20:21] op_sel:[0,1,0] op_sel_hi:[1,1,1]
	v_pk_fma_f32 v[18:19], v[36:37], v[146:147], v[18:19] op_sel:[0,1,0] op_sel_hi:[1,1,1]
	v_pk_fma_f32 v[6:7], v[38:39], v[146:147], v[6:7] op_sel:[0,1,0] op_sel_hi:[1,1,1]
	v_pk_fma_f32 v[8:9], v[40:41], v[146:147], v[8:9] op_sel:[0,1,0] op_sel_hi:[1,1,1]
	ds_read_b128 v[26:29], v24 offset:7296
	ds_read_b128 v[30:33], v24 offset:7312
	ds_read_b128 v[34:37], v24 offset:7328
	ds_read_b128 v[38:41], v24 offset:7344
	s_waitcnt vmcnt(15) lgkmcnt(8)
	v_pk_fma_f32 v[12:13], v[48:49], v[148:149], v[12:13] op_sel_hi:[1,0,1]
	v_pk_fma_f32 v[10:11], v[50:51], v[148:149], v[10:11] op_sel_hi:[1,0,1]
	v_pk_fma_f32 v[16:17], v[52:53], v[148:149], v[16:17] op_sel_hi:[1,0,1]
	v_pk_fma_f32 v[14:15], v[54:55], v[148:149], v[14:15] op_sel_hi:[1,0,1]
	v_pk_fma_f32 v[20:21], v[56:57], v[148:149], v[20:21] op_sel_hi:[1,0,1]
	v_pk_fma_f32 v[18:19], v[58:59], v[148:149], v[18:19] op_sel_hi:[1,0,1]
	v_pk_fma_f32 v[6:7], v[60:61], v[148:149], v[6:7] op_sel_hi:[1,0,1]
	v_pk_fma_f32 v[8:9], v[62:63], v[148:149], v[8:9] op_sel_hi:[1,0,1]
	ds_read_b128 v[48:51], v24 offset:7360
	ds_read_b128 v[52:55], v24 offset:7376
	ds_read_b128 v[56:59], v24 offset:7392
	ds_read_b128 v[60:63], v24 offset:7408
	s_waitcnt vmcnt(14) lgkmcnt(8)
	v_pk_fma_f32 v[12:13], v[228:229], v[148:149], v[12:13] op_sel:[0,1,0] op_sel_hi:[1,1,1]
	v_pk_fma_f32 v[10:11], v[230:231], v[148:149], v[10:11] op_sel:[0,1,0] op_sel_hi:[1,1,1]
	v_pk_fma_f32 v[16:17], v[232:233], v[148:149], v[16:17] op_sel:[0,1,0] op_sel_hi:[1,1,1]
	v_pk_fma_f32 v[14:15], v[234:235], v[148:149], v[14:15] op_sel:[0,1,0] op_sel_hi:[1,1,1]
	v_pk_fma_f32 v[20:21], v[240:241], v[148:149], v[20:21] op_sel:[0,1,0] op_sel_hi:[1,1,1]
	v_pk_fma_f32 v[18:19], v[242:243], v[148:149], v[18:19] op_sel:[0,1,0] op_sel_hi:[1,1,1]
	v_pk_fma_f32 v[6:7], v[244:245], v[148:149], v[6:7] op_sel:[0,1,0] op_sel_hi:[1,1,1]
	v_pk_fma_f32 v[8:9], v[246:247], v[148:149], v[8:9] op_sel:[0,1,0] op_sel_hi:[1,1,1]
	ds_read_b128 v[228:231], v24 offset:7424
	ds_read_b128 v[232:235], v24 offset:7440
	ds_read_b128 v[240:243], v24 offset:7456
	ds_read_b128 v[244:247], v24 offset:7472
	s_waitcnt vmcnt(13) lgkmcnt(8)
	v_pk_fma_f32 v[12:13], v[26:27], v[150:151], v[12:13] op_sel_hi:[1,0,1]
	v_pk_fma_f32 v[10:11], v[28:29], v[150:151], v[10:11] op_sel_hi:[1,0,1]
	v_pk_fma_f32 v[16:17], v[30:31], v[150:151], v[16:17] op_sel_hi:[1,0,1]
	v_pk_fma_f32 v[14:15], v[32:33], v[150:151], v[14:15] op_sel_hi:[1,0,1]
	v_pk_fma_f32 v[20:21], v[34:35], v[150:151], v[20:21] op_sel_hi:[1,0,1]
	v_pk_fma_f32 v[18:19], v[36:37], v[150:151], v[18:19] op_sel_hi:[1,0,1]
	v_pk_fma_f32 v[6:7], v[38:39], v[150:151], v[6:7] op_sel_hi:[1,0,1]
	v_pk_fma_f32 v[8:9], v[40:41], v[150:151], v[8:9] op_sel_hi:[1,0,1]
	ds_read_b128 v[26:29], v24 offset:7488
	ds_read_b128 v[30:33], v24 offset:7504
	ds_read_b128 v[34:37], v24 offset:7520
	ds_read_b128 v[38:41], v24 offset:7536
	s_waitcnt vmcnt(12) lgkmcnt(8)
	v_pk_fma_f32 v[12:13], v[48:49], v[150:151], v[12:13] op_sel:[0,1,0] op_sel_hi:[1,1,1]
	v_pk_fma_f32 v[10:11], v[50:51], v[150:151], v[10:11] op_sel:[0,1,0] op_sel_hi:[1,1,1]
	v_pk_fma_f32 v[16:17], v[52:53], v[150:151], v[16:17] op_sel:[0,1,0] op_sel_hi:[1,1,1]
	v_pk_fma_f32 v[14:15], v[54:55], v[150:151], v[14:15] op_sel:[0,1,0] op_sel_hi:[1,1,1]
	v_pk_fma_f32 v[20:21], v[56:57], v[150:151], v[20:21] op_sel:[0,1,0] op_sel_hi:[1,1,1]
	v_pk_fma_f32 v[18:19], v[58:59], v[150:151], v[18:19] op_sel:[0,1,0] op_sel_hi:[1,1,1]
	v_pk_fma_f32 v[6:7], v[60:61], v[150:151], v[6:7] op_sel:[0,1,0] op_sel_hi:[1,1,1]
	v_pk_fma_f32 v[8:9], v[62:63], v[150:151], v[8:9] op_sel:[0,1,0] op_sel_hi:[1,1,1]
	ds_read_b128 v[48:51], v24 offset:7552
	ds_read_b128 v[52:55], v24 offset:7568
	ds_read_b128 v[56:59], v24 offset:7584
	ds_read_b128 v[60:63], v24 offset:7600
	s_waitcnt vmcnt(11) lgkmcnt(8)
	v_pk_fma_f32 v[12:13], v[228:229], v[152:153], v[12:13] op_sel_hi:[1,0,1]
	v_pk_fma_f32 v[10:11], v[230:231], v[152:153], v[10:11] op_sel_hi:[1,0,1]
	v_pk_fma_f32 v[16:17], v[232:233], v[152:153], v[16:17] op_sel_hi:[1,0,1]
	v_pk_fma_f32 v[14:15], v[234:235], v[152:153], v[14:15] op_sel_hi:[1,0,1]
	v_pk_fma_f32 v[20:21], v[240:241], v[152:153], v[20:21] op_sel_hi:[1,0,1]
	v_pk_fma_f32 v[18:19], v[242:243], v[152:153], v[18:19] op_sel_hi:[1,0,1]
	v_pk_fma_f32 v[6:7], v[244:245], v[152:153], v[6:7] op_sel_hi:[1,0,1]
	v_pk_fma_f32 v[8:9], v[246:247], v[152:153], v[8:9] op_sel_hi:[1,0,1]
	ds_read_b128 v[228:231], v24 offset:7616
	ds_read_b128 v[232:235], v24 offset:7632
	ds_read_b128 v[240:243], v24 offset:7648
	ds_read_b128 v[244:247], v24 offset:7664
	s_waitcnt vmcnt(10) lgkmcnt(8)
	v_pk_fma_f32 v[12:13], v[26:27], v[152:153], v[12:13] op_sel:[0,1,0] op_sel_hi:[1,1,1]
	v_pk_fma_f32 v[10:11], v[28:29], v[152:153], v[10:11] op_sel:[0,1,0] op_sel_hi:[1,1,1]
	v_pk_fma_f32 v[16:17], v[30:31], v[152:153], v[16:17] op_sel:[0,1,0] op_sel_hi:[1,1,1]
	v_pk_fma_f32 v[14:15], v[32:33], v[152:153], v[14:15] op_sel:[0,1,0] op_sel_hi:[1,1,1]
	v_pk_fma_f32 v[20:21], v[34:35], v[152:153], v[20:21] op_sel:[0,1,0] op_sel_hi:[1,1,1]
	v_pk_fma_f32 v[18:19], v[36:37], v[152:153], v[18:19] op_sel:[0,1,0] op_sel_hi:[1,1,1]
	v_pk_fma_f32 v[6:7], v[38:39], v[152:153], v[6:7] op_sel:[0,1,0] op_sel_hi:[1,1,1]
	v_pk_fma_f32 v[8:9], v[40:41], v[152:153], v[8:9] op_sel:[0,1,0] op_sel_hi:[1,1,1]
	ds_read_b128 v[26:29], v24 offset:7680
	ds_read_b128 v[30:33], v24 offset:7696
	ds_read_b128 v[34:37], v24 offset:7712
	ds_read_b128 v[38:41], v24 offset:7728
	s_waitcnt vmcnt(9) lgkmcnt(8)
	v_pk_fma_f32 v[12:13], v[48:49], v[154:155], v[12:13] op_sel_hi:[1,0,1]
	v_pk_fma_f32 v[10:11], v[50:51], v[154:155], v[10:11] op_sel_hi:[1,0,1]
	v_pk_fma_f32 v[16:17], v[52:53], v[154:155], v[16:17] op_sel_hi:[1,0,1]
	v_pk_fma_f32 v[14:15], v[54:55], v[154:155], v[14:15] op_sel_hi:[1,0,1]
	v_pk_fma_f32 v[20:21], v[56:57], v[154:155], v[20:21] op_sel_hi:[1,0,1]
	v_pk_fma_f32 v[18:19], v[58:59], v[154:155], v[18:19] op_sel_hi:[1,0,1]
	v_pk_fma_f32 v[6:7], v[60:61], v[154:155], v[6:7] op_sel_hi:[1,0,1]
	v_pk_fma_f32 v[8:9], v[62:63], v[154:155], v[8:9] op_sel_hi:[1,0,1]
	ds_read_b128 v[48:51], v24 offset:7744
	ds_read_b128 v[52:55], v24 offset:7760
	ds_read_b128 v[56:59], v24 offset:7776
	ds_read_b128 v[60:63], v24 offset:7792
	s_waitcnt vmcnt(8) lgkmcnt(8)
	v_pk_fma_f32 v[12:13], v[228:229], v[154:155], v[12:13] op_sel:[0,1,0] op_sel_hi:[1,1,1]
	v_pk_fma_f32 v[10:11], v[230:231], v[154:155], v[10:11] op_sel:[0,1,0] op_sel_hi:[1,1,1]
	v_pk_fma_f32 v[16:17], v[232:233], v[154:155], v[16:17] op_sel:[0,1,0] op_sel_hi:[1,1,1]
	v_pk_fma_f32 v[14:15], v[234:235], v[154:155], v[14:15] op_sel:[0,1,0] op_sel_hi:[1,1,1]
	v_pk_fma_f32 v[20:21], v[240:241], v[154:155], v[20:21] op_sel:[0,1,0] op_sel_hi:[1,1,1]
	v_pk_fma_f32 v[18:19], v[242:243], v[154:155], v[18:19] op_sel:[0,1,0] op_sel_hi:[1,1,1]
	v_pk_fma_f32 v[6:7], v[244:245], v[154:155], v[6:7] op_sel:[0,1,0] op_sel_hi:[1,1,1]
	v_pk_fma_f32 v[8:9], v[246:247], v[154:155], v[8:9] op_sel:[0,1,0] op_sel_hi:[1,1,1]
	ds_read_b128 v[228:231], v24 offset:7808
	ds_read_b128 v[232:235], v24 offset:7824
	ds_read_b128 v[240:243], v24 offset:7840
	ds_read_b128 v[244:247], v24 offset:7856
	s_waitcnt vmcnt(7) lgkmcnt(8)
	v_pk_fma_f32 v[12:13], v[26:27], v[96:97], v[12:13] op_sel_hi:[1,0,1]
	v_pk_fma_f32 v[10:11], v[28:29], v[96:97], v[10:11] op_sel_hi:[1,0,1]
	v_pk_fma_f32 v[16:17], v[30:31], v[96:97], v[16:17] op_sel_hi:[1,0,1]
	v_pk_fma_f32 v[14:15], v[32:33], v[96:97], v[14:15] op_sel_hi:[1,0,1]
	v_pk_fma_f32 v[20:21], v[34:35], v[96:97], v[20:21] op_sel_hi:[1,0,1]
	v_pk_fma_f32 v[18:19], v[36:37], v[96:97], v[18:19] op_sel_hi:[1,0,1]
	v_pk_fma_f32 v[6:7], v[38:39], v[96:97], v[6:7] op_sel_hi:[1,0,1]
	v_pk_fma_f32 v[8:9], v[40:41], v[96:97], v[8:9] op_sel_hi:[1,0,1]
	ds_read_b128 v[26:29], v24 offset:7872
	ds_read_b128 v[30:33], v24 offset:7888
	ds_read_b128 v[34:37], v24 offset:7904
	ds_read_b128 v[38:41], v24 offset:7920
	s_waitcnt vmcnt(6) lgkmcnt(8)
	v_pk_fma_f32 v[12:13], v[48:49], v[96:97], v[12:13] op_sel:[0,1,0] op_sel_hi:[1,1,1]
	v_pk_fma_f32 v[10:11], v[50:51], v[96:97], v[10:11] op_sel:[0,1,0] op_sel_hi:[1,1,1]
	v_pk_fma_f32 v[16:17], v[52:53], v[96:97], v[16:17] op_sel:[0,1,0] op_sel_hi:[1,1,1]
	v_pk_fma_f32 v[14:15], v[54:55], v[96:97], v[14:15] op_sel:[0,1,0] op_sel_hi:[1,1,1]
	v_pk_fma_f32 v[20:21], v[56:57], v[96:97], v[20:21] op_sel:[0,1,0] op_sel_hi:[1,1,1]
	v_pk_fma_f32 v[18:19], v[58:59], v[96:97], v[18:19] op_sel:[0,1,0] op_sel_hi:[1,1,1]
	v_pk_fma_f32 v[6:7], v[60:61], v[96:97], v[6:7] op_sel:[0,1,0] op_sel_hi:[1,1,1]
	v_pk_fma_f32 v[8:9], v[62:63], v[96:97], v[8:9] op_sel:[0,1,0] op_sel_hi:[1,1,1]
	ds_read_b128 v[48:51], v24 offset:7936
	ds_read_b128 v[52:55], v24 offset:7952
	ds_read_b128 v[56:59], v24 offset:7968
	ds_read_b128 v[60:63], v24 offset:7984
	s_waitcnt vmcnt(5) lgkmcnt(8)
	v_pk_fma_f32 v[12:13], v[228:229], v[98:99], v[12:13] op_sel_hi:[1,0,1]
	v_pk_fma_f32 v[10:11], v[230:231], v[98:99], v[10:11] op_sel_hi:[1,0,1]
	v_pk_fma_f32 v[16:17], v[232:233], v[98:99], v[16:17] op_sel_hi:[1,0,1]
	v_pk_fma_f32 v[14:15], v[234:235], v[98:99], v[14:15] op_sel_hi:[1,0,1]
	v_pk_fma_f32 v[20:21], v[240:241], v[98:99], v[20:21] op_sel_hi:[1,0,1]
	v_pk_fma_f32 v[18:19], v[242:243], v[98:99], v[18:19] op_sel_hi:[1,0,1]
	v_pk_fma_f32 v[6:7], v[244:245], v[98:99], v[6:7] op_sel_hi:[1,0,1]
	v_pk_fma_f32 v[8:9], v[246:247], v[98:99], v[8:9] op_sel_hi:[1,0,1]
	ds_read_b128 v[228:231], v24 offset:8000
	ds_read_b128 v[232:235], v24 offset:8016
	ds_read_b128 v[240:243], v24 offset:8032
	ds_read_b128 v[244:247], v24 offset:8048
	s_waitcnt vmcnt(4) lgkmcnt(8)
	v_pk_fma_f32 v[12:13], v[26:27], v[98:99], v[12:13] op_sel:[0,1,0] op_sel_hi:[1,1,1]
	v_pk_fma_f32 v[10:11], v[28:29], v[98:99], v[10:11] op_sel:[0,1,0] op_sel_hi:[1,1,1]
	v_pk_fma_f32 v[16:17], v[30:31], v[98:99], v[16:17] op_sel:[0,1,0] op_sel_hi:[1,1,1]
	v_pk_fma_f32 v[14:15], v[32:33], v[98:99], v[14:15] op_sel:[0,1,0] op_sel_hi:[1,1,1]
	v_pk_fma_f32 v[20:21], v[34:35], v[98:99], v[20:21] op_sel:[0,1,0] op_sel_hi:[1,1,1]
	v_pk_fma_f32 v[18:19], v[36:37], v[98:99], v[18:19] op_sel:[0,1,0] op_sel_hi:[1,1,1]
	v_pk_fma_f32 v[6:7], v[38:39], v[98:99], v[6:7] op_sel:[0,1,0] op_sel_hi:[1,1,1]
	v_pk_fma_f32 v[8:9], v[40:41], v[98:99], v[8:9] op_sel:[0,1,0] op_sel_hi:[1,1,1]
	ds_read_b128 v[26:29], v24 offset:8064
	ds_read_b128 v[30:33], v24 offset:8080
	ds_read_b128 v[34:37], v24 offset:8096
	ds_read_b128 v[38:41], v24 offset:8112
	s_waitcnt vmcnt(3) lgkmcnt(8)
	v_pk_fma_f32 v[12:13], v[48:49], v[100:101], v[12:13] op_sel_hi:[1,0,1]
	v_pk_fma_f32 v[10:11], v[50:51], v[100:101], v[10:11] op_sel_hi:[1,0,1]
	v_pk_fma_f32 v[16:17], v[52:53], v[100:101], v[16:17] op_sel_hi:[1,0,1]
	v_pk_fma_f32 v[14:15], v[54:55], v[100:101], v[14:15] op_sel_hi:[1,0,1]
	v_pk_fma_f32 v[20:21], v[56:57], v[100:101], v[20:21] op_sel_hi:[1,0,1]
	v_pk_fma_f32 v[18:19], v[58:59], v[100:101], v[18:19] op_sel_hi:[1,0,1]
	v_pk_fma_f32 v[6:7], v[60:61], v[100:101], v[6:7] op_sel_hi:[1,0,1]
	v_pk_fma_f32 v[8:9], v[62:63], v[100:101], v[8:9] op_sel_hi:[1,0,1]
	ds_read_b128 v[48:51], v24 offset:8128
	ds_read_b128 v[52:55], v24 offset:8144
	ds_read_b128 v[56:59], v24 offset:8160
	ds_read_b128 v[60:63], v24 offset:8176
	s_waitcnt vmcnt(2) lgkmcnt(8)
	v_pk_fma_f32 v[12:13], v[228:229], v[100:101], v[12:13] op_sel:[0,1,0] op_sel_hi:[1,1,1]
	v_pk_fma_f32 v[10:11], v[230:231], v[100:101], v[10:11] op_sel:[0,1,0] op_sel_hi:[1,1,1]
	v_pk_fma_f32 v[16:17], v[232:233], v[100:101], v[16:17] op_sel:[0,1,0] op_sel_hi:[1,1,1]
	v_pk_fma_f32 v[14:15], v[234:235], v[100:101], v[14:15] op_sel:[0,1,0] op_sel_hi:[1,1,1]
	v_pk_fma_f32 v[20:21], v[240:241], v[100:101], v[20:21] op_sel:[0,1,0] op_sel_hi:[1,1,1]
	v_pk_fma_f32 v[18:19], v[242:243], v[100:101], v[18:19] op_sel:[0,1,0] op_sel_hi:[1,1,1]
	v_pk_fma_f32 v[6:7], v[244:245], v[100:101], v[6:7] op_sel:[0,1,0] op_sel_hi:[1,1,1]
	v_pk_fma_f32 v[8:9], v[246:247], v[100:101], v[8:9] op_sel:[0,1,0] op_sel_hi:[1,1,1]
	s_waitcnt vmcnt(1) lgkmcnt(4)
	v_pk_fma_f32 v[12:13], v[26:27], v[102:103], v[12:13] op_sel_hi:[1,0,1]
	v_pk_fma_f32 v[10:11], v[28:29], v[102:103], v[10:11] op_sel_hi:[1,0,1]
	v_pk_fma_f32 v[16:17], v[30:31], v[102:103], v[16:17] op_sel_hi:[1,0,1]
	v_pk_fma_f32 v[14:15], v[32:33], v[102:103], v[14:15] op_sel_hi:[1,0,1]
	v_pk_fma_f32 v[20:21], v[34:35], v[102:103], v[20:21] op_sel_hi:[1,0,1]
	v_pk_fma_f32 v[18:19], v[36:37], v[102:103], v[18:19] op_sel_hi:[1,0,1]
	v_pk_fma_f32 v[6:7], v[38:39], v[102:103], v[6:7] op_sel_hi:[1,0,1]
	v_pk_fma_f32 v[8:9], v[40:41], v[102:103], v[8:9] op_sel_hi:[1,0,1]
	s_waitcnt vmcnt(0) lgkmcnt(0)
	v_pk_fma_f32 v[12:13], v[48:49], v[102:103], v[12:13] op_sel:[0,1,0] op_sel_hi:[1,1,1]
	v_pk_fma_f32 v[10:11], v[50:51], v[102:103], v[10:11] op_sel:[0,1,0] op_sel_hi:[1,1,1]
	v_pk_fma_f32 v[16:17], v[52:53], v[102:103], v[16:17] op_sel:[0,1,0] op_sel_hi:[1,1,1]
	v_pk_fma_f32 v[14:15], v[54:55], v[102:103], v[14:15] op_sel:[0,1,0] op_sel_hi:[1,1,1]
	v_pk_fma_f32 v[20:21], v[56:57], v[102:103], v[20:21] op_sel:[0,1,0] op_sel_hi:[1,1,1]
	v_pk_fma_f32 v[18:19], v[58:59], v[102:103], v[18:19] op_sel:[0,1,0] op_sel_hi:[1,1,1]
	v_pk_fma_f32 v[6:7], v[60:61], v[102:103], v[6:7] op_sel:[0,1,0] op_sel_hi:[1,1,1]
	v_pk_fma_f32 v[8:9], v[62:63], v[102:103], v[8:9] op_sel:[0,1,0] op_sel_hi:[1,1,1]
	s_lshl_b32 s2, s70, 6
	s_and_b32 s2, s2, 0x3c0
	v_or_b32_e32 v4, s2, v2
	v_mov_b32_e32 v5, v3
	v_lshlrev_b64 v[4:5], 11, v[4:5]
	v_lshl_add_u64 v[4:5], s[18:19], 0, v[4:5]
	s_lshl_b32 s54, s72, 1
	v_lshl_add_u64 v[4:5], v[4:5], 0, s[54:55]
	s_lshl_b32 s54, s71, 1
	v_lshl_add_u64 v[26:27], v[4:5], 0, s[54:55]
	v_cvt_pk_bf16_f32 v22, v12, v13
	v_cvt_pk_bf16_f32 v23, v10, v11
	v_cvt_pk_bf16_f32 v24, v16, v17
	v_cvt_pk_bf16_f32 v25, v14, v15
	v_cvt_pk_bf16_f32 v4, v20, v21
	v_cvt_pk_bf16_f32 v5, v18, v19
	v_cvt_pk_bf16_f32 v6, v6, v7
	v_cvt_pk_bf16_f32 v7, v8, v9
	v_add_co_u32_e32 v8, vcc, 0xe00000, v26
	v_lshl_add_u64 v[28:29], v[26:27], 0, s[10:11]
	s_nop 0
	v_addc_co_u32_e32 v9, vcc, 0, v27, vcc
	global_store_dwordx4 v[8:9], v[22:25], off offset:1024
	global_store_dwordx4 v[28:29], v[4:7], off offset:16
	s_waitcnt lgkmcnt(0)
	s_add_i32 s70, s70, s14
	s_add_i32 s59, s59, s16
	s_cmpk_gt_i32 s70, 0x1ff
	s_cbranch_scc0 .LBB0_696

.LBB0_715:
	s_waitcnt vmcnt(4)
	s_andn2_b64 vcc, exec, s[6:7]
	s_mov_b64 s[6:7], s[2:3]
	s_mov_b32 s74, s54
	v_mov_b32_e32 v2, v38
	v_mov_b32_e32 v3, v39
	v_mov_b32_e32 v4, v40
	v_mov_b32_e32 v5, v41
	v_mov_b32_e32 v6, v34
	v_mov_b32_e32 v7, v35
	v_mov_b32_e32 v8, v36
	v_mov_b32_e32 v9, v37
	v_mov_b32_e32 v10, v46
	v_mov_b32_e32 v11, v47
	v_mov_b32_e32 v12, v48
	v_mov_b32_e32 v13, v49
	v_mov_b32_e32 v14, v42
	v_mov_b32_e32 v15, v43
	v_mov_b32_e32 v16, v44
	v_mov_b32_e32 v17, v45
	v_mov_b32_e32 v18, v54
	v_mov_b32_e32 v19, v55
	v_mov_b32_e32 v20, v56
	v_mov_b32_e32 v21, v57
	v_mov_b32_e32 v22, v50
	v_mov_b32_e32 v23, v51
	v_mov_b32_e32 v24, v52
	v_mov_b32_e32 v25, v53
	v_mov_b32_e32 v26, v62
	v_mov_b32_e32 v27, v63
	v_mov_b32_e32 v28, v64
	v_mov_b32_e32 v29, v65
	v_mov_b32_e32 v30, v58
	v_mov_b32_e32 v31, v59
	v_mov_b32_e32 v32, v60
	v_mov_b32_e32 v33, v61
	s_cbranch_vccz .LBB0_732

.LBB0_728:
	v_mov_b32_e32 v93, v1
	v_mul_u32_u24_e32 v34, s70, v68
	v_mul_u32_u24_e32 v36, s70, v72
	v_mul_u32_u24_e32 v42, s70, v74
	v_mul_u32_u24_e32 v44, s70, v76
	v_mul_u32_u24_e32 v50, s70, v67
	v_mul_u32_u24_e32 v52, s70, v69
	v_mul_u32_u24_e32 v60, s70, v71
	v_mul_u32_u24_e32 v62, s70, v73
	v_lshl_add_u64 v[58:59], s[58:59], 0, v[92:93]
	v_lshlrev_b32_e32 v34, 2, v34
	v_mov_b32_e32 v35, v1
	v_lshlrev_b32_e32 v36, 2, v36
	v_mov_b32_e32 v37, v1
	v_lshlrev_b32_e32 v42, 2, v42
	v_mov_b32_e32 v43, v1
	v_lshlrev_b32_e32 v44, 2, v44
	v_mov_b32_e32 v45, v1
	v_lshlrev_b32_e32 v50, 2, v50
	v_mov_b32_e32 v51, v1
	v_lshlrev_b32_e32 v52, 2, v52
	v_mov_b32_e32 v53, v1
	v_lshlrev_b32_e32 v60, 2, v60
	v_mov_b32_e32 v61, v1
	v_lshlrev_b32_e32 v62, 2, v62
	v_mov_b32_e32 v63, v1
	v_lshl_add_u64 v[34:35], v[58:59], 0, v[34:35]
	v_lshl_add_u64 v[36:37], v[58:59], 0, v[36:37]
	v_lshl_add_u64 v[42:43], v[58:59], 0, v[42:43]
	v_lshl_add_u64 v[44:45], v[58:59], 0, v[44:45]
	v_lshl_add_u64 v[50:51], v[58:59], 0, v[50:51]
	v_lshl_add_u64 v[52:53], v[58:59], 0, v[52:53]
	v_lshl_add_u64 v[60:61], v[58:59], 0, v[60:61]
	v_lshl_add_u64 v[58:59], v[58:59], 0, v[62:63]
	global_load_dwordx4 v[38:41], v[34:35], off
	s_nop 0
	global_load_dwordx4 v[34:37], v[36:37], off
	s_nop 0
	global_load_dwordx4 v[46:49], v[42:43], off
	s_nop 0
	global_load_dwordx4 v[42:45], v[44:45], off
	s_nop 0
	global_load_dwordx4 v[54:57], v[50:51], off
	s_nop 0
	global_load_dwordx4 v[50:53], v[52:53], off
	s_nop 0
	global_load_dwordx4 v[62:65], v[60:61], off
	s_nop 0
	global_load_dwordx4 v[58:61], v[58:59], off
	s_waitcnt vmcnt(8)
	s_branch .Lcvw716_go

.LBB0_729:
.Lcvw716_go:
	v_add_u32_e32 v91, v75, v77
	ds_write2_b32 v91, v2, v3 offset1:1
	ds_write2_b32 v91, v4, v5 offset0:2 offset1:3
	v_add_u32_e32 v2, 0x420, v91
	ds_write2_b32 v2, v6, v7 offset1:1
	v_add_u32_e32 v2, 0x428, v91
	ds_write2_b32 v2, v8, v9 offset1:1
	v_add_u32_e32 v2, 0x840, v91
	ds_write2_b32 v2, v10, v11 offset1:1
	v_add_u32_e32 v2, 0x848, v91
	ds_write2_b32 v2, v12, v13 offset1:1
	v_add_u32_e32 v2, 0xc60, v91
	ds_write2_b32 v2, v14, v15 offset1:1
	v_add_u32_e32 v2, 0xc68, v91
	ds_write2_b32 v2, v16, v17 offset1:1
	v_add_u32_e32 v2, 0x1080, v91
	ds_write2_b32 v2, v18, v19 offset1:1
	v_add_u32_e32 v2, 0x1088, v91
	ds_write2_b32 v2, v20, v21 offset1:1
	v_add_u32_e32 v2, 0x14a0, v91
	ds_write2_b32 v2, v22, v23 offset1:1
	v_add_u32_e32 v2, 0x14a8, v91
	ds_write2_b32 v2, v24, v25 offset1:1
	v_add_u32_e32 v2, 0x18c0, v91
	ds_write2_b32 v2, v26, v27 offset1:1
	v_add_u32_e32 v2, 0x18c8, v91
	ds_write2_b32 v2, v28, v29 offset1:1
	v_add_u32_e32 v2, 0x1ce0, v91
	ds_write2_b32 v2, v30, v31 offset1:1
	v_add_u32_e32 v2, 0x1ce8, v91
	ds_write2_b32 v2, v32, v33 offset1:1
	s_waitcnt lgkmcnt(0)
	ds_read2_b32 v[2:3], v79 offset1:33
	s_waitcnt lgkmcnt(0)
	v_cvt_pk_bf16_f32 v2, v2, v3
	ds_read2_b32 v[4:5], v79 offset0:66 offset1:99
	v_lshlrev_b32_e32 v8, 1, v78
	v_mov_b32_e32 v9, v1
	s_waitcnt lgkmcnt(0)
	v_cvt_pk_bf16_f32 v3, v4, v5
	ds_read2_b32 v[4:5], v79 offset0:132 offset1:165
	v_lshl_add_u64 v[8:9], s[6:7], 0, v[8:9]
	v_mad_u64_u32 v[10:11], s[6:7], s74, v68, 0
	s_waitcnt lgkmcnt(0)
	v_cvt_pk_bf16_f32 v4, v4, v5
	ds_read2_b32 v[6:7], v79 offset0:198 offset1:231
	s_waitcnt lgkmcnt(0)
	v_cvt_pk_bf16_f32 v5, v6, v7
	v_lshl_add_u64 v[10:11], v[10:11], 1, v[8:9]
	ds_read2_b32 v[6:7], v79 offset0:8 offset1:41
	global_store_dwordx4 v[10:11], v[2:5], off
	v_mad_u64_u32 v[10:11], s[6:7], s74, v72, 0
	s_waitcnt lgkmcnt(0)
	v_cvt_pk_bf16_f32 v2, v6, v7
	ds_read2_b32 v[4:5], v79 offset0:74 offset1:107
	s_waitcnt lgkmcnt(0)
	v_cvt_pk_bf16_f32 v3, v4, v5
	ds_read2_b32 v[4:5], v79 offset0:140 offset1:173
	s_waitcnt lgkmcnt(0)
	v_cvt_pk_bf16_f32 v4, v4, v5
	ds_read2_b32 v[6:7], v79 offset0:206 offset1:239
	s_waitcnt lgkmcnt(0)
	v_cvt_pk_bf16_f32 v5, v6, v7
	v_lshl_add_u64 v[10:11], v[10:11], 1, v[8:9]
	ds_read2_b32 v[6:7], v79 offset0:16 offset1:49
	global_store_dwordx4 v[10:11], v[2:5], off
	v_mad_u64_u32 v[10:11], s[6:7], s74, v74, 0
	s_waitcnt lgkmcnt(0)
	v_cvt_pk_bf16_f32 v2, v6, v7
	ds_read2_b32 v[4:5], v79 offset0:82 offset1:115
	s_waitcnt lgkmcnt(0)
	v_cvt_pk_bf16_f32 v3, v4, v5
	ds_read2_b32 v[4:5], v79 offset0:148 offset1:181
	s_waitcnt lgkmcnt(0)
	v_cvt_pk_bf16_f32 v4, v4, v5
	ds_read2_b32 v[6:7], v79 offset0:214 offset1:247
	s_waitcnt lgkmcnt(0)
	v_cvt_pk_bf16_f32 v5, v6, v7
	v_lshl_add_u64 v[10:11], v[10:11], 1, v[8:9]
	ds_read2_b32 v[6:7], v79 offset0:24 offset1:57
	global_store_dwordx4 v[10:11], v[2:5], off
	v_mad_u64_u32 v[10:11], s[6:7], s74, v76, 0
	s_waitcnt lgkmcnt(0)
	v_cvt_pk_bf16_f32 v2, v6, v7
	ds_read2_b32 v[4:5], v79 offset0:90 offset1:123
	s_waitcnt lgkmcnt(0)
	v_cvt_pk_bf16_f32 v3, v4, v5
	ds_read2_b32 v[4:5], v79 offset0:156 offset1:189
	v_lshl_add_u64 v[8:9], v[10:11], 1, v[8:9]
	s_waitcnt lgkmcnt(0)
	v_cvt_pk_bf16_f32 v4, v4, v5
	ds_read2_b32 v[6:7], v79 offset0:222 offset1:255
	s_waitcnt lgkmcnt(0)
	v_cvt_pk_bf16_f32 v5, v6, v7
	global_store_dwordx4 v[8:9], v[2:5], off
	s_waitcnt lgkmcnt(0)
	s_andn2_b64 vcc, exec, s[56:57]
	s_mov_b64 s[6:7], -1
	s_cbranch_vccnz .LBB0_715
	s_add_i32 s85, s85, s14
	s_add_i32 s65, s65, s84
	s_add_i32 s30, s30, s31
	s_add_i32 s38, s38, s39
	s_mov_b64 s[6:7], 0
	s_branch .LBB0_715

.LBB0_744:
	s_waitcnt vmcnt(4)
	s_andn2_b64 vcc, exec, s[58:59]
	s_mov_b32 s39, s38
	s_mov_b64 s[70:71], s[6:7]
	v_mov_b32_e32 v2, v38
	v_mov_b32_e32 v3, v39
	v_mov_b32_e32 v4, v40
	v_mov_b32_e32 v5, v41
	v_mov_b32_e32 v6, v34
	v_mov_b32_e32 v7, v35
	v_mov_b32_e32 v8, v36
	v_mov_b32_e32 v9, v37
	v_mov_b32_e32 v10, v46
	v_mov_b32_e32 v11, v47
	v_mov_b32_e32 v12, v48
	v_mov_b32_e32 v13, v49
	v_mov_b32_e32 v14, v42
	v_mov_b32_e32 v15, v43
	v_mov_b32_e32 v16, v44
	v_mov_b32_e32 v17, v45
	v_mov_b32_e32 v18, v54
	v_mov_b32_e32 v19, v55
	v_mov_b32_e32 v20, v56
	v_mov_b32_e32 v21, v57
	v_mov_b32_e32 v22, v50
	v_mov_b32_e32 v23, v51
	v_mov_b32_e32 v24, v52
	v_mov_b32_e32 v25, v53
	v_mov_b32_e32 v26, v62
	v_mov_b32_e32 v27, v63
	v_mov_b32_e32 v28, v64
	v_mov_b32_e32 v29, v65
	v_mov_b32_e32 v30, v58
	v_mov_b32_e32 v31, v59
	v_mov_b32_e32 v32, v60
	v_mov_b32_e32 v33, v61
	s_cbranch_vccz .LBB0_757

.LBB0_754:
	v_mov_b32_e32 v93, v1
	v_mul_u32_u24_e32 v34, s72, v68
	v_mul_u32_u24_e32 v36, s72, v72
	v_mul_u32_u24_e32 v42, s72, v74
	v_mul_u32_u24_e32 v44, s72, v76
	v_mul_u32_u24_e32 v50, s72, v67
	v_mul_u32_u24_e32 v52, s72, v69
	v_mul_u32_u24_e32 v60, s72, v71
	v_mul_u32_u24_e32 v62, s72, v73
	v_lshl_add_u64 v[58:59], s[76:77], 0, v[92:93]
	v_lshlrev_b32_e32 v34, 2, v34
	v_mov_b32_e32 v35, v1
	v_lshlrev_b32_e32 v36, 2, v36
	v_mov_b32_e32 v37, v1
	v_lshlrev_b32_e32 v42, 2, v42
	v_mov_b32_e32 v43, v1
	v_lshlrev_b32_e32 v44, 2, v44
	v_mov_b32_e32 v45, v1
	v_lshlrev_b32_e32 v50, 2, v50
	v_mov_b32_e32 v51, v1
	v_lshlrev_b32_e32 v52, 2, v52
	v_mov_b32_e32 v53, v1
	v_lshlrev_b32_e32 v60, 2, v60
	v_mov_b32_e32 v61, v1
	v_lshlrev_b32_e32 v62, 2, v62
	v_mov_b32_e32 v63, v1
	v_lshl_add_u64 v[34:35], v[58:59], 0, v[34:35]
	v_lshl_add_u64 v[36:37], v[58:59], 0, v[36:37]
	v_lshl_add_u64 v[42:43], v[58:59], 0, v[42:43]
	v_lshl_add_u64 v[44:45], v[58:59], 0, v[44:45]
	v_lshl_add_u64 v[50:51], v[58:59], 0, v[50:51]
	v_lshl_add_u64 v[52:53], v[58:59], 0, v[52:53]
	v_lshl_add_u64 v[60:61], v[58:59], 0, v[60:61]
	v_lshl_add_u64 v[58:59], v[58:59], 0, v[62:63]
	global_load_dwordx4 v[38:41], v[34:35], off
	s_nop 0
	global_load_dwordx4 v[34:37], v[36:37], off
	s_nop 0
	global_load_dwordx4 v[46:49], v[42:43], off
	s_nop 0
	global_load_dwordx4 v[42:45], v[44:45], off
	s_nop 0
	global_load_dwordx4 v[54:57], v[50:51], off
	s_nop 0
	global_load_dwordx4 v[50:53], v[52:53], off
	s_nop 0
	global_load_dwordx4 v[62:65], v[60:61], off
	s_nop 0
	global_load_dwordx4 v[58:61], v[58:59], off
	s_lshl_b64 s[44:45], s[88:89], 11
	s_add_u32 s39, s86, s44
	s_addc_u32 s44, s87, s45
	s_lshl_b64 s[6:7], s[6:7], 1
	s_add_u32 s6, s39, s6
	s_addc_u32 s7, s44, s7
	s_waitcnt vmcnt(8)
	s_branch .Lcvw745_go

.LBB0_755:
.Lcvw745_go:
	v_add_u32_e32 v91, v75, v77
	ds_write2_b32 v91, v2, v3 offset1:1
	ds_write2_b32 v91, v4, v5 offset0:2 offset1:3
	v_add_u32_e32 v2, 0x420, v91
	ds_write2_b32 v2, v6, v7 offset1:1
	v_add_u32_e32 v2, 0x428, v91
	ds_write2_b32 v2, v8, v9 offset1:1
	v_add_u32_e32 v2, 0x840, v91
	ds_write2_b32 v2, v10, v11 offset1:1
	v_add_u32_e32 v2, 0x848, v91
	ds_write2_b32 v2, v12, v13 offset1:1
	v_add_u32_e32 v2, 0xc60, v91
	ds_write2_b32 v2, v14, v15 offset1:1
	v_add_u32_e32 v2, 0xc68, v91
	ds_write2_b32 v2, v16, v17 offset1:1
	v_add_u32_e32 v2, 0x1080, v91
	ds_write2_b32 v2, v18, v19 offset1:1
	v_add_u32_e32 v2, 0x1088, v91
	ds_write2_b32 v2, v20, v21 offset1:1
	v_add_u32_e32 v2, 0x14a0, v91
	ds_write2_b32 v2, v22, v23 offset1:1
	v_add_u32_e32 v2, 0x14a8, v91
	ds_write2_b32 v2, v24, v25 offset1:1
	v_add_u32_e32 v2, 0x18c0, v91
	ds_write2_b32 v2, v26, v27 offset1:1
	v_add_u32_e32 v2, 0x18c8, v91
	ds_write2_b32 v2, v28, v29 offset1:1
	v_add_u32_e32 v2, 0x1ce0, v91
	ds_write2_b32 v2, v30, v31 offset1:1
	v_add_u32_e32 v2, 0x1ce8, v91
	ds_write2_b32 v2, v32, v33 offset1:1
	s_waitcnt lgkmcnt(0)
	ds_read2_b32 v[2:3], v79 offset1:33
	s_waitcnt lgkmcnt(0)
	v_cvt_pk_bf16_f32 v2, v2, v3
	ds_read2_b32 v[4:5], v79 offset0:66 offset1:99
	v_lshlrev_b32_e32 v8, 1, v78
	v_mov_b32_e32 v9, v1
	s_waitcnt lgkmcnt(0)
	v_cvt_pk_bf16_f32 v3, v4, v5
	ds_read2_b32 v[4:5], v79 offset0:132 offset1:165
	v_lshl_add_u64 v[8:9], s[70:71], 0, v[8:9]
	s_waitcnt lgkmcnt(0)
	v_cvt_pk_bf16_f32 v4, v4, v5
	ds_read2_b32 v[6:7], v79 offset0:198 offset1:231
	s_waitcnt lgkmcnt(0)
	v_cvt_pk_bf16_f32 v5, v6, v7
	v_lshl_add_u64 v[10:11], v[8:9], 0, v[80:81]
	ds_read2_b32 v[6:7], v79 offset0:8 offset1:41
	global_store_dwordx4 v[10:11], v[2:5], off
	v_lshl_add_u64 v[10:11], v[8:9], 0, v[82:83]
	s_andn2_b64 vcc, exec, s[58:59]
	s_waitcnt lgkmcnt(0)
	v_cvt_pk_bf16_f32 v2, v6, v7
	ds_read2_b32 v[4:5], v79 offset0:74 offset1:107
	s_waitcnt lgkmcnt(0)
	v_cvt_pk_bf16_f32 v3, v4, v5
	ds_read2_b32 v[4:5], v79 offset0:140 offset1:173
	s_waitcnt lgkmcnt(0)
	v_cvt_pk_bf16_f32 v4, v4, v5
	ds_read2_b32 v[6:7], v79 offset0:206 offset1:239
	s_waitcnt lgkmcnt(0)
	v_cvt_pk_bf16_f32 v5, v6, v7
	ds_read2_b32 v[6:7], v79 offset0:16 offset1:49
	global_store_dwordx4 v[10:11], v[2:5], off
	v_lshl_add_u64 v[10:11], v[8:9], 0, v[84:85]
	v_lshl_add_u64 v[8:9], v[8:9], 0, v[86:87]
	s_waitcnt lgkmcnt(0)
	v_cvt_pk_bf16_f32 v2, v6, v7
	ds_read2_b32 v[4:5], v79 offset0:82 offset1:115
	s_waitcnt lgkmcnt(0)
	v_cvt_pk_bf16_f32 v3, v4, v5
	ds_read2_b32 v[4:5], v79 offset0:148 offset1:181
	s_waitcnt lgkmcnt(0)
	v_cvt_pk_bf16_f32 v4, v4, v5
	ds_read2_b32 v[6:7], v79 offset0:214 offset1:247
	s_waitcnt lgkmcnt(0)
	v_cvt_pk_bf16_f32 v5, v6, v7
	ds_read2_b32 v[6:7], v79 offset0:24 offset1:57
	global_store_dwordx4 v[10:11], v[2:5], off
	s_mov_b64 s[58:59], -1
	s_waitcnt lgkmcnt(0)
	v_cvt_pk_bf16_f32 v2, v6, v7
	ds_read2_b32 v[4:5], v79 offset0:90 offset1:123
	s_waitcnt lgkmcnt(0)
	v_cvt_pk_bf16_f32 v3, v4, v5
	ds_read2_b32 v[4:5], v79 offset0:156 offset1:189
	s_waitcnt lgkmcnt(0)
	v_cvt_pk_bf16_f32 v4, v4, v5
	ds_read2_b32 v[6:7], v79 offset0:222 offset1:255
	s_waitcnt lgkmcnt(0)
	v_cvt_pk_bf16_f32 v5, v6, v7
	global_store_dwordx4 v[8:9], v[2:5], off
	s_waitcnt lgkmcnt(0)
	s_cbranch_vccnz .LBB0_744
	s_addk_i32 s4, 0x4000
	s_add_i32 s30, s30, 0x10000
	s_addk_i32 s31, 0x400
	s_mov_b64 s[58:59], 0
	s_branch .LBB0_744

.LBB0_786:
.Lcvw773_go:
	v_add_u32_e32 v91, v75, v77
	ds_write2_b32 v91, v2, v3 offset1:1
	ds_write2_b32 v91, v4, v5 offset0:2 offset1:3
	v_add_u32_e32 v2, 0x420, v91
	ds_write2_b32 v2, v6, v7 offset1:1
	v_add_u32_e32 v2, 0x428, v91
	ds_write2_b32 v2, v8, v9 offset1:1
	v_add_u32_e32 v2, 0x840, v91
	ds_write2_b32 v2, v10, v11 offset1:1
	v_add_u32_e32 v2, 0x848, v91
	ds_write2_b32 v2, v12, v13 offset1:1
	v_add_u32_e32 v2, 0xc60, v91
	ds_write2_b32 v2, v14, v15 offset1:1
	v_add_u32_e32 v2, 0xc68, v91
	ds_write2_b32 v2, v16, v17 offset1:1
	v_add_u32_e32 v2, 0x1080, v91
	ds_write2_b32 v2, v18, v19 offset1:1
	v_add_u32_e32 v2, 0x1088, v91
	ds_write2_b32 v2, v20, v21 offset1:1
	v_add_u32_e32 v2, 0x14a0, v91
	ds_write2_b32 v2, v22, v23 offset1:1
	v_add_u32_e32 v2, 0x14a8, v91
	ds_write2_b32 v2, v24, v25 offset1:1
	v_add_u32_e32 v2, 0x18c0, v91
	ds_write2_b32 v2, v26, v27 offset1:1
	v_add_u32_e32 v2, 0x18c8, v91
	ds_write2_b32 v2, v28, v29 offset1:1
	v_add_u32_e32 v2, 0x1ce0, v91
	ds_write2_b32 v2, v30, v31 offset1:1
	v_add_u32_e32 v2, 0x1ce8, v91
	ds_write2_b32 v2, v32, v33 offset1:1
	s_waitcnt lgkmcnt(0)
	ds_read2_b32 v[2:3], v79 offset1:33
	s_waitcnt lgkmcnt(0)
	v_cvt_pk_bf16_f32 v2, v2, v3
	ds_read2_b32 v[4:5], v79 offset0:66 offset1:99
	v_lshlrev_b32_e32 v8, 1, v78
	v_mov_b32_e32 v9, v1
	s_waitcnt lgkmcnt(0)
	v_cvt_pk_bf16_f32 v3, v4, v5
	ds_read2_b32 v[4:5], v79 offset0:132 offset1:165
	v_lshl_add_u64 v[8:9], s[6:7], 0, v[8:9]
	v_mad_u64_u32 v[10:11], s[6:7], s74, v68, 0
	s_waitcnt lgkmcnt(0)
	v_cvt_pk_bf16_f32 v4, v4, v5
	ds_read2_b32 v[6:7], v79 offset0:198 offset1:231
	s_waitcnt lgkmcnt(0)
	v_cvt_pk_bf16_f32 v5, v6, v7
	v_lshl_add_u64 v[10:11], v[10:11], 1, v[8:9]
	ds_read2_b32 v[6:7], v79 offset0:8 offset1:41
	global_store_dwordx4 v[10:11], v[2:5], off
	v_mad_u64_u32 v[10:11], s[6:7], s74, v72, 0
	s_waitcnt lgkmcnt(0)
	v_cvt_pk_bf16_f32 v2, v6, v7
	ds_read2_b32 v[4:5], v79 offset0:74 offset1:107
	s_waitcnt lgkmcnt(0)
	v_cvt_pk_bf16_f32 v3, v4, v5
	ds_read2_b32 v[4:5], v79 offset0:140 offset1:173
	s_waitcnt lgkmcnt(0)
	v_cvt_pk_bf16_f32 v4, v4, v5
	ds_read2_b32 v[6:7], v79 offset0:206 offset1:239
	s_waitcnt lgkmcnt(0)
	v_cvt_pk_bf16_f32 v5, v6, v7
	v_lshl_add_u64 v[10:11], v[10:11], 1, v[8:9]
	ds_read2_b32 v[6:7], v79 offset0:16 offset1:49
	global_store_dwordx4 v[10:11], v[2:5], off
	v_mad_u64_u32 v[10:11], s[6:7], s74, v74, 0
	s_waitcnt lgkmcnt(0)
	v_cvt_pk_bf16_f32 v2, v6, v7
	ds_read2_b32 v[4:5], v79 offset0:82 offset1:115
	s_waitcnt lgkmcnt(0)
	v_cvt_pk_bf16_f32 v3, v4, v5
	ds_read2_b32 v[4:5], v79 offset0:148 offset1:181
	s_waitcnt lgkmcnt(0)
	v_cvt_pk_bf16_f32 v4, v4, v5
	ds_read2_b32 v[6:7], v79 offset0:214 offset1:247
	s_waitcnt lgkmcnt(0)
	v_cvt_pk_bf16_f32 v5, v6, v7
	v_lshl_add_u64 v[10:11], v[10:11], 1, v[8:9]
	ds_read2_b32 v[6:7], v79 offset0:24 offset1:57
	global_store_dwordx4 v[10:11], v[2:5], off
	v_mad_u64_u32 v[10:11], s[6:7], s74, v76, 0
	s_waitcnt lgkmcnt(0)
	v_cvt_pk_bf16_f32 v2, v6, v7
	ds_read2_b32 v[4:5], v79 offset0:90 offset1:123
	s_waitcnt lgkmcnt(0)
	v_cvt_pk_bf16_f32 v3, v4, v5
	ds_read2_b32 v[4:5], v79 offset0:156 offset1:189
	v_lshl_add_u64 v[8:9], v[10:11], 1, v[8:9]
	s_waitcnt lgkmcnt(0)
	v_cvt_pk_bf16_f32 v4, v4, v5
	ds_read2_b32 v[6:7], v79 offset0:222 offset1:255
	s_waitcnt lgkmcnt(0)
	v_cvt_pk_bf16_f32 v5, v6, v7
	global_store_dwordx4 v[8:9], v[2:5], off
	s_waitcnt lgkmcnt(0)
	s_andn2_b64 vcc, exec, s[56:57]
	s_mov_b64 s[6:7], -1
	s_cbranch_vccnz .LBB0_772
	s_add_i32 s84, s84, s14
	s_add_i32 s85, s85, s65
	s_add_i32 s30, s30, s31
	s_add_i32 s38, s38, s39
	s_mov_b64 s[6:7], 0
	s_branch .LBB0_772
